# v23 with s_setprio removed from all GEMM K-loops (MFMA blocks no longer raise wave priority)
# baseline (speedup 1.0000x reference)
.LBB0_833:
	ds_read_b128 v[146:149], v154
	ds_read_b128 v[158:161], v154 offset:1024
	ds_read_b128 v[162:165], v154 offset:2048
	ds_read_b128 v[166:169], v154 offset:3072
	ds_read_b128 v[170:173], v155
	ds_read_b128 v[174:177], v155 offset:1024
	ds_read_b128 v[178:181], v155 offset:2048
	ds_read_b128 v[182:185], v155 offset:3072
	s_add_u32 s68, s66, 0xfffc0080
	s_addc_u32 s69, s67, -1
	s_cmp_eq_u32 s86, 12
	s_cselect_b32 s71, s17, s69
	s_cselect_b32 s70, s62, s68
	s_cselect_b32 s69, s15, s85
	s_cselect_b32 s68, s63, s84
	v_lshl_add_u64 v[150:151], s[66:67], 0, v[138:139]
	s_add_i32 m0, s23, 0xc000
	ds_read_b128 v[186:189], v156
	ds_read_b128 v[190:193], v156 offset:1024
	ds_read_b128 v[194:197], v156 offset:2048
	ds_read_b128 v[198:201], v156 offset:3072
	ds_read_b128 v[202:205], v156 offset:4096
	ds_read_b128 v[206:209], v156 offset:5120
	ds_read_b128 v[210:213], v156 offset:6144
	ds_read_b128 v[214:217], v156 offset:7168
	global_load_lds_dwordx4 v[150:151], off
	v_lshl_add_u64 v[150:151], s[66:67], 0, v[140:141]
	s_add_i32 m0, s23, 0xe000
	s_nop 0
	global_load_lds_dwordx4 v[150:151], off
	s_waitcnt vmcnt(8)
	s_waitcnt lgkmcnt(0)
	s_barrier
	s_waitcnt lgkmcnt(0)
	v_mfma_f32_16x16x32_bf16 v[126:129], v[146:149], v[186:189], v[126:129]
	v_mfma_f32_16x16x32_bf16 v[122:125], v[162:165], v[186:189], v[122:125]
	v_mfma_f32_16x16x32_bf16 v[110:113], v[146:149], v[194:197], v[110:113]
	v_mfma_f32_16x16x32_bf16 v[106:109], v[162:165], v[194:197], v[106:109]
	v_mfma_f32_16x16x32_bf16 v[94:97], v[146:149], v[202:205], v[94:97]
	v_mfma_f32_16x16x32_bf16 v[90:93], v[162:165], v[202:205], v[90:93]
	v_mfma_f32_16x16x32_bf16 v[78:81], v[146:149], v[210:213], v[78:81]
	v_mfma_f32_16x16x32_bf16 v[74:77], v[162:165], v[210:213], v[74:77]
	v_mfma_f32_16x16x32_bf16 v[126:129], v[158:161], v[190:193], v[126:129]
	v_mfma_f32_16x16x32_bf16 v[122:125], v[166:169], v[190:193], v[122:125]
	v_mfma_f32_16x16x32_bf16 v[110:113], v[158:161], v[198:201], v[110:113]
	v_mfma_f32_16x16x32_bf16 v[106:109], v[166:169], v[198:201], v[106:109]
	v_mfma_f32_16x16x32_bf16 v[94:97], v[158:161], v[206:209], v[94:97]
	v_mfma_f32_16x16x32_bf16 v[90:93], v[166:169], v[206:209], v[90:93]
	v_mfma_f32_16x16x32_bf16 v[78:81], v[158:161], v[214:217], v[78:81]
	v_mfma_f32_16x16x32_bf16 v[74:77], v[166:169], v[214:217], v[74:77]
	v_mfma_f32_16x16x32_bf16 v[118:121], v[170:173], v[186:189], v[118:121]
	v_mfma_f32_16x16x32_bf16 v[114:117], v[178:181], v[186:189], v[114:117]
	v_mfma_f32_16x16x32_bf16 v[102:105], v[170:173], v[194:197], v[102:105]
	v_mfma_f32_16x16x32_bf16 v[98:101], v[178:181], v[194:197], v[98:101]
	v_mfma_f32_16x16x32_bf16 v[86:89], v[170:173], v[202:205], v[86:89]
	v_mfma_f32_16x16x32_bf16 v[82:85], v[178:181], v[202:205], v[82:85]
	v_mfma_f32_16x16x32_bf16 v[70:73], v[170:173], v[210:213], v[70:73]
	v_mfma_f32_16x16x32_bf16 v[66:69], v[178:181], v[210:213], v[66:69]
	v_mfma_f32_16x16x32_bf16 v[118:121], v[174:177], v[190:193], v[118:121]
	v_mfma_f32_16x16x32_bf16 v[114:117], v[182:185], v[190:193], v[114:117]
	v_mfma_f32_16x16x32_bf16 v[102:105], v[174:177], v[198:201], v[102:105]
	v_mfma_f32_16x16x32_bf16 v[98:101], v[182:185], v[198:201], v[98:101]
	v_mfma_f32_16x16x32_bf16 v[86:89], v[174:177], v[206:209], v[86:89]
	v_mfma_f32_16x16x32_bf16 v[82:85], v[182:185], v[206:209], v[82:85]
	v_mfma_f32_16x16x32_bf16 v[70:73], v[174:177], v[214:217], v[70:73]
	v_mfma_f32_16x16x32_bf16 v[66:69], v[182:185], v[214:217], v[66:69]
	s_barrier
	s_add_i32 s87, s58, s33
	v_lshl_add_u64 v[150:151], s[68:69], 0, v[132:133]
	s_mov_b32 m0, s87
	ds_read_b128 v[186:189], v156 offset:16384
	ds_read_b128 v[190:193], v156 offset:17408
	ds_read_b128 v[194:197], v156 offset:18432
	ds_read_b128 v[198:201], v156 offset:19456
	ds_read_b128 v[202:205], v156 offset:20480
	ds_read_b128 v[206:209], v156 offset:21504
	ds_read_b128 v[210:213], v156 offset:22528
	ds_read_b128 v[214:217], v156 offset:23552
	global_load_lds_dwordx4 v[150:151], off
	s_add_i32 m0, s87, 0x2000
	s_add_u32 s90, s68, 0x40000
	v_lshl_add_u64 v[218:219], s[68:69], 0, v[136:137]
	s_addc_u32 s91, s69, 0
	s_add_i32 s87, s59, s33
	global_load_lds_dwordx4 v[218:219], off
	v_lshl_add_u64 v[220:221], s[90:91], 0, v[132:133]
	s_mov_b32 m0, s87
	v_lshl_add_u64 v[222:223], s[70:71], 0, v[134:135]
	global_load_lds_dwordx4 v[220:221], off
	v_lshl_add_u64 v[220:221], s[90:91], 0, v[136:137]
	s_add_i32 m0, s87, 0x2000
	s_nop 0
	global_load_lds_dwordx4 v[220:221], off
	v_lshl_add_u64 v[220:221], s[70:71], 0, v[130:131]
	s_mov_b32 m0, s23
	s_nop 0
	global_load_lds_dwordx4 v[220:221], off
	s_mov_b32 m0, s35
	s_nop 0
	global_load_lds_dwordx4 v[222:223], off
	s_waitcnt vmcnt(8)
	s_waitcnt lgkmcnt(0)
	s_barrier
	s_waitcnt lgkmcnt(0)
	v_mfma_f32_16x16x32_bf16 v[62:65], v[146:149], v[186:189], v[62:65]
	v_mfma_f32_16x16x32_bf16 v[58:61], v[162:165], v[186:189], v[58:61]
	v_mfma_f32_16x16x32_bf16 v[46:49], v[146:149], v[194:197], v[46:49]
	v_mfma_f32_16x16x32_bf16 v[42:45], v[162:165], v[194:197], v[42:45]
	v_mfma_f32_16x16x32_bf16 v[30:33], v[146:149], v[202:205], v[30:33]
	v_mfma_f32_16x16x32_bf16 v[26:29], v[162:165], v[202:205], v[26:29]
	v_mfma_f32_16x16x32_bf16 v[14:17], v[146:149], v[210:213], v[14:17]
	v_mfma_f32_16x16x32_bf16 v[10:13], v[162:165], v[210:213], v[10:13]
	v_mfma_f32_16x16x32_bf16 v[62:65], v[158:161], v[190:193], v[62:65]
	v_mfma_f32_16x16x32_bf16 v[58:61], v[166:169], v[190:193], v[58:61]
	v_mfma_f32_16x16x32_bf16 v[46:49], v[158:161], v[198:201], v[46:49]
	v_mfma_f32_16x16x32_bf16 v[42:45], v[166:169], v[198:201], v[42:45]
	v_mfma_f32_16x16x32_bf16 v[30:33], v[158:161], v[206:209], v[30:33]
	v_mfma_f32_16x16x32_bf16 v[26:29], v[166:169], v[206:209], v[26:29]
	v_mfma_f32_16x16x32_bf16 v[14:17], v[158:161], v[214:217], v[14:17]
	v_mfma_f32_16x16x32_bf16 v[10:13], v[166:169], v[214:217], v[10:13]
	v_mfma_f32_16x16x32_bf16 v[54:57], v[170:173], v[186:189], v[54:57]
	v_mfma_f32_16x16x32_bf16 v[50:53], v[178:181], v[186:189], v[50:53]
	v_mfma_f32_16x16x32_bf16 v[38:41], v[170:173], v[194:197], v[38:41]
	v_mfma_f32_16x16x32_bf16 v[34:37], v[178:181], v[194:197], v[34:37]
	v_mfma_f32_16x16x32_bf16 v[22:25], v[170:173], v[202:205], v[22:25]
	v_mfma_f32_16x16x32_bf16 v[18:21], v[178:181], v[202:205], v[18:21]
	v_mfma_f32_16x16x32_bf16 v[6:9], v[170:173], v[210:213], v[6:9]
	v_mfma_f32_16x16x32_bf16 v[2:5], v[178:181], v[210:213], v[2:5]
	v_mfma_f32_16x16x32_bf16 v[54:57], v[174:177], v[190:193], v[54:57]
	v_mfma_f32_16x16x32_bf16 v[50:53], v[182:185], v[190:193], v[50:53]
	v_mfma_f32_16x16x32_bf16 v[38:41], v[174:177], v[198:201], v[38:41]
	v_mfma_f32_16x16x32_bf16 v[34:37], v[182:185], v[198:201], v[34:37]
	v_mfma_f32_16x16x32_bf16 v[22:25], v[174:177], v[206:209], v[22:25]
	v_mfma_f32_16x16x32_bf16 v[18:21], v[182:185], v[206:209], v[18:21]
	v_mfma_f32_16x16x32_bf16 v[6:9], v[174:177], v[214:217], v[6:9]
	v_mfma_f32_16x16x32_bf16 v[2:5], v[182:185], v[214:217], v[2:5]
	s_barrier
	s_add_i32 s87, 0, 0x18000
	v_add_u32_e32 v157, s87, v152
	s_add_i32 s90, 0, 0x1c000
	ds_read_b128 v[146:149], v157
	ds_read_b128 v[158:161], v157 offset:1024
	ds_read_b128 v[162:165], v157 offset:2048
	ds_read_b128 v[166:169], v157 offset:3072
	v_add_u32_e32 v157, s90, v152
	ds_read_b128 v[170:173], v157
	ds_read_b128 v[174:177], v157 offset:1024
	ds_read_b128 v[178:181], v157 offset:2048
	ds_read_b128 v[182:185], v157 offset:3072
	s_add_u32 s70, s70, 0x40000
	s_addc_u32 s71, s71, 0
	s_mov_b32 m0, s52
	v_lshl_add_u64 v[224:225], s[70:71], 0, v[130:131]
	ds_read_b128 v[186:189], v156 offset:32768
	ds_read_b128 v[190:193], v156 offset:33792
	ds_read_b128 v[194:197], v156 offset:34816
	ds_read_b128 v[198:201], v156 offset:35840
	ds_read_b128 v[202:205], v156 offset:36864
	ds_read_b128 v[206:209], v156 offset:37888
	ds_read_b128 v[210:213], v156 offset:38912
	ds_read_b128 v[214:217], v156 offset:39936
	global_load_lds_dwordx4 v[224:225], off
	v_lshl_add_u64 v[224:225], s[70:71], 0, v[134:135]
	s_mov_b32 m0, s53
	s_nop 0
	global_load_lds_dwordx4 v[224:225], off
	s_waitcnt vmcnt(8)
	s_waitcnt lgkmcnt(0)
	s_barrier
	s_waitcnt lgkmcnt(0)
	v_mfma_f32_16x16x32_bf16 v[126:129], v[146:149], v[186:189], v[126:129]
	v_mfma_f32_16x16x32_bf16 v[122:125], v[162:165], v[186:189], v[122:125]
	v_mfma_f32_16x16x32_bf16 v[110:113], v[146:149], v[194:197], v[110:113]
	v_mfma_f32_16x16x32_bf16 v[106:109], v[162:165], v[194:197], v[106:109]
	v_mfma_f32_16x16x32_bf16 v[94:97], v[146:149], v[202:205], v[94:97]
	v_mfma_f32_16x16x32_bf16 v[90:93], v[162:165], v[202:205], v[90:93]
	v_mfma_f32_16x16x32_bf16 v[78:81], v[146:149], v[210:213], v[78:81]
	v_mfma_f32_16x16x32_bf16 v[74:77], v[162:165], v[210:213], v[74:77]
	v_mfma_f32_16x16x32_bf16 v[126:129], v[158:161], v[190:193], v[126:129]
	v_mfma_f32_16x16x32_bf16 v[122:125], v[166:169], v[190:193], v[122:125]
	v_mfma_f32_16x16x32_bf16 v[110:113], v[158:161], v[198:201], v[110:113]
	v_mfma_f32_16x16x32_bf16 v[106:109], v[166:169], v[198:201], v[106:109]
	v_mfma_f32_16x16x32_bf16 v[94:97], v[158:161], v[206:209], v[94:97]
	v_mfma_f32_16x16x32_bf16 v[90:93], v[166:169], v[206:209], v[90:93]
	v_mfma_f32_16x16x32_bf16 v[78:81], v[158:161], v[214:217], v[78:81]
	v_mfma_f32_16x16x32_bf16 v[74:77], v[166:169], v[214:217], v[74:77]
	v_mfma_f32_16x16x32_bf16 v[118:121], v[170:173], v[186:189], v[118:121]
	v_mfma_f32_16x16x32_bf16 v[114:117], v[178:181], v[186:189], v[114:117]
	v_mfma_f32_16x16x32_bf16 v[102:105], v[170:173], v[194:197], v[102:105]
	v_mfma_f32_16x16x32_bf16 v[98:101], v[178:181], v[194:197], v[98:101]
	v_mfma_f32_16x16x32_bf16 v[86:89], v[170:173], v[202:205], v[86:89]
	v_mfma_f32_16x16x32_bf16 v[82:85], v[178:181], v[202:205], v[82:85]
	v_mfma_f32_16x16x32_bf16 v[70:73], v[170:173], v[210:213], v[70:73]
	v_mfma_f32_16x16x32_bf16 v[66:69], v[178:181], v[210:213], v[66:69]
	v_mfma_f32_16x16x32_bf16 v[118:121], v[174:177], v[190:193], v[118:121]
	v_mfma_f32_16x16x32_bf16 v[114:117], v[182:185], v[190:193], v[114:117]
	v_mfma_f32_16x16x32_bf16 v[102:105], v[174:177], v[198:201], v[102:105]
	v_mfma_f32_16x16x32_bf16 v[98:101], v[182:185], v[198:201], v[98:101]
	v_mfma_f32_16x16x32_bf16 v[86:89], v[174:177], v[206:209], v[86:89]
	v_mfma_f32_16x16x32_bf16 v[82:85], v[182:185], v[206:209], v[82:85]
	v_mfma_f32_16x16x32_bf16 v[70:73], v[174:177], v[214:217], v[70:73]
	v_mfma_f32_16x16x32_bf16 v[66:69], v[182:185], v[214:217], v[66:69]
	s_barrier
	s_add_i32 s70, s87, s33
	v_lshl_add_u64 v[150:151], v[150:151], 0, s[10:11]
	s_mov_b32 m0, s70
	ds_read_b128 v[186:189], v156 offset:49152
	ds_read_b128 v[190:193], v156 offset:50176
	ds_read_b128 v[194:197], v156 offset:51200
	ds_read_b128 v[198:201], v156 offset:52224
	ds_read_b128 v[202:205], v156 offset:53248
	ds_read_b128 v[206:209], v156 offset:54272
	ds_read_b128 v[210:213], v156 offset:55296
	ds_read_b128 v[214:217], v156 offset:56320
	global_load_lds_dwordx4 v[150:151], off
	s_add_i32 m0, s70, 0x2000
	s_add_u32 s68, s68, 0x40080
	v_lshl_add_u64 v[150:151], v[218:219], 0, s[10:11]
	s_addc_u32 s69, s69, 0
	s_add_i32 s70, s90, s33
	global_load_lds_dwordx4 v[150:151], off
	v_lshl_add_u64 v[150:151], s[68:69], 0, v[132:133]
	s_mov_b32 m0, s70
	s_nop 0
	global_load_lds_dwordx4 v[150:151], off
	v_lshl_add_u64 v[150:151], s[68:69], 0, v[136:137]
	s_add_i32 m0, s70, 0x2000
	s_nop 0
	global_load_lds_dwordx4 v[150:151], off
	v_lshl_add_u64 v[150:151], v[220:221], 0, s[10:11]
	s_mov_b32 m0, s55
	s_nop 0
	global_load_lds_dwordx4 v[150:151], off
	v_lshl_add_u64 v[150:151], v[222:223], 0, s[10:11]
	s_mov_b32 m0, s56
	s_nop 0
	global_load_lds_dwordx4 v[150:151], off
	s_waitcnt vmcnt(8)
	s_waitcnt lgkmcnt(0)
	s_barrier
	s_waitcnt lgkmcnt(0)
	v_mfma_f32_16x16x32_bf16 v[62:65], v[146:149], v[186:189], v[62:65]
	v_mfma_f32_16x16x32_bf16 v[58:61], v[162:165], v[186:189], v[58:61]
	v_mfma_f32_16x16x32_bf16 v[46:49], v[146:149], v[194:197], v[46:49]
	v_mfma_f32_16x16x32_bf16 v[42:45], v[162:165], v[194:197], v[42:45]
	v_mfma_f32_16x16x32_bf16 v[30:33], v[146:149], v[202:205], v[30:33]
	v_mfma_f32_16x16x32_bf16 v[26:29], v[162:165], v[202:205], v[26:29]
	v_mfma_f32_16x16x32_bf16 v[14:17], v[146:149], v[210:213], v[14:17]
	v_mfma_f32_16x16x32_bf16 v[10:13], v[162:165], v[210:213], v[10:13]
	v_mfma_f32_16x16x32_bf16 v[62:65], v[158:161], v[190:193], v[62:65]
	v_mfma_f32_16x16x32_bf16 v[58:61], v[166:169], v[190:193], v[58:61]
	v_mfma_f32_16x16x32_bf16 v[46:49], v[158:161], v[198:201], v[46:49]
	v_mfma_f32_16x16x32_bf16 v[42:45], v[166:169], v[198:201], v[42:45]
	v_mfma_f32_16x16x32_bf16 v[30:33], v[158:161], v[206:209], v[30:33]
	v_mfma_f32_16x16x32_bf16 v[26:29], v[166:169], v[206:209], v[26:29]
	v_mfma_f32_16x16x32_bf16 v[14:17], v[158:161], v[214:217], v[14:17]
	v_mfma_f32_16x16x32_bf16 v[10:13], v[166:169], v[214:217], v[10:13]
	v_mfma_f32_16x16x32_bf16 v[54:57], v[170:173], v[186:189], v[54:57]
	v_mfma_f32_16x16x32_bf16 v[50:53], v[178:181], v[186:189], v[50:53]
	v_mfma_f32_16x16x32_bf16 v[38:41], v[170:173], v[194:197], v[38:41]
	v_mfma_f32_16x16x32_bf16 v[34:37], v[178:181], v[194:197], v[34:37]
	v_mfma_f32_16x16x32_bf16 v[22:25], v[170:173], v[202:205], v[22:25]
	v_mfma_f32_16x16x32_bf16 v[18:21], v[178:181], v[202:205], v[18:21]
	v_mfma_f32_16x16x32_bf16 v[6:9], v[170:173], v[210:213], v[6:9]
	v_mfma_f32_16x16x32_bf16 v[2:5], v[178:181], v[210:213], v[2:5]
	v_mfma_f32_16x16x32_bf16 v[54:57], v[174:177], v[190:193], v[54:57]
	v_mfma_f32_16x16x32_bf16 v[50:53], v[182:185], v[190:193], v[50:53]
	v_mfma_f32_16x16x32_bf16 v[38:41], v[174:177], v[198:201], v[38:41]
	v_mfma_f32_16x16x32_bf16 v[34:37], v[182:185], v[198:201], v[34:37]
	v_mfma_f32_16x16x32_bf16 v[22:25], v[174:177], v[206:209], v[22:25]
	v_mfma_f32_16x16x32_bf16 v[18:21], v[182:185], v[206:209], v[18:21]
	v_mfma_f32_16x16x32_bf16 v[6:9], v[174:177], v[214:217], v[6:9]
	v_mfma_f32_16x16x32_bf16 v[2:5], v[182:185], v[214:217], v[2:5]
	s_add_i32 s86, s86, 2
	s_add_u32 s66, s66, 0x100
	s_addc_u32 s67, s67, 0
	s_add_u32 s84, s84, 0x100
	s_addc_u32 s85, s85, 0
	s_cmp_gt_u32 s86, 13
	s_barrier
	s_cbranch_scc0 .LBB0_833
	s_and_b64 vcc, exec, s[12:13]
	s_cbranch_vccz .LBB0_836
	s_barrier

.LBB0_918:
	ds_read_b128 v[130:133], v174
	ds_read_b128 v[134:137], v174 offset:1024
	ds_read_b128 v[160:163], v174 offset:2048
	ds_read_b128 v[164:167], v174 offset:3072
	ds_read_b128 v[178:181], v175
	ds_read_b128 v[182:185], v175 offset:1024
	ds_read_b128 v[186:189], v175 offset:2048
	ds_read_b128 v[190:193], v175 offset:3072
	s_add_u32 s66, s8, 0xfff50080
	s_addc_u32 s67, s9, -1
	s_cmp_eq_u32 s96, 40
	s_cselect_b32 s91, s23, s67
	s_cselect_b32 s90, s22, s66
	s_cselect_b32 s71, s69, s95
	s_cselect_b32 s70, s68, s53
	v_lshl_add_u64 v[138:139], s[8:9], 0, v[152:153]
	s_add_i32 m0, s33, 0xc000
	ds_read_b128 v[194:197], v176
	ds_read_b128 v[198:201], v176 offset:1024
	ds_read_b128 v[202:205], v176 offset:2048
	ds_read_b128 v[206:209], v176 offset:3072
	ds_read_b128 v[210:213], v176 offset:4096
	ds_read_b128 v[214:217], v176 offset:5120
	ds_read_b128 v[218:221], v176 offset:6144
	ds_read_b128 v[222:225], v176 offset:7168
	global_load_lds_dwordx4 v[138:139], off
	v_lshl_add_u64 v[138:139], s[8:9], 0, v[154:155]
	s_add_i32 m0, s33, 0xe000
	s_nop 0
	global_load_lds_dwordx4 v[138:139], off
	s_waitcnt vmcnt(8)
	s_waitcnt lgkmcnt(0)
	s_barrier
	s_waitcnt lgkmcnt(0)
	v_mfma_f32_16x16x32_bf16 v[126:129], v[130:133], v[194:197], v[126:129]
	v_mfma_f32_16x16x32_bf16 v[122:125], v[160:163], v[194:197], v[122:125]
	v_mfma_f32_16x16x32_bf16 v[110:113], v[130:133], v[202:205], v[110:113]
	v_mfma_f32_16x16x32_bf16 v[106:109], v[160:163], v[202:205], v[106:109]
	v_mfma_f32_16x16x32_bf16 v[94:97], v[130:133], v[210:213], v[94:97]
	v_mfma_f32_16x16x32_bf16 v[90:93], v[160:163], v[210:213], v[90:93]
	v_mfma_f32_16x16x32_bf16 v[78:81], v[130:133], v[218:221], v[78:81]
	v_mfma_f32_16x16x32_bf16 v[74:77], v[160:163], v[218:221], v[74:77]
	v_mfma_f32_16x16x32_bf16 v[126:129], v[134:137], v[198:201], v[126:129]
	v_mfma_f32_16x16x32_bf16 v[122:125], v[164:167], v[198:201], v[122:125]
	v_mfma_f32_16x16x32_bf16 v[110:113], v[134:137], v[206:209], v[110:113]
	v_mfma_f32_16x16x32_bf16 v[106:109], v[164:167], v[206:209], v[106:109]
	v_mfma_f32_16x16x32_bf16 v[94:97], v[134:137], v[214:217], v[94:97]
	v_mfma_f32_16x16x32_bf16 v[90:93], v[164:167], v[214:217], v[90:93]
	v_mfma_f32_16x16x32_bf16 v[78:81], v[134:137], v[222:225], v[78:81]
	v_mfma_f32_16x16x32_bf16 v[74:77], v[164:167], v[222:225], v[74:77]
	v_mfma_f32_16x16x32_bf16 v[118:121], v[178:181], v[194:197], v[118:121]
	v_mfma_f32_16x16x32_bf16 v[114:117], v[186:189], v[194:197], v[114:117]
	v_mfma_f32_16x16x32_bf16 v[102:105], v[178:181], v[202:205], v[102:105]
	v_mfma_f32_16x16x32_bf16 v[98:101], v[186:189], v[202:205], v[98:101]
	v_mfma_f32_16x16x32_bf16 v[86:89], v[178:181], v[210:213], v[86:89]
	v_mfma_f32_16x16x32_bf16 v[82:85], v[186:189], v[210:213], v[82:85]
	v_mfma_f32_16x16x32_bf16 v[70:73], v[178:181], v[218:221], v[70:73]
	v_mfma_f32_16x16x32_bf16 v[66:69], v[186:189], v[218:221], v[66:69]
	v_mfma_f32_16x16x32_bf16 v[118:121], v[182:185], v[198:201], v[118:121]
	v_mfma_f32_16x16x32_bf16 v[114:117], v[190:193], v[198:201], v[114:117]
	v_mfma_f32_16x16x32_bf16 v[102:105], v[182:185], v[206:209], v[102:105]
	v_mfma_f32_16x16x32_bf16 v[98:101], v[190:193], v[206:209], v[98:101]
	v_mfma_f32_16x16x32_bf16 v[86:89], v[182:185], v[214:217], v[86:89]
	v_mfma_f32_16x16x32_bf16 v[82:85], v[190:193], v[214:217], v[82:85]
	v_mfma_f32_16x16x32_bf16 v[70:73], v[182:185], v[222:225], v[70:73]
	v_mfma_f32_16x16x32_bf16 v[66:69], v[190:193], v[222:225], v[66:69]
	s_barrier
	s_add_i32 s66, s84, s3
	v_lshl_add_u64 v[138:139], s[70:71], 0, v[142:143]
	s_mov_b32 m0, s66
	ds_read_b128 v[194:197], v176 offset:16384
	ds_read_b128 v[198:201], v176 offset:17408
	ds_read_b128 v[202:205], v176 offset:18432
	ds_read_b128 v[206:209], v176 offset:19456
	ds_read_b128 v[210:213], v176 offset:20480
	ds_read_b128 v[214:217], v176 offset:21504
	ds_read_b128 v[218:221], v176 offset:22528
	ds_read_b128 v[222:225], v176 offset:23552
	global_load_lds_dwordx4 v[138:139], off
	s_add_i32 m0, s66, 0x2000
	s_add_u32 vcc_lo, s70, 0xb0000
	v_lshl_add_u64 v[226:227], s[70:71], 0, v[146:147]
	s_addc_u32 vcc_hi, s71, 0
	s_add_i32 s66, s85, s3
	global_load_lds_dwordx4 v[226:227], off
	v_lshl_add_u64 v[228:229], vcc, 0, v[142:143]
	s_mov_b32 m0, s66
	v_lshl_add_u64 v[230:231], s[90:91], 0, v[144:145]
	global_load_lds_dwordx4 v[228:229], off
	v_lshl_add_u64 v[228:229], vcc, 0, v[146:147]
	s_add_i32 m0, s66, 0x2000
	s_nop 0
	global_load_lds_dwordx4 v[228:229], off
	v_lshl_add_u64 v[228:229], s[90:91], 0, v[140:141]
	s_mov_b32 m0, s33
	s_nop 0
	global_load_lds_dwordx4 v[228:229], off
	s_mov_b32 m0, s35
	s_nop 0
	global_load_lds_dwordx4 v[230:231], off
	s_waitcnt vmcnt(8)
	s_waitcnt lgkmcnt(0)
	s_barrier
	s_waitcnt lgkmcnt(0)
	v_mfma_f32_16x16x32_bf16 v[62:65], v[130:133], v[194:197], v[62:65]
	v_mfma_f32_16x16x32_bf16 v[58:61], v[160:163], v[194:197], v[58:61]
	v_mfma_f32_16x16x32_bf16 v[46:49], v[130:133], v[202:205], v[46:49]
	v_mfma_f32_16x16x32_bf16 v[42:45], v[160:163], v[202:205], v[42:45]
	v_mfma_f32_16x16x32_bf16 v[30:33], v[130:133], v[210:213], v[30:33]
	v_mfma_f32_16x16x32_bf16 v[26:29], v[160:163], v[210:213], v[26:29]
	v_mfma_f32_16x16x32_bf16 v[14:17], v[130:133], v[218:221], v[14:17]
	v_mfma_f32_16x16x32_bf16 v[10:13], v[160:163], v[218:221], v[10:13]
	v_mfma_f32_16x16x32_bf16 v[62:65], v[134:137], v[198:201], v[62:65]
	v_mfma_f32_16x16x32_bf16 v[58:61], v[164:167], v[198:201], v[58:61]
	v_mfma_f32_16x16x32_bf16 v[46:49], v[134:137], v[206:209], v[46:49]
	v_mfma_f32_16x16x32_bf16 v[42:45], v[164:167], v[206:209], v[42:45]
	v_mfma_f32_16x16x32_bf16 v[30:33], v[134:137], v[214:217], v[30:33]
	v_mfma_f32_16x16x32_bf16 v[26:29], v[164:167], v[214:217], v[26:29]
	v_mfma_f32_16x16x32_bf16 v[14:17], v[134:137], v[222:225], v[14:17]
	v_mfma_f32_16x16x32_bf16 v[10:13], v[164:167], v[222:225], v[10:13]
	v_mfma_f32_16x16x32_bf16 v[54:57], v[178:181], v[194:197], v[54:57]
	v_mfma_f32_16x16x32_bf16 v[50:53], v[186:189], v[194:197], v[50:53]
	v_mfma_f32_16x16x32_bf16 v[38:41], v[178:181], v[202:205], v[38:41]
	v_mfma_f32_16x16x32_bf16 v[34:37], v[186:189], v[202:205], v[34:37]
	v_mfma_f32_16x16x32_bf16 v[22:25], v[178:181], v[210:213], v[22:25]
	v_mfma_f32_16x16x32_bf16 v[18:21], v[186:189], v[210:213], v[18:21]
	v_mfma_f32_16x16x32_bf16 v[6:9], v[178:181], v[218:221], v[6:9]
	v_mfma_f32_16x16x32_bf16 v[2:5], v[186:189], v[218:221], v[2:5]
	v_mfma_f32_16x16x32_bf16 v[54:57], v[182:185], v[198:201], v[54:57]
	v_mfma_f32_16x16x32_bf16 v[50:53], v[190:193], v[198:201], v[50:53]
	v_mfma_f32_16x16x32_bf16 v[38:41], v[182:185], v[206:209], v[38:41]
	v_mfma_f32_16x16x32_bf16 v[34:37], v[190:193], v[206:209], v[34:37]
	v_mfma_f32_16x16x32_bf16 v[22:25], v[182:185], v[214:217], v[22:25]
	v_mfma_f32_16x16x32_bf16 v[18:21], v[190:193], v[214:217], v[18:21]
	v_mfma_f32_16x16x32_bf16 v[6:9], v[182:185], v[222:225], v[6:9]
	v_mfma_f32_16x16x32_bf16 v[2:5], v[190:193], v[222:225], v[2:5]
	s_barrier
	s_add_i32 s66, 0, 0x18000
	v_add_u32_e32 v148, s66, v172
	s_add_i32 s67, 0, 0x1c000
	ds_read_b128 v[130:133], v148
	ds_read_b128 v[134:137], v148 offset:1024
	ds_read_b128 v[160:163], v148 offset:2048
	ds_read_b128 v[164:167], v148 offset:3072
	v_add_u32_e32 v148, s67, v172
	ds_read_b128 v[178:181], v148
	ds_read_b128 v[182:185], v148 offset:1024
	ds_read_b128 v[186:189], v148 offset:2048
	ds_read_b128 v[190:193], v148 offset:3072
	s_add_u32 s90, s90, 0xb0000
	s_addc_u32 s91, s91, 0
	s_mov_b32 m0, s54
	v_lshl_add_u64 v[232:233], s[90:91], 0, v[140:141]
	ds_read_b128 v[194:197], v176 offset:32768
	ds_read_b128 v[198:201], v176 offset:33792
	ds_read_b128 v[202:205], v176 offset:34816
	ds_read_b128 v[206:209], v176 offset:35840
	ds_read_b128 v[210:213], v176 offset:36864
	ds_read_b128 v[214:217], v176 offset:37888
	ds_read_b128 v[218:221], v176 offset:38912
	ds_read_b128 v[222:225], v176 offset:39936
	global_load_lds_dwordx4 v[232:233], off
	v_lshl_add_u64 v[232:233], s[90:91], 0, v[144:145]
	s_mov_b32 m0, s55
	s_nop 0
	global_load_lds_dwordx4 v[232:233], off
	s_waitcnt vmcnt(8)
	s_waitcnt lgkmcnt(0)
	s_barrier
	s_waitcnt lgkmcnt(0)
	v_mfma_f32_16x16x32_bf16 v[126:129], v[130:133], v[194:197], v[126:129]
	v_mfma_f32_16x16x32_bf16 v[122:125], v[160:163], v[194:197], v[122:125]
	v_mfma_f32_16x16x32_bf16 v[110:113], v[130:133], v[202:205], v[110:113]
	v_mfma_f32_16x16x32_bf16 v[106:109], v[160:163], v[202:205], v[106:109]
	v_mfma_f32_16x16x32_bf16 v[94:97], v[130:133], v[210:213], v[94:97]
	v_mfma_f32_16x16x32_bf16 v[90:93], v[160:163], v[210:213], v[90:93]
	v_mfma_f32_16x16x32_bf16 v[78:81], v[130:133], v[218:221], v[78:81]
	v_mfma_f32_16x16x32_bf16 v[74:77], v[160:163], v[218:221], v[74:77]
	v_mfma_f32_16x16x32_bf16 v[126:129], v[134:137], v[198:201], v[126:129]
	v_mfma_f32_16x16x32_bf16 v[122:125], v[164:167], v[198:201], v[122:125]
	v_mfma_f32_16x16x32_bf16 v[110:113], v[134:137], v[206:209], v[110:113]
	v_mfma_f32_16x16x32_bf16 v[106:109], v[164:167], v[206:209], v[106:109]
	v_mfma_f32_16x16x32_bf16 v[94:97], v[134:137], v[214:217], v[94:97]
	v_mfma_f32_16x16x32_bf16 v[90:93], v[164:167], v[214:217], v[90:93]
	v_mfma_f32_16x16x32_bf16 v[78:81], v[134:137], v[222:225], v[78:81]
	v_mfma_f32_16x16x32_bf16 v[74:77], v[164:167], v[222:225], v[74:77]
	v_mfma_f32_16x16x32_bf16 v[118:121], v[178:181], v[194:197], v[118:121]
	v_mfma_f32_16x16x32_bf16 v[114:117], v[186:189], v[194:197], v[114:117]
	v_mfma_f32_16x16x32_bf16 v[102:105], v[178:181], v[202:205], v[102:105]
	v_mfma_f32_16x16x32_bf16 v[98:101], v[186:189], v[202:205], v[98:101]
	v_mfma_f32_16x16x32_bf16 v[86:89], v[178:181], v[210:213], v[86:89]
	v_mfma_f32_16x16x32_bf16 v[82:85], v[186:189], v[210:213], v[82:85]
	v_mfma_f32_16x16x32_bf16 v[70:73], v[178:181], v[218:221], v[70:73]
	v_mfma_f32_16x16x32_bf16 v[66:69], v[186:189], v[218:221], v[66:69]
	v_mfma_f32_16x16x32_bf16 v[118:121], v[182:185], v[198:201], v[118:121]
	v_mfma_f32_16x16x32_bf16 v[114:117], v[190:193], v[198:201], v[114:117]
	v_mfma_f32_16x16x32_bf16 v[102:105], v[182:185], v[206:209], v[102:105]
	v_mfma_f32_16x16x32_bf16 v[98:101], v[190:193], v[206:209], v[98:101]
	v_mfma_f32_16x16x32_bf16 v[86:89], v[182:185], v[214:217], v[86:89]
	v_mfma_f32_16x16x32_bf16 v[82:85], v[190:193], v[214:217], v[82:85]
	v_mfma_f32_16x16x32_bf16 v[70:73], v[182:185], v[222:225], v[70:73]
	v_mfma_f32_16x16x32_bf16 v[66:69], v[190:193], v[222:225], v[66:69]
	s_barrier
	s_add_i32 s66, s66, s3
	v_lshl_add_u64 v[138:139], v[138:139], 0, s[18:19]
	s_mov_b32 m0, s66
	ds_read_b128 v[194:197], v176 offset:49152
	ds_read_b128 v[198:201], v176 offset:50176
	ds_read_b128 v[202:205], v176 offset:51200
	ds_read_b128 v[206:209], v176 offset:52224
	ds_read_b128 v[210:213], v176 offset:53248
	ds_read_b128 v[214:217], v176 offset:54272
	ds_read_b128 v[218:221], v176 offset:55296
	ds_read_b128 v[222:225], v176 offset:56320
	global_load_lds_dwordx4 v[138:139], off
	s_add_i32 m0, s66, 0x2000
	s_add_u32 s70, s70, 0xb0080
	v_lshl_add_u64 v[138:139], v[226:227], 0, s[18:19]
	s_addc_u32 s71, s71, 0
	s_add_i32 s66, s67, s3
	global_load_lds_dwordx4 v[138:139], off
	v_lshl_add_u64 v[138:139], s[70:71], 0, v[142:143]
	s_mov_b32 m0, s66
	s_nop 0
	global_load_lds_dwordx4 v[138:139], off
	v_lshl_add_u64 v[138:139], s[70:71], 0, v[146:147]
	s_add_i32 m0, s66, 0x2000
	s_nop 0
	global_load_lds_dwordx4 v[138:139], off
	v_lshl_add_u64 v[138:139], v[228:229], 0, s[18:19]
	s_mov_b32 m0, s58
	s_nop 0
	global_load_lds_dwordx4 v[138:139], off
	v_lshl_add_u64 v[138:139], v[230:231], 0, s[18:19]
	s_mov_b32 m0, s59
	s_nop 0
	global_load_lds_dwordx4 v[138:139], off
	s_waitcnt vmcnt(8)
	s_waitcnt lgkmcnt(0)
	s_barrier
	s_waitcnt lgkmcnt(0)
	v_mfma_f32_16x16x32_bf16 v[62:65], v[130:133], v[194:197], v[62:65]
	v_mfma_f32_16x16x32_bf16 v[58:61], v[160:163], v[194:197], v[58:61]
	v_mfma_f32_16x16x32_bf16 v[46:49], v[130:133], v[202:205], v[46:49]
	v_mfma_f32_16x16x32_bf16 v[42:45], v[160:163], v[202:205], v[42:45]
	v_mfma_f32_16x16x32_bf16 v[30:33], v[130:133], v[210:213], v[30:33]
	v_mfma_f32_16x16x32_bf16 v[26:29], v[160:163], v[210:213], v[26:29]
	v_mfma_f32_16x16x32_bf16 v[14:17], v[130:133], v[218:221], v[14:17]
	v_mfma_f32_16x16x32_bf16 v[10:13], v[160:163], v[218:221], v[10:13]
	v_mfma_f32_16x16x32_bf16 v[62:65], v[134:137], v[198:201], v[62:65]
	v_mfma_f32_16x16x32_bf16 v[58:61], v[164:167], v[198:201], v[58:61]
	v_mfma_f32_16x16x32_bf16 v[46:49], v[134:137], v[206:209], v[46:49]
	v_mfma_f32_16x16x32_bf16 v[42:45], v[164:167], v[206:209], v[42:45]
	v_mfma_f32_16x16x32_bf16 v[30:33], v[134:137], v[214:217], v[30:33]
	v_mfma_f32_16x16x32_bf16 v[26:29], v[164:167], v[214:217], v[26:29]
	v_mfma_f32_16x16x32_bf16 v[14:17], v[134:137], v[222:225], v[14:17]
	v_mfma_f32_16x16x32_bf16 v[10:13], v[164:167], v[222:225], v[10:13]
	v_mfma_f32_16x16x32_bf16 v[54:57], v[178:181], v[194:197], v[54:57]
	v_mfma_f32_16x16x32_bf16 v[50:53], v[186:189], v[194:197], v[50:53]
	v_mfma_f32_16x16x32_bf16 v[38:41], v[178:181], v[202:205], v[38:41]
	v_mfma_f32_16x16x32_bf16 v[34:37], v[186:189], v[202:205], v[34:37]
	v_mfma_f32_16x16x32_bf16 v[22:25], v[178:181], v[210:213], v[22:25]
	v_mfma_f32_16x16x32_bf16 v[18:21], v[186:189], v[210:213], v[18:21]
	v_mfma_f32_16x16x32_bf16 v[6:9], v[178:181], v[218:221], v[6:9]
	v_mfma_f32_16x16x32_bf16 v[2:5], v[186:189], v[218:221], v[2:5]
	v_mfma_f32_16x16x32_bf16 v[54:57], v[182:185], v[198:201], v[54:57]
	v_mfma_f32_16x16x32_bf16 v[50:53], v[190:193], v[198:201], v[50:53]
	v_mfma_f32_16x16x32_bf16 v[38:41], v[182:185], v[206:209], v[38:41]
	v_mfma_f32_16x16x32_bf16 v[34:37], v[190:193], v[206:209], v[34:37]
	v_mfma_f32_16x16x32_bf16 v[22:25], v[182:185], v[214:217], v[22:25]
	v_mfma_f32_16x16x32_bf16 v[18:21], v[190:193], v[214:217], v[18:21]
	v_mfma_f32_16x16x32_bf16 v[6:9], v[182:185], v[222:225], v[6:9]
	v_mfma_f32_16x16x32_bf16 v[2:5], v[190:193], v[222:225], v[2:5]
	s_add_i32 s96, s96, 2
	s_add_u32 s8, s8, 0x100
	s_addc_u32 s9, s9, 0
	s_add_u32 s53, s53, 0x100
	s_addc_u32 s95, s95, 0
	s_cmp_gt_u32 s96, 41
	s_barrier
	s_cbranch_scc0 .LBB0_918
	s_and_b64 vcc, exec, s[20:21]
	s_cbranch_vccz .LBB0_921
	s_barrier

.LBB0_1159:
	ds_read_b128 v[130:133], v184
	ds_read_b128 v[134:137], v184 offset:1024
	ds_read_b128 v[138:141], v184 offset:2048
	ds_read_b128 v[142:145], v184 offset:3072
	ds_read_b128 v[172:175], v185
	ds_read_b128 v[176:179], v185 offset:1024
	ds_read_b128 v[190:193], v185 offset:2048
	ds_read_b128 v[194:197], v185 offset:3072
	s_add_u32 s22, s8, 0xfffc0080
	s_addc_u32 s23, s9, -1
	s_cmp_eq_u32 s84, 12
	s_cselect_b32 vcc_hi, s56, s23
	s_cselect_b32 vcc_lo, s57, s22
	s_cselect_b32 s97, s58, s69
	s_cselect_b32 s96, s59, s63
	v_lshl_add_u64 v[180:181], s[8:9], 0, v[164:165]
	s_add_i32 m0, s55, 0xc000
	ds_read_b128 v[198:201], v186
	ds_read_b128 v[202:205], v186 offset:1024
	ds_read_b128 v[206:209], v186 offset:2048
	ds_read_b128 v[210:213], v186 offset:3072
	ds_read_b128 v[214:217], v186 offset:4096
	ds_read_b128 v[218:221], v186 offset:5120
	ds_read_b128 v[222:225], v186 offset:6144
	ds_read_b128 v[226:229], v186 offset:7168
	global_load_lds_dwordx4 v[180:181], off
	v_lshl_add_u64 v[180:181], s[8:9], 0, v[166:167]
	s_add_i32 m0, s55, 0xe000
	s_nop 0
	global_load_lds_dwordx4 v[180:181], off
	s_waitcnt vmcnt(8)
	s_waitcnt lgkmcnt(0)
	s_barrier
	s_waitcnt lgkmcnt(0)
	v_mfma_f32_16x16x32_bf16 v[126:129], v[130:133], v[198:201], v[126:129]
	v_mfma_f32_16x16x32_bf16 v[122:125], v[138:141], v[198:201], v[122:125]
	v_mfma_f32_16x16x32_bf16 v[110:113], v[130:133], v[206:209], v[110:113]
	v_mfma_f32_16x16x32_bf16 v[106:109], v[138:141], v[206:209], v[106:109]
	v_mfma_f32_16x16x32_bf16 v[94:97], v[130:133], v[214:217], v[94:97]
	v_mfma_f32_16x16x32_bf16 v[90:93], v[138:141], v[214:217], v[90:93]
	v_mfma_f32_16x16x32_bf16 v[78:81], v[130:133], v[222:225], v[78:81]
	v_mfma_f32_16x16x32_bf16 v[74:77], v[138:141], v[222:225], v[74:77]
	v_mfma_f32_16x16x32_bf16 v[126:129], v[134:137], v[202:205], v[126:129]
	v_mfma_f32_16x16x32_bf16 v[122:125], v[142:145], v[202:205], v[122:125]
	v_mfma_f32_16x16x32_bf16 v[110:113], v[134:137], v[210:213], v[110:113]
	v_mfma_f32_16x16x32_bf16 v[106:109], v[142:145], v[210:213], v[106:109]
	v_mfma_f32_16x16x32_bf16 v[94:97], v[134:137], v[218:221], v[94:97]
	v_mfma_f32_16x16x32_bf16 v[90:93], v[142:145], v[218:221], v[90:93]
	v_mfma_f32_16x16x32_bf16 v[78:81], v[134:137], v[226:229], v[78:81]
	v_mfma_f32_16x16x32_bf16 v[74:77], v[142:145], v[226:229], v[74:77]
	v_mfma_f32_16x16x32_bf16 v[118:121], v[172:175], v[198:201], v[118:121]
	v_mfma_f32_16x16x32_bf16 v[114:117], v[190:193], v[198:201], v[114:117]
	v_mfma_f32_16x16x32_bf16 v[102:105], v[172:175], v[206:209], v[102:105]
	v_mfma_f32_16x16x32_bf16 v[98:101], v[190:193], v[206:209], v[98:101]
	v_mfma_f32_16x16x32_bf16 v[86:89], v[172:175], v[214:217], v[86:89]
	v_mfma_f32_16x16x32_bf16 v[82:85], v[190:193], v[214:217], v[82:85]
	v_mfma_f32_16x16x32_bf16 v[70:73], v[172:175], v[222:225], v[70:73]
	v_mfma_f32_16x16x32_bf16 v[66:69], v[190:193], v[222:225], v[66:69]
	v_mfma_f32_16x16x32_bf16 v[118:121], v[176:179], v[202:205], v[118:121]
	v_mfma_f32_16x16x32_bf16 v[114:117], v[194:197], v[202:205], v[114:117]
	v_mfma_f32_16x16x32_bf16 v[102:105], v[176:179], v[210:213], v[102:105]
	v_mfma_f32_16x16x32_bf16 v[98:101], v[194:197], v[210:213], v[98:101]
	v_mfma_f32_16x16x32_bf16 v[86:89], v[176:179], v[218:221], v[86:89]
	v_mfma_f32_16x16x32_bf16 v[82:85], v[194:197], v[218:221], v[82:85]
	v_mfma_f32_16x16x32_bf16 v[70:73], v[176:179], v[226:229], v[70:73]
	v_mfma_f32_16x16x32_bf16 v[66:69], v[194:197], v[226:229], v[66:69]
	s_barrier
	s_add_i32 s22, s12, s35
	v_lshl_add_u64 v[180:181], s[96:97], 0, v[148:149]
	s_mov_b32 m0, s22
	ds_read_b128 v[198:201], v186 offset:16384
	ds_read_b128 v[202:205], v186 offset:17408
	ds_read_b128 v[206:209], v186 offset:18432
	ds_read_b128 v[210:213], v186 offset:19456
	ds_read_b128 v[214:217], v186 offset:20480
	ds_read_b128 v[218:221], v186 offset:21504
	ds_read_b128 v[222:225], v186 offset:22528
	ds_read_b128 v[226:229], v186 offset:23552
	global_load_lds_dwordx4 v[180:181], off
	s_add_i32 m0, s22, 0x2000
	s_add_u32 s22, s96, 0x40000
	v_lshl_add_u64 v[230:231], s[96:97], 0, v[152:153]
	s_addc_u32 s23, s97, 0
	s_add_i32 s66, s13, s35
	global_load_lds_dwordx4 v[230:231], off
	v_lshl_add_u64 v[232:233], s[22:23], 0, v[148:149]
	s_mov_b32 m0, s66
	v_lshl_add_u64 v[234:235], vcc, 0, v[150:151]
	global_load_lds_dwordx4 v[232:233], off
	v_lshl_add_u64 v[232:233], s[22:23], 0, v[152:153]
	s_add_i32 m0, s66, 0x2000
	s_nop 0
	global_load_lds_dwordx4 v[232:233], off
	v_lshl_add_u64 v[232:233], vcc, 0, v[146:147]
	s_mov_b32 m0, s55
	s_nop 0
	global_load_lds_dwordx4 v[232:233], off
	s_mov_b32 m0, s60
	s_nop 0
	global_load_lds_dwordx4 v[234:235], off
	s_waitcnt vmcnt(8)
	s_waitcnt lgkmcnt(0)
	s_barrier
	s_waitcnt lgkmcnt(0)
	v_mfma_f32_16x16x32_bf16 v[62:65], v[130:133], v[198:201], v[62:65]
	v_mfma_f32_16x16x32_bf16 v[58:61], v[138:141], v[198:201], v[58:61]
	v_mfma_f32_16x16x32_bf16 v[46:49], v[130:133], v[206:209], v[46:49]
	v_mfma_f32_16x16x32_bf16 v[42:45], v[138:141], v[206:209], v[42:45]
	v_mfma_f32_16x16x32_bf16 v[30:33], v[130:133], v[214:217], v[30:33]
	v_mfma_f32_16x16x32_bf16 v[26:29], v[138:141], v[214:217], v[26:29]
	v_mfma_f32_16x16x32_bf16 v[14:17], v[130:133], v[222:225], v[14:17]
	v_mfma_f32_16x16x32_bf16 v[10:13], v[138:141], v[222:225], v[10:13]
	v_mfma_f32_16x16x32_bf16 v[62:65], v[134:137], v[202:205], v[62:65]
	v_mfma_f32_16x16x32_bf16 v[58:61], v[142:145], v[202:205], v[58:61]
	v_mfma_f32_16x16x32_bf16 v[46:49], v[134:137], v[210:213], v[46:49]
	v_mfma_f32_16x16x32_bf16 v[42:45], v[142:145], v[210:213], v[42:45]
	v_mfma_f32_16x16x32_bf16 v[30:33], v[134:137], v[218:221], v[30:33]
	v_mfma_f32_16x16x32_bf16 v[26:29], v[142:145], v[218:221], v[26:29]
	v_mfma_f32_16x16x32_bf16 v[14:17], v[134:137], v[226:229], v[14:17]
	v_mfma_f32_16x16x32_bf16 v[10:13], v[142:145], v[226:229], v[10:13]
	v_mfma_f32_16x16x32_bf16 v[54:57], v[172:175], v[198:201], v[54:57]
	v_mfma_f32_16x16x32_bf16 v[50:53], v[190:193], v[198:201], v[50:53]
	v_mfma_f32_16x16x32_bf16 v[38:41], v[172:175], v[206:209], v[38:41]
	v_mfma_f32_16x16x32_bf16 v[34:37], v[190:193], v[206:209], v[34:37]
	v_mfma_f32_16x16x32_bf16 v[22:25], v[172:175], v[214:217], v[22:25]
	v_mfma_f32_16x16x32_bf16 v[18:21], v[190:193], v[214:217], v[18:21]
	v_mfma_f32_16x16x32_bf16 v[6:9], v[172:175], v[222:225], v[6:9]
	v_mfma_f32_16x16x32_bf16 v[2:5], v[190:193], v[222:225], v[2:5]
	v_mfma_f32_16x16x32_bf16 v[54:57], v[176:179], v[202:205], v[54:57]
	v_mfma_f32_16x16x32_bf16 v[50:53], v[194:197], v[202:205], v[50:53]
	v_mfma_f32_16x16x32_bf16 v[38:41], v[176:179], v[210:213], v[38:41]
	v_mfma_f32_16x16x32_bf16 v[34:37], v[194:197], v[210:213], v[34:37]
	v_mfma_f32_16x16x32_bf16 v[22:25], v[176:179], v[218:221], v[22:25]
	v_mfma_f32_16x16x32_bf16 v[18:21], v[194:197], v[218:221], v[18:21]
	v_mfma_f32_16x16x32_bf16 v[6:9], v[176:179], v[226:229], v[6:9]
	v_mfma_f32_16x16x32_bf16 v[2:5], v[194:197], v[226:229], v[2:5]
	s_barrier
	s_add_i32 s66, 0, 0x18000
	s_add_i32 s67, 0, 0x1c000
	v_add_u32_e32 v142, s66, v159
	v_add_u32_e32 v154, s67, v159
	ds_read_b128 v[130:133], v142
	ds_read_b128 v[134:137], v142 offset:1024
	ds_read_b128 v[138:141], v142 offset:2048
	ds_read_b128 v[142:145], v142 offset:3072
	ds_read_b128 v[172:175], v154
	ds_read_b128 v[176:179], v154 offset:1024
	ds_read_b128 v[190:193], v154 offset:2048
	ds_read_b128 v[194:197], v154 offset:3072
	s_add_u32 s22, vcc_lo, 0x40000
	s_addc_u32 s23, vcc_hi, 0
	s_mov_b32 m0, s61
	v_lshl_add_u64 v[236:237], s[22:23], 0, v[146:147]
	ds_read_b128 v[198:201], v186 offset:32768
	ds_read_b128 v[202:205], v186 offset:33792
	ds_read_b128 v[206:209], v186 offset:34816
	ds_read_b128 v[210:213], v186 offset:35840
	ds_read_b128 v[214:217], v186 offset:36864
	ds_read_b128 v[218:221], v186 offset:37888
	ds_read_b128 v[222:225], v186 offset:38912
	ds_read_b128 v[226:229], v186 offset:39936
	global_load_lds_dwordx4 v[236:237], off
	v_lshl_add_u64 v[236:237], s[22:23], 0, v[150:151]
	s_mov_b32 m0, s86
	s_nop 0
	global_load_lds_dwordx4 v[236:237], off
	s_waitcnt vmcnt(8)
	s_waitcnt lgkmcnt(0)
	s_barrier
	s_waitcnt lgkmcnt(0)
	v_mfma_f32_16x16x32_bf16 v[126:129], v[130:133], v[198:201], v[126:129]
	v_mfma_f32_16x16x32_bf16 v[122:125], v[138:141], v[198:201], v[122:125]
	v_mfma_f32_16x16x32_bf16 v[110:113], v[130:133], v[206:209], v[110:113]
	v_mfma_f32_16x16x32_bf16 v[106:109], v[138:141], v[206:209], v[106:109]
	v_mfma_f32_16x16x32_bf16 v[94:97], v[130:133], v[214:217], v[94:97]
	v_mfma_f32_16x16x32_bf16 v[90:93], v[138:141], v[214:217], v[90:93]
	v_mfma_f32_16x16x32_bf16 v[78:81], v[130:133], v[222:225], v[78:81]
	v_mfma_f32_16x16x32_bf16 v[74:77], v[138:141], v[222:225], v[74:77]
	v_mfma_f32_16x16x32_bf16 v[126:129], v[134:137], v[202:205], v[126:129]
	v_mfma_f32_16x16x32_bf16 v[122:125], v[142:145], v[202:205], v[122:125]
	v_mfma_f32_16x16x32_bf16 v[110:113], v[134:137], v[210:213], v[110:113]
	v_mfma_f32_16x16x32_bf16 v[106:109], v[142:145], v[210:213], v[106:109]
	v_mfma_f32_16x16x32_bf16 v[94:97], v[134:137], v[218:221], v[94:97]
	v_mfma_f32_16x16x32_bf16 v[90:93], v[142:145], v[218:221], v[90:93]
	v_mfma_f32_16x16x32_bf16 v[78:81], v[134:137], v[226:229], v[78:81]
	v_mfma_f32_16x16x32_bf16 v[74:77], v[142:145], v[226:229], v[74:77]
	v_mfma_f32_16x16x32_bf16 v[118:121], v[172:175], v[198:201], v[118:121]
	v_mfma_f32_16x16x32_bf16 v[114:117], v[190:193], v[198:201], v[114:117]
	v_mfma_f32_16x16x32_bf16 v[102:105], v[172:175], v[206:209], v[102:105]
	v_mfma_f32_16x16x32_bf16 v[98:101], v[190:193], v[206:209], v[98:101]
	v_mfma_f32_16x16x32_bf16 v[86:89], v[172:175], v[214:217], v[86:89]
	v_mfma_f32_16x16x32_bf16 v[82:85], v[190:193], v[214:217], v[82:85]
	v_mfma_f32_16x16x32_bf16 v[70:73], v[172:175], v[222:225], v[70:73]
	v_mfma_f32_16x16x32_bf16 v[66:69], v[190:193], v[222:225], v[66:69]
	v_mfma_f32_16x16x32_bf16 v[118:121], v[176:179], v[202:205], v[118:121]
	v_mfma_f32_16x16x32_bf16 v[114:117], v[194:197], v[202:205], v[114:117]
	v_mfma_f32_16x16x32_bf16 v[102:105], v[176:179], v[210:213], v[102:105]
	v_mfma_f32_16x16x32_bf16 v[98:101], v[194:197], v[210:213], v[98:101]
	v_mfma_f32_16x16x32_bf16 v[86:89], v[176:179], v[218:221], v[86:89]
	v_mfma_f32_16x16x32_bf16 v[82:85], v[194:197], v[218:221], v[82:85]
	v_mfma_f32_16x16x32_bf16 v[70:73], v[176:179], v[226:229], v[70:73]
	v_mfma_f32_16x16x32_bf16 v[66:69], v[194:197], v[226:229], v[66:69]
	s_barrier
	s_add_i32 s22, s66, s35
	v_lshl_add_u64 v[180:181], v[180:181], 0, s[14:15]
	s_mov_b32 m0, s22
	ds_read_b128 v[198:201], v186 offset:49152
	ds_read_b128 v[202:205], v186 offset:50176
	ds_read_b128 v[206:209], v186 offset:51200
	ds_read_b128 v[210:213], v186 offset:52224
	ds_read_b128 v[214:217], v186 offset:53248
	ds_read_b128 v[218:221], v186 offset:54272
	ds_read_b128 v[222:225], v186 offset:55296
	ds_read_b128 v[226:229], v186 offset:56320
	global_load_lds_dwordx4 v[180:181], off
	s_add_i32 m0, s22, 0x2000
	s_add_u32 s22, s96, 0x40080
	v_lshl_add_u64 v[180:181], v[230:231], 0, s[14:15]
	s_addc_u32 s23, s97, 0
	s_add_i32 s66, s67, s35
	global_load_lds_dwordx4 v[180:181], off
	v_lshl_add_u64 v[180:181], s[22:23], 0, v[148:149]
	s_mov_b32 m0, s66
	s_nop 0
	global_load_lds_dwordx4 v[180:181], off
	v_lshl_add_u64 v[180:181], s[22:23], 0, v[152:153]
	s_add_i32 m0, s66, 0x2000
	s_nop 0
	global_load_lds_dwordx4 v[180:181], off
	v_lshl_add_u64 v[180:181], v[232:233], 0, s[14:15]
	s_mov_b32 m0, s53
	s_nop 0
	global_load_lds_dwordx4 v[180:181], off
	v_lshl_add_u64 v[180:181], v[234:235], 0, s[14:15]
	s_mov_b32 m0, s54
	s_nop 0
	global_load_lds_dwordx4 v[180:181], off
	s_waitcnt vmcnt(8)
	s_waitcnt lgkmcnt(0)
	s_barrier
	s_waitcnt lgkmcnt(0)
	v_mfma_f32_16x16x32_bf16 v[62:65], v[130:133], v[198:201], v[62:65]
	v_mfma_f32_16x16x32_bf16 v[58:61], v[138:141], v[198:201], v[58:61]
	v_mfma_f32_16x16x32_bf16 v[46:49], v[130:133], v[206:209], v[46:49]
	v_mfma_f32_16x16x32_bf16 v[42:45], v[138:141], v[206:209], v[42:45]
	v_mfma_f32_16x16x32_bf16 v[30:33], v[130:133], v[214:217], v[30:33]
	v_mfma_f32_16x16x32_bf16 v[26:29], v[138:141], v[214:217], v[26:29]
	v_mfma_f32_16x16x32_bf16 v[14:17], v[130:133], v[222:225], v[14:17]
	v_mfma_f32_16x16x32_bf16 v[10:13], v[138:141], v[222:225], v[10:13]
	v_mfma_f32_16x16x32_bf16 v[62:65], v[134:137], v[202:205], v[62:65]
	v_mfma_f32_16x16x32_bf16 v[58:61], v[142:145], v[202:205], v[58:61]
	v_mfma_f32_16x16x32_bf16 v[46:49], v[134:137], v[210:213], v[46:49]
	v_mfma_f32_16x16x32_bf16 v[42:45], v[142:145], v[210:213], v[42:45]
	v_mfma_f32_16x16x32_bf16 v[30:33], v[134:137], v[218:221], v[30:33]
	v_mfma_f32_16x16x32_bf16 v[26:29], v[142:145], v[218:221], v[26:29]
	v_mfma_f32_16x16x32_bf16 v[14:17], v[134:137], v[226:229], v[14:17]
	v_mfma_f32_16x16x32_bf16 v[10:13], v[142:145], v[226:229], v[10:13]
	v_mfma_f32_16x16x32_bf16 v[54:57], v[172:175], v[198:201], v[54:57]
	v_mfma_f32_16x16x32_bf16 v[50:53], v[190:193], v[198:201], v[50:53]
	v_mfma_f32_16x16x32_bf16 v[38:41], v[172:175], v[206:209], v[38:41]
	v_mfma_f32_16x16x32_bf16 v[34:37], v[190:193], v[206:209], v[34:37]
	v_mfma_f32_16x16x32_bf16 v[22:25], v[172:175], v[214:217], v[22:25]
	v_mfma_f32_16x16x32_bf16 v[18:21], v[190:193], v[214:217], v[18:21]
	v_mfma_f32_16x16x32_bf16 v[6:9], v[172:175], v[222:225], v[6:9]
	v_mfma_f32_16x16x32_bf16 v[2:5], v[190:193], v[222:225], v[2:5]
	v_mfma_f32_16x16x32_bf16 v[54:57], v[176:179], v[202:205], v[54:57]
	v_mfma_f32_16x16x32_bf16 v[50:53], v[194:197], v[202:205], v[50:53]
	v_mfma_f32_16x16x32_bf16 v[38:41], v[176:179], v[210:213], v[38:41]
	v_mfma_f32_16x16x32_bf16 v[34:37], v[194:197], v[210:213], v[34:37]
	v_mfma_f32_16x16x32_bf16 v[22:25], v[176:179], v[218:221], v[22:25]
	v_mfma_f32_16x16x32_bf16 v[18:21], v[194:197], v[218:221], v[18:21]
	v_mfma_f32_16x16x32_bf16 v[6:9], v[176:179], v[226:229], v[6:9]
	v_mfma_f32_16x16x32_bf16 v[2:5], v[194:197], v[226:229], v[2:5]
	s_add_i32 s84, s84, 2
	s_add_u32 s8, s8, 0x100
	s_addc_u32 s9, s9, 0
	s_add_u32 s63, s63, 0x100
	s_addc_u32 s69, s69, 0
	s_cmp_gt_u32 s84, 13
	s_barrier
	s_cbranch_scc0 .LBB0_1159
	s_and_b64 vcc, exec, s[16:17]
	s_cbranch_vccnz .LBB0_1164
	s_cmp_gt_i32 s92, 11
	s_mov_b64 s[8:9], -1
	s_cbranch_scc1 .LBB0_1165

.LBB0_2648:
	ds_read_b128 v[150:153], v167
	ds_read_b128 v[154:157], v167 offset:1024
	ds_read_b128 v[158:161], v167 offset:2048
	ds_read_b128 v[172:175], v167 offset:3072
	ds_read_b128 v[176:179], v168
	ds_read_b128 v[180:183], v168 offset:1024
	ds_read_b128 v[184:187], v168 offset:2048
	ds_read_b128 v[188:191], v168 offset:3072
	s_add_u32 s50, s48, 0xfffc0080
	s_addc_u32 s51, s49, -1
	s_cmp_eq_u32 s81, 12
	s_cselect_b32 s53, s7, s51
	s_cselect_b32 s52, s9, s50
	s_cselect_b32 s51, s41, s80
	s_cselect_b32 s50, s43, s79
	v_lshl_add_u64 v[162:163], s[48:49], 0, v[142:143]
	s_add_i32 m0, s54, 0xc000
	ds_read_b128 v[192:195], v169
	ds_read_b128 v[196:199], v169 offset:1024
	ds_read_b128 v[200:203], v169 offset:2048
	ds_read_b128 v[204:207], v169 offset:3072
	ds_read_b128 v[208:211], v169 offset:4096
	ds_read_b128 v[212:215], v169 offset:5120
	ds_read_b128 v[216:219], v169 offset:6144
	ds_read_b128 v[220:223], v169 offset:7168
	global_load_lds_dwordx4 v[162:163], off
	v_lshl_add_u64 v[162:163], s[48:49], 0, v[144:145]
	s_add_i32 m0, s54, 0xe000
	s_nop 0
	global_load_lds_dwordx4 v[162:163], off
	s_waitcnt vmcnt(8)
	s_waitcnt lgkmcnt(0)
	s_barrier
	s_waitcnt lgkmcnt(0)
	v_mfma_f32_16x16x32_bf16 v[126:129], v[150:153], v[192:195], v[126:129]
	v_mfma_f32_16x16x32_bf16 v[122:125], v[158:161], v[192:195], v[122:125]
	v_mfma_f32_16x16x32_bf16 v[110:113], v[150:153], v[200:203], v[110:113]
	v_mfma_f32_16x16x32_bf16 v[106:109], v[158:161], v[200:203], v[106:109]
	v_mfma_f32_16x16x32_bf16 v[94:97], v[150:153], v[208:211], v[94:97]
	v_mfma_f32_16x16x32_bf16 v[90:93], v[158:161], v[208:211], v[90:93]
	v_mfma_f32_16x16x32_bf16 v[78:81], v[150:153], v[216:219], v[78:81]
	v_mfma_f32_16x16x32_bf16 v[74:77], v[158:161], v[216:219], v[74:77]
	v_mfma_f32_16x16x32_bf16 v[126:129], v[154:157], v[196:199], v[126:129]
	v_mfma_f32_16x16x32_bf16 v[122:125], v[172:175], v[196:199], v[122:125]
	v_mfma_f32_16x16x32_bf16 v[110:113], v[154:157], v[204:207], v[110:113]
	v_mfma_f32_16x16x32_bf16 v[106:109], v[172:175], v[204:207], v[106:109]
	v_mfma_f32_16x16x32_bf16 v[94:97], v[154:157], v[212:215], v[94:97]
	v_mfma_f32_16x16x32_bf16 v[90:93], v[172:175], v[212:215], v[90:93]
	v_mfma_f32_16x16x32_bf16 v[78:81], v[154:157], v[220:223], v[78:81]
	v_mfma_f32_16x16x32_bf16 v[74:77], v[172:175], v[220:223], v[74:77]
	v_mfma_f32_16x16x32_bf16 v[118:121], v[176:179], v[192:195], v[118:121]
	v_mfma_f32_16x16x32_bf16 v[114:117], v[184:187], v[192:195], v[114:117]
	v_mfma_f32_16x16x32_bf16 v[102:105], v[176:179], v[200:203], v[102:105]
	v_mfma_f32_16x16x32_bf16 v[98:101], v[184:187], v[200:203], v[98:101]
	v_mfma_f32_16x16x32_bf16 v[86:89], v[176:179], v[208:211], v[86:89]
	v_mfma_f32_16x16x32_bf16 v[82:85], v[184:187], v[208:211], v[82:85]
	v_mfma_f32_16x16x32_bf16 v[70:73], v[176:179], v[216:219], v[70:73]
	v_mfma_f32_16x16x32_bf16 v[66:69], v[184:187], v[216:219], v[66:69]
	v_mfma_f32_16x16x32_bf16 v[118:121], v[180:183], v[196:199], v[118:121]
	v_mfma_f32_16x16x32_bf16 v[114:117], v[188:191], v[196:199], v[114:117]
	v_mfma_f32_16x16x32_bf16 v[102:105], v[180:183], v[204:207], v[102:105]
	v_mfma_f32_16x16x32_bf16 v[98:101], v[188:191], v[204:207], v[98:101]
	v_mfma_f32_16x16x32_bf16 v[86:89], v[180:183], v[212:215], v[86:89]
	v_mfma_f32_16x16x32_bf16 v[82:85], v[188:191], v[212:215], v[82:85]
	v_mfma_f32_16x16x32_bf16 v[70:73], v[180:183], v[220:223], v[70:73]
	v_mfma_f32_16x16x32_bf16 v[66:69], v[188:191], v[220:223], v[66:69]
	s_barrier
	s_add_i32 s66, s72, s35
	v_lshl_add_u64 v[162:163], s[50:51], 0, v[132:133]
	s_mov_b32 m0, s66
	ds_read_b128 v[192:195], v169 offset:16384
	ds_read_b128 v[196:199], v169 offset:17408
	ds_read_b128 v[200:203], v169 offset:18432
	ds_read_b128 v[204:207], v169 offset:19456
	ds_read_b128 v[208:211], v169 offset:20480
	ds_read_b128 v[212:215], v169 offset:21504
	ds_read_b128 v[216:219], v169 offset:22528
	ds_read_b128 v[220:223], v169 offset:23552
	global_load_lds_dwordx4 v[162:163], off
	s_add_i32 m0, s66, 0x2000
	s_add_u32 s66, s50, 0x40000
	v_lshl_add_u64 v[224:225], s[50:51], 0, v[136:137]
	s_addc_u32 s67, s51, 0
	s_add_i32 s82, s73, s35
	global_load_lds_dwordx4 v[224:225], off
	v_lshl_add_u64 v[226:227], s[66:67], 0, v[132:133]
	s_mov_b32 m0, s82
	v_lshl_add_u64 v[228:229], s[52:53], 0, v[134:135]
	global_load_lds_dwordx4 v[226:227], off
	v_lshl_add_u64 v[226:227], s[66:67], 0, v[136:137]
	s_add_i32 m0, s82, 0x2000
	s_nop 0
	global_load_lds_dwordx4 v[226:227], off
	v_lshl_add_u64 v[226:227], s[52:53], 0, v[130:131]
	s_mov_b32 m0, s54
	s_nop 0
	global_load_lds_dwordx4 v[226:227], off
	s_mov_b32 m0, s55
	s_nop 0
	global_load_lds_dwordx4 v[228:229], off
	s_waitcnt vmcnt(8)
	s_waitcnt lgkmcnt(0)
	s_barrier
	s_waitcnt lgkmcnt(0)
	v_mfma_f32_16x16x32_bf16 v[62:65], v[150:153], v[192:195], v[62:65]
	v_mfma_f32_16x16x32_bf16 v[58:61], v[158:161], v[192:195], v[58:61]
	v_mfma_f32_16x16x32_bf16 v[46:49], v[150:153], v[200:203], v[46:49]
	v_mfma_f32_16x16x32_bf16 v[42:45], v[158:161], v[200:203], v[42:45]
	v_mfma_f32_16x16x32_bf16 v[30:33], v[150:153], v[208:211], v[30:33]
	v_mfma_f32_16x16x32_bf16 v[26:29], v[158:161], v[208:211], v[26:29]
	v_mfma_f32_16x16x32_bf16 v[14:17], v[150:153], v[216:219], v[14:17]
	v_mfma_f32_16x16x32_bf16 v[10:13], v[158:161], v[216:219], v[10:13]
	v_mfma_f32_16x16x32_bf16 v[62:65], v[154:157], v[196:199], v[62:65]
	v_mfma_f32_16x16x32_bf16 v[58:61], v[172:175], v[196:199], v[58:61]
	v_mfma_f32_16x16x32_bf16 v[46:49], v[154:157], v[204:207], v[46:49]
	v_mfma_f32_16x16x32_bf16 v[42:45], v[172:175], v[204:207], v[42:45]
	v_mfma_f32_16x16x32_bf16 v[30:33], v[154:157], v[212:215], v[30:33]
	v_mfma_f32_16x16x32_bf16 v[26:29], v[172:175], v[212:215], v[26:29]
	v_mfma_f32_16x16x32_bf16 v[14:17], v[154:157], v[220:223], v[14:17]
	v_mfma_f32_16x16x32_bf16 v[10:13], v[172:175], v[220:223], v[10:13]
	v_mfma_f32_16x16x32_bf16 v[54:57], v[176:179], v[192:195], v[54:57]
	v_mfma_f32_16x16x32_bf16 v[50:53], v[184:187], v[192:195], v[50:53]
	v_mfma_f32_16x16x32_bf16 v[38:41], v[176:179], v[200:203], v[38:41]
	v_mfma_f32_16x16x32_bf16 v[34:37], v[184:187], v[200:203], v[34:37]
	v_mfma_f32_16x16x32_bf16 v[22:25], v[176:179], v[208:211], v[22:25]
	v_mfma_f32_16x16x32_bf16 v[18:21], v[184:187], v[208:211], v[18:21]
	v_mfma_f32_16x16x32_bf16 v[6:9], v[176:179], v[216:219], v[6:9]
	v_mfma_f32_16x16x32_bf16 v[2:5], v[184:187], v[216:219], v[2:5]
	v_mfma_f32_16x16x32_bf16 v[54:57], v[180:183], v[196:199], v[54:57]
	v_mfma_f32_16x16x32_bf16 v[50:53], v[188:191], v[196:199], v[50:53]
	v_mfma_f32_16x16x32_bf16 v[38:41], v[180:183], v[204:207], v[38:41]
	v_mfma_f32_16x16x32_bf16 v[34:37], v[188:191], v[204:207], v[34:37]
	v_mfma_f32_16x16x32_bf16 v[22:25], v[180:183], v[212:215], v[22:25]
	v_mfma_f32_16x16x32_bf16 v[18:21], v[188:191], v[212:215], v[18:21]
	v_mfma_f32_16x16x32_bf16 v[6:9], v[180:183], v[220:223], v[6:9]
	v_mfma_f32_16x16x32_bf16 v[2:5], v[188:191], v[220:223], v[2:5]
	s_barrier
	s_add_i32 s66, 0, 0x18000
	v_add_u32_e32 v138, s66, v164
	s_add_i32 s67, 0, 0x1c000
	ds_read_b128 v[150:153], v138
	ds_read_b128 v[154:157], v138 offset:1024
	ds_read_b128 v[158:161], v138 offset:2048
	ds_read_b128 v[172:175], v138 offset:3072
	v_add_u32_e32 v138, s67, v164
	ds_read_b128 v[176:179], v138
	ds_read_b128 v[180:183], v138 offset:1024
	ds_read_b128 v[184:187], v138 offset:2048
	ds_read_b128 v[188:191], v138 offset:3072
	s_add_u32 s52, s52, 0x40000
	s_addc_u32 s53, s53, 0
	s_mov_b32 m0, s56
	v_lshl_add_u64 v[230:231], s[52:53], 0, v[130:131]
	ds_read_b128 v[192:195], v169 offset:32768
	ds_read_b128 v[196:199], v169 offset:33792
	ds_read_b128 v[200:203], v169 offset:34816
	ds_read_b128 v[204:207], v169 offset:35840
	ds_read_b128 v[208:211], v169 offset:36864
	ds_read_b128 v[212:215], v169 offset:37888
	ds_read_b128 v[216:219], v169 offset:38912
	ds_read_b128 v[220:223], v169 offset:39936
	global_load_lds_dwordx4 v[230:231], off
	v_lshl_add_u64 v[230:231], s[52:53], 0, v[134:135]
	s_mov_b32 m0, s57
	s_nop 0
	global_load_lds_dwordx4 v[230:231], off
	s_waitcnt vmcnt(8)
	s_waitcnt lgkmcnt(0)
	s_barrier
	s_waitcnt lgkmcnt(0)
	v_mfma_f32_16x16x32_bf16 v[126:129], v[150:153], v[192:195], v[126:129]
	v_mfma_f32_16x16x32_bf16 v[122:125], v[158:161], v[192:195], v[122:125]
	v_mfma_f32_16x16x32_bf16 v[110:113], v[150:153], v[200:203], v[110:113]
	v_mfma_f32_16x16x32_bf16 v[106:109], v[158:161], v[200:203], v[106:109]
	v_mfma_f32_16x16x32_bf16 v[94:97], v[150:153], v[208:211], v[94:97]
	v_mfma_f32_16x16x32_bf16 v[90:93], v[158:161], v[208:211], v[90:93]
	v_mfma_f32_16x16x32_bf16 v[78:81], v[150:153], v[216:219], v[78:81]
	v_mfma_f32_16x16x32_bf16 v[74:77], v[158:161], v[216:219], v[74:77]
	v_mfma_f32_16x16x32_bf16 v[126:129], v[154:157], v[196:199], v[126:129]
	v_mfma_f32_16x16x32_bf16 v[122:125], v[172:175], v[196:199], v[122:125]
	v_mfma_f32_16x16x32_bf16 v[110:113], v[154:157], v[204:207], v[110:113]
	v_mfma_f32_16x16x32_bf16 v[106:109], v[172:175], v[204:207], v[106:109]
	v_mfma_f32_16x16x32_bf16 v[94:97], v[154:157], v[212:215], v[94:97]
	v_mfma_f32_16x16x32_bf16 v[90:93], v[172:175], v[212:215], v[90:93]
	v_mfma_f32_16x16x32_bf16 v[78:81], v[154:157], v[220:223], v[78:81]
	v_mfma_f32_16x16x32_bf16 v[74:77], v[172:175], v[220:223], v[74:77]
	v_mfma_f32_16x16x32_bf16 v[118:121], v[176:179], v[192:195], v[118:121]
	v_mfma_f32_16x16x32_bf16 v[114:117], v[184:187], v[192:195], v[114:117]
	v_mfma_f32_16x16x32_bf16 v[102:105], v[176:179], v[200:203], v[102:105]
	v_mfma_f32_16x16x32_bf16 v[98:101], v[184:187], v[200:203], v[98:101]
	v_mfma_f32_16x16x32_bf16 v[86:89], v[176:179], v[208:211], v[86:89]
	v_mfma_f32_16x16x32_bf16 v[82:85], v[184:187], v[208:211], v[82:85]
	v_mfma_f32_16x16x32_bf16 v[70:73], v[176:179], v[216:219], v[70:73]
	v_mfma_f32_16x16x32_bf16 v[66:69], v[184:187], v[216:219], v[66:69]
	v_mfma_f32_16x16x32_bf16 v[118:121], v[180:183], v[196:199], v[118:121]
	v_mfma_f32_16x16x32_bf16 v[114:117], v[188:191], v[196:199], v[114:117]
	v_mfma_f32_16x16x32_bf16 v[102:105], v[180:183], v[204:207], v[102:105]
	v_mfma_f32_16x16x32_bf16 v[98:101], v[188:191], v[204:207], v[98:101]
	v_mfma_f32_16x16x32_bf16 v[86:89], v[180:183], v[212:215], v[86:89]
	v_mfma_f32_16x16x32_bf16 v[82:85], v[188:191], v[212:215], v[82:85]
	v_mfma_f32_16x16x32_bf16 v[70:73], v[180:183], v[220:223], v[70:73]
	v_mfma_f32_16x16x32_bf16 v[66:69], v[188:191], v[220:223], v[66:69]
	s_barrier
	s_add_i32 s52, s66, s35
	v_lshl_add_u64 v[162:163], v[162:163], 0, s[16:17]
	s_mov_b32 m0, s52
	ds_read_b128 v[192:195], v169 offset:49152
	ds_read_b128 v[196:199], v169 offset:50176
	ds_read_b128 v[200:203], v169 offset:51200
	ds_read_b128 v[204:207], v169 offset:52224
	ds_read_b128 v[208:211], v169 offset:53248
	ds_read_b128 v[212:215], v169 offset:54272
	ds_read_b128 v[216:219], v169 offset:55296
	ds_read_b128 v[220:223], v169 offset:56320
	global_load_lds_dwordx4 v[162:163], off
	s_add_i32 m0, s52, 0x2000
	s_add_u32 s50, s50, 0x40080
	v_lshl_add_u64 v[162:163], v[224:225], 0, s[16:17]
	s_addc_u32 s51, s51, 0
	s_add_i32 s52, s67, s35
	global_load_lds_dwordx4 v[162:163], off
	v_lshl_add_u64 v[162:163], s[50:51], 0, v[132:133]
	s_mov_b32 m0, s52
	s_nop 0
	global_load_lds_dwordx4 v[162:163], off
	v_lshl_add_u64 v[162:163], s[50:51], 0, v[136:137]
	s_add_i32 m0, s52, 0x2000
	s_nop 0
	global_load_lds_dwordx4 v[162:163], off
	v_lshl_add_u64 v[162:163], v[226:227], 0, s[16:17]
	s_mov_b32 m0, s61
	s_nop 0
	global_load_lds_dwordx4 v[162:163], off
	v_lshl_add_u64 v[162:163], v[228:229], 0, s[16:17]
	s_mov_b32 m0, s68
	s_nop 0
	global_load_lds_dwordx4 v[162:163], off
	s_waitcnt vmcnt(8)
	s_waitcnt lgkmcnt(0)
	s_barrier
	s_waitcnt lgkmcnt(0)
	v_mfma_f32_16x16x32_bf16 v[62:65], v[150:153], v[192:195], v[62:65]
	v_mfma_f32_16x16x32_bf16 v[58:61], v[158:161], v[192:195], v[58:61]
	v_mfma_f32_16x16x32_bf16 v[46:49], v[150:153], v[200:203], v[46:49]
	v_mfma_f32_16x16x32_bf16 v[42:45], v[158:161], v[200:203], v[42:45]
	v_mfma_f32_16x16x32_bf16 v[30:33], v[150:153], v[208:211], v[30:33]
	v_mfma_f32_16x16x32_bf16 v[26:29], v[158:161], v[208:211], v[26:29]
	v_mfma_f32_16x16x32_bf16 v[14:17], v[150:153], v[216:219], v[14:17]
	v_mfma_f32_16x16x32_bf16 v[10:13], v[158:161], v[216:219], v[10:13]
	v_mfma_f32_16x16x32_bf16 v[62:65], v[154:157], v[196:199], v[62:65]
	v_mfma_f32_16x16x32_bf16 v[58:61], v[172:175], v[196:199], v[58:61]
	v_mfma_f32_16x16x32_bf16 v[46:49], v[154:157], v[204:207], v[46:49]
	v_mfma_f32_16x16x32_bf16 v[42:45], v[172:175], v[204:207], v[42:45]
	v_mfma_f32_16x16x32_bf16 v[30:33], v[154:157], v[212:215], v[30:33]
	v_mfma_f32_16x16x32_bf16 v[26:29], v[172:175], v[212:215], v[26:29]
	v_mfma_f32_16x16x32_bf16 v[14:17], v[154:157], v[220:223], v[14:17]
	v_mfma_f32_16x16x32_bf16 v[10:13], v[172:175], v[220:223], v[10:13]
	v_mfma_f32_16x16x32_bf16 v[54:57], v[176:179], v[192:195], v[54:57]
	v_mfma_f32_16x16x32_bf16 v[50:53], v[184:187], v[192:195], v[50:53]
	v_mfma_f32_16x16x32_bf16 v[38:41], v[176:179], v[200:203], v[38:41]
	v_mfma_f32_16x16x32_bf16 v[34:37], v[184:187], v[200:203], v[34:37]
	v_mfma_f32_16x16x32_bf16 v[22:25], v[176:179], v[208:211], v[22:25]
	v_mfma_f32_16x16x32_bf16 v[18:21], v[184:187], v[208:211], v[18:21]
	v_mfma_f32_16x16x32_bf16 v[6:9], v[176:179], v[216:219], v[6:9]
	v_mfma_f32_16x16x32_bf16 v[2:5], v[184:187], v[216:219], v[2:5]
	v_mfma_f32_16x16x32_bf16 v[54:57], v[180:183], v[196:199], v[54:57]
	v_mfma_f32_16x16x32_bf16 v[50:53], v[188:191], v[196:199], v[50:53]
	v_mfma_f32_16x16x32_bf16 v[38:41], v[180:183], v[204:207], v[38:41]
	v_mfma_f32_16x16x32_bf16 v[34:37], v[188:191], v[204:207], v[34:37]
	v_mfma_f32_16x16x32_bf16 v[22:25], v[180:183], v[212:215], v[22:25]
	v_mfma_f32_16x16x32_bf16 v[18:21], v[188:191], v[212:215], v[18:21]
	v_mfma_f32_16x16x32_bf16 v[6:9], v[180:183], v[220:223], v[6:9]
	v_mfma_f32_16x16x32_bf16 v[2:5], v[188:191], v[220:223], v[2:5]
	s_add_i32 s81, s81, 2
	s_add_u32 s48, s48, 0x100
	s_addc_u32 s49, s49, 0
	s_add_u32 s79, s79, 0x100
	s_addc_u32 s80, s80, 0
	s_cmp_gt_u32 s81, 13
	s_barrier
	s_cbranch_scc0 .LBB0_2648
	s_and_b64 vcc, exec, s[18:19]
	s_cbranch_vccz .LBB0_2651
	s_barrier

.LBB0_2870:
	ds_read_b128 v[130:133], v172
	ds_read_b128 v[134:137], v172 offset:1024
	ds_read_b128 v[138:141], v172 offset:2048
	ds_read_b128 v[158:161], v172 offset:3072
	ds_read_b128 v[162:165], v173
	ds_read_b128 v[176:179], v173 offset:1024
	ds_read_b128 v[180:183], v173 offset:2048
	ds_read_b128 v[184:187], v173 offset:3072
	s_add_u32 s44, s42, 0xfffc0080
	s_addc_u32 s45, s43, -1
	s_cmp_eq_u32 s61, 12
	s_cselect_b32 s47, s19, s45
	s_cselect_b32 s46, s57, s44
	s_cselect_b32 s45, s17, s60
	s_cselect_b32 s44, s58, s59
	v_lshl_add_u64 v[166:167], s[42:43], 0, v[150:151]
	s_add_i32 m0, s35, 0xc000
	ds_read_b128 v[188:191], v174
	ds_read_b128 v[192:195], v174 offset:1024
	ds_read_b128 v[196:199], v174 offset:2048
	ds_read_b128 v[200:203], v174 offset:3072
	ds_read_b128 v[204:207], v174 offset:4096
	ds_read_b128 v[208:211], v174 offset:5120
	ds_read_b128 v[212:215], v174 offset:6144
	ds_read_b128 v[216:219], v174 offset:7168
	global_load_lds_dwordx4 v[166:167], off
	v_lshl_add_u64 v[166:167], s[42:43], 0, v[152:153]
	s_add_i32 m0, s35, 0xe000
	s_nop 0
	global_load_lds_dwordx4 v[166:167], off
	s_waitcnt vmcnt(8)
	s_waitcnt lgkmcnt(0)
	s_barrier
	s_waitcnt lgkmcnt(0)
	v_mfma_f32_16x16x32_bf16 v[126:129], v[130:133], v[188:191], v[126:129]
	v_mfma_f32_16x16x32_bf16 v[122:125], v[138:141], v[188:191], v[122:125]
	v_mfma_f32_16x16x32_bf16 v[114:117], v[130:133], v[196:199], v[114:117]
	v_mfma_f32_16x16x32_bf16 v[106:109], v[138:141], v[196:199], v[106:109]
	v_mfma_f32_16x16x32_bf16 v[94:97], v[130:133], v[204:207], v[94:97]
	v_mfma_f32_16x16x32_bf16 v[90:93], v[138:141], v[204:207], v[90:93]
	v_mfma_f32_16x16x32_bf16 v[78:81], v[130:133], v[212:215], v[78:81]
	v_mfma_f32_16x16x32_bf16 v[74:77], v[138:141], v[212:215], v[74:77]
	v_mfma_f32_16x16x32_bf16 v[126:129], v[134:137], v[192:195], v[126:129]
	v_mfma_f32_16x16x32_bf16 v[122:125], v[158:161], v[192:195], v[122:125]
	v_mfma_f32_16x16x32_bf16 v[114:117], v[134:137], v[200:203], v[114:117]
	v_mfma_f32_16x16x32_bf16 v[106:109], v[158:161], v[200:203], v[106:109]
	v_mfma_f32_16x16x32_bf16 v[94:97], v[134:137], v[208:211], v[94:97]
	v_mfma_f32_16x16x32_bf16 v[90:93], v[158:161], v[208:211], v[90:93]
	v_mfma_f32_16x16x32_bf16 v[78:81], v[134:137], v[216:219], v[78:81]
	v_mfma_f32_16x16x32_bf16 v[74:77], v[158:161], v[216:219], v[74:77]
	v_mfma_f32_16x16x32_bf16 v[118:121], v[162:165], v[188:191], v[118:121]
	v_mfma_f32_16x16x32_bf16 v[110:113], v[180:183], v[188:191], v[110:113]
	v_mfma_f32_16x16x32_bf16 v[102:105], v[162:165], v[196:199], v[102:105]
	v_mfma_f32_16x16x32_bf16 v[98:101], v[180:183], v[196:199], v[98:101]
	v_mfma_f32_16x16x32_bf16 v[86:89], v[162:165], v[204:207], v[86:89]
	v_mfma_f32_16x16x32_bf16 v[82:85], v[180:183], v[204:207], v[82:85]
	v_mfma_f32_16x16x32_bf16 v[70:73], v[162:165], v[212:215], v[70:73]
	v_mfma_f32_16x16x32_bf16 v[66:69], v[180:183], v[212:215], v[66:69]
	v_mfma_f32_16x16x32_bf16 v[118:121], v[176:179], v[192:195], v[118:121]
	v_mfma_f32_16x16x32_bf16 v[110:113], v[184:187], v[192:195], v[110:113]
	v_mfma_f32_16x16x32_bf16 v[102:105], v[176:179], v[200:203], v[102:105]
	v_mfma_f32_16x16x32_bf16 v[98:101], v[184:187], v[200:203], v[98:101]
	v_mfma_f32_16x16x32_bf16 v[86:89], v[176:179], v[208:211], v[86:89]
	v_mfma_f32_16x16x32_bf16 v[82:85], v[184:187], v[208:211], v[82:85]
	v_mfma_f32_16x16x32_bf16 v[70:73], v[176:179], v[216:219], v[70:73]
	v_mfma_f32_16x16x32_bf16 v[66:69], v[184:187], v[216:219], v[66:69]
	s_barrier
	s_add_i32 s66, s54, s33
	v_lshl_add_u64 v[166:167], s[44:45], 0, v[144:145]
	s_mov_b32 m0, s66
	ds_read_b128 v[188:191], v174 offset:16384
	ds_read_b128 v[192:195], v174 offset:17408
	ds_read_b128 v[196:199], v174 offset:18432
	ds_read_b128 v[200:203], v174 offset:19456
	ds_read_b128 v[204:207], v174 offset:20480
	ds_read_b128 v[208:211], v174 offset:21504
	ds_read_b128 v[212:215], v174 offset:22528
	ds_read_b128 v[216:219], v174 offset:23552
	global_load_lds_dwordx4 v[166:167], off
	s_add_i32 m0, s66, 0x2000
	s_add_u32 s66, s44, 0x40000
	v_lshl_add_u64 v[220:221], s[44:45], 0, v[148:149]
	s_addc_u32 s67, s45, 0
	s_add_i32 s68, s55, s33
	global_load_lds_dwordx4 v[220:221], off
	v_lshl_add_u64 v[222:223], s[66:67], 0, v[144:145]
	s_mov_b32 m0, s68
	v_lshl_add_u64 v[224:225], s[46:47], 0, v[146:147]
	global_load_lds_dwordx4 v[222:223], off
	v_lshl_add_u64 v[222:223], s[66:67], 0, v[148:149]
	s_add_i32 m0, s68, 0x2000
	s_nop 0
	global_load_lds_dwordx4 v[222:223], off
	v_lshl_add_u64 v[222:223], s[46:47], 0, v[142:143]
	s_mov_b32 m0, s35
	s_nop 0
	global_load_lds_dwordx4 v[222:223], off
	s_mov_b32 m0, s41
	s_nop 0
	global_load_lds_dwordx4 v[224:225], off
	s_waitcnt vmcnt(8)
	s_waitcnt lgkmcnt(0)
	s_barrier
	s_waitcnt lgkmcnt(0)
	v_mfma_f32_16x16x32_bf16 v[62:65], v[130:133], v[188:191], v[62:65]
	v_mfma_f32_16x16x32_bf16 v[58:61], v[138:141], v[188:191], v[58:61]
	v_mfma_f32_16x16x32_bf16 v[50:53], v[130:133], v[196:199], v[50:53]
	v_mfma_f32_16x16x32_bf16 v[42:45], v[138:141], v[196:199], v[42:45]
	v_mfma_f32_16x16x32_bf16 v[38:41], v[130:133], v[204:207], v[38:41]
	v_mfma_f32_16x16x32_bf16 v[30:33], v[138:141], v[204:207], v[30:33]
	v_mfma_f32_16x16x32_bf16 v[22:25], v[130:133], v[212:215], v[22:25]
	v_mfma_f32_16x16x32_bf16 v[14:17], v[138:141], v[212:215], v[14:17]
	v_mfma_f32_16x16x32_bf16 v[62:65], v[134:137], v[192:195], v[62:65]
	v_mfma_f32_16x16x32_bf16 v[58:61], v[158:161], v[192:195], v[58:61]
	v_mfma_f32_16x16x32_bf16 v[50:53], v[134:137], v[200:203], v[50:53]
	v_mfma_f32_16x16x32_bf16 v[42:45], v[158:161], v[200:203], v[42:45]
	v_mfma_f32_16x16x32_bf16 v[38:41], v[134:137], v[208:211], v[38:41]
	v_mfma_f32_16x16x32_bf16 v[30:33], v[158:161], v[208:211], v[30:33]
	v_mfma_f32_16x16x32_bf16 v[22:25], v[134:137], v[216:219], v[22:25]
	v_mfma_f32_16x16x32_bf16 v[14:17], v[158:161], v[216:219], v[14:17]
	v_mfma_f32_16x16x32_bf16 v[54:57], v[162:165], v[188:191], v[54:57]
	v_mfma_f32_16x16x32_bf16 v[46:49], v[180:183], v[188:191], v[46:49]
	v_mfma_f32_16x16x32_bf16 v[34:37], v[162:165], v[196:199], v[34:37]
	v_mfma_f32_16x16x32_bf16 v[26:29], v[180:183], v[196:199], v[26:29]
	v_mfma_f32_16x16x32_bf16 v[18:21], v[162:165], v[204:207], v[18:21]
	v_mfma_f32_16x16x32_bf16 v[10:13], v[180:183], v[204:207], v[10:13]
	v_mfma_f32_16x16x32_bf16 v[6:9], v[162:165], v[212:215], v[6:9]
	v_mfma_f32_16x16x32_bf16 v[2:5], v[180:183], v[212:215], v[2:5]
	v_mfma_f32_16x16x32_bf16 v[54:57], v[176:179], v[192:195], v[54:57]
	v_mfma_f32_16x16x32_bf16 v[46:49], v[184:187], v[192:195], v[46:49]
	v_mfma_f32_16x16x32_bf16 v[34:37], v[176:179], v[200:203], v[34:37]
	v_mfma_f32_16x16x32_bf16 v[26:29], v[184:187], v[200:203], v[26:29]
	v_mfma_f32_16x16x32_bf16 v[18:21], v[176:179], v[208:211], v[18:21]
	v_mfma_f32_16x16x32_bf16 v[10:13], v[184:187], v[208:211], v[10:13]
	v_mfma_f32_16x16x32_bf16 v[6:9], v[176:179], v[216:219], v[6:9]
	v_mfma_f32_16x16x32_bf16 v[2:5], v[184:187], v[216:219], v[2:5]
	s_barrier
	s_add_i32 s66, 0, 0x18000
	s_add_i32 s67, 0, 0x1c000
	v_add_u32_e32 v158, s66, v170
	v_add_u32_e32 v175, s67, v170
	ds_read_b128 v[130:133], v158
	ds_read_b128 v[134:137], v158 offset:1024
	ds_read_b128 v[138:141], v158 offset:2048
	ds_read_b128 v[158:161], v158 offset:3072
	ds_read_b128 v[162:165], v175
	ds_read_b128 v[176:179], v175 offset:1024
	ds_read_b128 v[180:183], v175 offset:2048
	ds_read_b128 v[184:187], v175 offset:3072
	s_add_u32 s46, s46, 0x40000
	s_addc_u32 s47, s47, 0
	s_mov_b32 m0, s48
	v_lshl_add_u64 v[226:227], s[46:47], 0, v[142:143]
	ds_read_b128 v[188:191], v174 offset:32768
	ds_read_b128 v[192:195], v174 offset:33792
	ds_read_b128 v[196:199], v174 offset:34816
	ds_read_b128 v[200:203], v174 offset:35840
	ds_read_b128 v[204:207], v174 offset:36864
	ds_read_b128 v[208:211], v174 offset:37888
	ds_read_b128 v[212:215], v174 offset:38912
	ds_read_b128 v[216:219], v174 offset:39936
	global_load_lds_dwordx4 v[226:227], off
	v_lshl_add_u64 v[226:227], s[46:47], 0, v[146:147]
	s_mov_b32 m0, s49
	s_nop 0
	global_load_lds_dwordx4 v[226:227], off
	s_waitcnt vmcnt(8)
	s_waitcnt lgkmcnt(0)
	s_barrier
	s_waitcnt lgkmcnt(0)
	v_mfma_f32_16x16x32_bf16 v[126:129], v[130:133], v[188:191], v[126:129]
	v_mfma_f32_16x16x32_bf16 v[122:125], v[138:141], v[188:191], v[122:125]
	v_mfma_f32_16x16x32_bf16 v[114:117], v[130:133], v[196:199], v[114:117]
	v_mfma_f32_16x16x32_bf16 v[106:109], v[138:141], v[196:199], v[106:109]
	v_mfma_f32_16x16x32_bf16 v[94:97], v[130:133], v[204:207], v[94:97]
	v_mfma_f32_16x16x32_bf16 v[90:93], v[138:141], v[204:207], v[90:93]
	v_mfma_f32_16x16x32_bf16 v[78:81], v[130:133], v[212:215], v[78:81]
	v_mfma_f32_16x16x32_bf16 v[74:77], v[138:141], v[212:215], v[74:77]
	v_mfma_f32_16x16x32_bf16 v[126:129], v[134:137], v[192:195], v[126:129]
	v_mfma_f32_16x16x32_bf16 v[122:125], v[158:161], v[192:195], v[122:125]
	v_mfma_f32_16x16x32_bf16 v[114:117], v[134:137], v[200:203], v[114:117]
	v_mfma_f32_16x16x32_bf16 v[106:109], v[158:161], v[200:203], v[106:109]
	v_mfma_f32_16x16x32_bf16 v[94:97], v[134:137], v[208:211], v[94:97]
	v_mfma_f32_16x16x32_bf16 v[90:93], v[158:161], v[208:211], v[90:93]
	v_mfma_f32_16x16x32_bf16 v[78:81], v[134:137], v[216:219], v[78:81]
	v_mfma_f32_16x16x32_bf16 v[74:77], v[158:161], v[216:219], v[74:77]
	v_mfma_f32_16x16x32_bf16 v[118:121], v[162:165], v[188:191], v[118:121]
	v_mfma_f32_16x16x32_bf16 v[110:113], v[180:183], v[188:191], v[110:113]
	v_mfma_f32_16x16x32_bf16 v[102:105], v[162:165], v[196:199], v[102:105]
	v_mfma_f32_16x16x32_bf16 v[98:101], v[180:183], v[196:199], v[98:101]
	v_mfma_f32_16x16x32_bf16 v[86:89], v[162:165], v[204:207], v[86:89]
	v_mfma_f32_16x16x32_bf16 v[82:85], v[180:183], v[204:207], v[82:85]
	v_mfma_f32_16x16x32_bf16 v[70:73], v[162:165], v[212:215], v[70:73]
	v_mfma_f32_16x16x32_bf16 v[66:69], v[180:183], v[212:215], v[66:69]
	v_mfma_f32_16x16x32_bf16 v[118:121], v[176:179], v[192:195], v[118:121]
	v_mfma_f32_16x16x32_bf16 v[110:113], v[184:187], v[192:195], v[110:113]
	v_mfma_f32_16x16x32_bf16 v[102:105], v[176:179], v[200:203], v[102:105]
	v_mfma_f32_16x16x32_bf16 v[98:101], v[184:187], v[200:203], v[98:101]
	v_mfma_f32_16x16x32_bf16 v[86:89], v[176:179], v[208:211], v[86:89]
	v_mfma_f32_16x16x32_bf16 v[82:85], v[184:187], v[208:211], v[82:85]
	v_mfma_f32_16x16x32_bf16 v[70:73], v[176:179], v[216:219], v[70:73]
	v_mfma_f32_16x16x32_bf16 v[66:69], v[184:187], v[216:219], v[66:69]
	s_barrier
	s_add_i32 s46, s66, s33
	v_lshl_add_u64 v[166:167], v[166:167], 0, s[10:11]
	s_mov_b32 m0, s46
	ds_read_b128 v[188:191], v174 offset:49152
	ds_read_b128 v[192:195], v174 offset:50176
	ds_read_b128 v[196:199], v174 offset:51200
	ds_read_b128 v[200:203], v174 offset:52224
	ds_read_b128 v[204:207], v174 offset:53248
	ds_read_b128 v[208:211], v174 offset:54272
	ds_read_b128 v[212:215], v174 offset:55296
	ds_read_b128 v[216:219], v174 offset:56320
	global_load_lds_dwordx4 v[166:167], off
	s_add_i32 m0, s46, 0x2000
	s_add_u32 s44, s44, 0x40080
	v_lshl_add_u64 v[166:167], v[220:221], 0, s[10:11]
	s_addc_u32 s45, s45, 0
	s_add_i32 s46, s67, s33
	global_load_lds_dwordx4 v[166:167], off
	v_lshl_add_u64 v[166:167], s[44:45], 0, v[144:145]
	s_mov_b32 m0, s46
	s_nop 0
	global_load_lds_dwordx4 v[166:167], off
	v_lshl_add_u64 v[166:167], s[44:45], 0, v[148:149]
	s_add_i32 m0, s46, 0x2000
	s_nop 0
	global_load_lds_dwordx4 v[166:167], off
	v_lshl_add_u64 v[166:167], v[222:223], 0, s[10:11]
	s_mov_b32 m0, s51
	s_nop 0
	global_load_lds_dwordx4 v[166:167], off
	v_lshl_add_u64 v[166:167], v[224:225], 0, s[10:11]
	s_mov_b32 m0, s52
	s_nop 0
	global_load_lds_dwordx4 v[166:167], off
	s_waitcnt vmcnt(8)
	s_waitcnt lgkmcnt(0)
	s_barrier
	s_waitcnt lgkmcnt(0)
	v_mfma_f32_16x16x32_bf16 v[62:65], v[130:133], v[188:191], v[62:65]
	v_mfma_f32_16x16x32_bf16 v[58:61], v[138:141], v[188:191], v[58:61]
	v_mfma_f32_16x16x32_bf16 v[50:53], v[130:133], v[196:199], v[50:53]
	v_mfma_f32_16x16x32_bf16 v[42:45], v[138:141], v[196:199], v[42:45]
	v_mfma_f32_16x16x32_bf16 v[38:41], v[130:133], v[204:207], v[38:41]
	v_mfma_f32_16x16x32_bf16 v[30:33], v[138:141], v[204:207], v[30:33]
	v_mfma_f32_16x16x32_bf16 v[22:25], v[130:133], v[212:215], v[22:25]
	v_mfma_f32_16x16x32_bf16 v[14:17], v[138:141], v[212:215], v[14:17]
	v_mfma_f32_16x16x32_bf16 v[62:65], v[134:137], v[192:195], v[62:65]
	v_mfma_f32_16x16x32_bf16 v[58:61], v[158:161], v[192:195], v[58:61]
	v_mfma_f32_16x16x32_bf16 v[50:53], v[134:137], v[200:203], v[50:53]
	v_mfma_f32_16x16x32_bf16 v[42:45], v[158:161], v[200:203], v[42:45]
	v_mfma_f32_16x16x32_bf16 v[38:41], v[134:137], v[208:211], v[38:41]
	v_mfma_f32_16x16x32_bf16 v[30:33], v[158:161], v[208:211], v[30:33]
	v_mfma_f32_16x16x32_bf16 v[22:25], v[134:137], v[216:219], v[22:25]
	v_mfma_f32_16x16x32_bf16 v[14:17], v[158:161], v[216:219], v[14:17]
	v_mfma_f32_16x16x32_bf16 v[54:57], v[162:165], v[188:191], v[54:57]
	v_mfma_f32_16x16x32_bf16 v[46:49], v[180:183], v[188:191], v[46:49]
	v_mfma_f32_16x16x32_bf16 v[34:37], v[162:165], v[196:199], v[34:37]
	v_mfma_f32_16x16x32_bf16 v[26:29], v[180:183], v[196:199], v[26:29]
	v_mfma_f32_16x16x32_bf16 v[18:21], v[162:165], v[204:207], v[18:21]
	v_mfma_f32_16x16x32_bf16 v[10:13], v[180:183], v[204:207], v[10:13]
	v_mfma_f32_16x16x32_bf16 v[6:9], v[162:165], v[212:215], v[6:9]
	v_mfma_f32_16x16x32_bf16 v[2:5], v[180:183], v[212:215], v[2:5]
	v_mfma_f32_16x16x32_bf16 v[54:57], v[176:179], v[192:195], v[54:57]
	v_mfma_f32_16x16x32_bf16 v[46:49], v[184:187], v[192:195], v[46:49]
	v_mfma_f32_16x16x32_bf16 v[34:37], v[176:179], v[200:203], v[34:37]
	v_mfma_f32_16x16x32_bf16 v[26:29], v[184:187], v[200:203], v[26:29]
	v_mfma_f32_16x16x32_bf16 v[18:21], v[176:179], v[208:211], v[18:21]
	v_mfma_f32_16x16x32_bf16 v[10:13], v[184:187], v[208:211], v[10:13]
	v_mfma_f32_16x16x32_bf16 v[6:9], v[176:179], v[216:219], v[6:9]
	v_mfma_f32_16x16x32_bf16 v[2:5], v[184:187], v[216:219], v[2:5]
	s_add_i32 s61, s61, 2
	s_add_u32 s42, s42, 0x100
	s_addc_u32 s43, s43, 0
	s_add_u32 s59, s59, 0x100
	s_addc_u32 s60, s60, 0
	s_cmp_gt_u32 s61, 13
	s_barrier
	s_cbranch_scc0 .LBB0_2870
	s_and_b64 vcc, exec, s[12:13]
	s_cbranch_vccz .LBB0_2873
	s_barrier

.LBB0_2916:
	ds_read_b128 v[150:153], v166
	ds_read_b128 v[154:157], v166 offset:1024
	ds_read_b128 v[170:173], v166 offset:2048
	ds_read_b128 v[174:177], v166 offset:3072
	ds_read_b128 v[178:181], v167
	ds_read_b128 v[182:185], v167 offset:1024
	ds_read_b128 v[186:189], v167 offset:2048
	ds_read_b128 v[190:193], v167 offset:3072
	s_add_u32 s46, s44, 0xfffc0080
	s_addc_u32 s47, s45, -1
	s_cmp_eq_u32 s71, 12
	s_cselect_b32 s49, s39, s47
	s_cselect_b32 s48, s61, s46
	s_cselect_b32 s47, s23, s70
	s_cselect_b32 s46, s68, s69
	v_lshl_add_u64 v[158:159], s[44:45], 0, v[142:143]
	s_add_i32 m0, s33, 0xc000
	ds_read_b128 v[194:197], v168
	ds_read_b128 v[198:201], v168 offset:1024
	ds_read_b128 v[202:205], v168 offset:2048
	ds_read_b128 v[206:209], v168 offset:3072
	ds_read_b128 v[210:213], v168 offset:4096
	ds_read_b128 v[214:217], v168 offset:5120
	ds_read_b128 v[218:221], v168 offset:6144
	ds_read_b128 v[222:225], v168 offset:7168
	global_load_lds_dwordx4 v[158:159], off
	v_lshl_add_u64 v[158:159], s[44:45], 0, v[144:145]
	s_add_i32 m0, s33, 0xe000
	s_nop 0
	global_load_lds_dwordx4 v[158:159], off
	s_waitcnt vmcnt(8)
	s_waitcnt lgkmcnt(0)
	s_barrier
	s_waitcnt lgkmcnt(0)
	v_mfma_f32_16x16x32_bf16 v[126:129], v[150:153], v[194:197], v[126:129]
	v_mfma_f32_16x16x32_bf16 v[122:125], v[170:173], v[194:197], v[122:125]
	v_mfma_f32_16x16x32_bf16 v[110:113], v[150:153], v[202:205], v[110:113]
	v_mfma_f32_16x16x32_bf16 v[106:109], v[170:173], v[202:205], v[106:109]
	v_mfma_f32_16x16x32_bf16 v[94:97], v[150:153], v[210:213], v[94:97]
	v_mfma_f32_16x16x32_bf16 v[90:93], v[170:173], v[210:213], v[90:93]
	v_mfma_f32_16x16x32_bf16 v[78:81], v[150:153], v[218:221], v[78:81]
	v_mfma_f32_16x16x32_bf16 v[74:77], v[170:173], v[218:221], v[74:77]
	v_mfma_f32_16x16x32_bf16 v[126:129], v[154:157], v[198:201], v[126:129]
	v_mfma_f32_16x16x32_bf16 v[122:125], v[174:177], v[198:201], v[122:125]
	v_mfma_f32_16x16x32_bf16 v[110:113], v[154:157], v[206:209], v[110:113]
	v_mfma_f32_16x16x32_bf16 v[106:109], v[174:177], v[206:209], v[106:109]
	v_mfma_f32_16x16x32_bf16 v[94:97], v[154:157], v[214:217], v[94:97]
	v_mfma_f32_16x16x32_bf16 v[90:93], v[174:177], v[214:217], v[90:93]
	v_mfma_f32_16x16x32_bf16 v[78:81], v[154:157], v[222:225], v[78:81]
	v_mfma_f32_16x16x32_bf16 v[74:77], v[174:177], v[222:225], v[74:77]
	v_mfma_f32_16x16x32_bf16 v[118:121], v[178:181], v[194:197], v[118:121]
	v_mfma_f32_16x16x32_bf16 v[114:117], v[186:189], v[194:197], v[114:117]
	v_mfma_f32_16x16x32_bf16 v[102:105], v[178:181], v[202:205], v[102:105]
	v_mfma_f32_16x16x32_bf16 v[98:101], v[186:189], v[202:205], v[98:101]
	v_mfma_f32_16x16x32_bf16 v[86:89], v[178:181], v[210:213], v[86:89]
	v_mfma_f32_16x16x32_bf16 v[82:85], v[186:189], v[210:213], v[82:85]
	v_mfma_f32_16x16x32_bf16 v[70:73], v[178:181], v[218:221], v[70:73]
	v_mfma_f32_16x16x32_bf16 v[66:69], v[186:189], v[218:221], v[66:69]
	v_mfma_f32_16x16x32_bf16 v[118:121], v[182:185], v[198:201], v[118:121]
	v_mfma_f32_16x16x32_bf16 v[114:117], v[190:193], v[198:201], v[114:117]
	v_mfma_f32_16x16x32_bf16 v[102:105], v[182:185], v[206:209], v[102:105]
	v_mfma_f32_16x16x32_bf16 v[98:101], v[190:193], v[206:209], v[98:101]
	v_mfma_f32_16x16x32_bf16 v[86:89], v[182:185], v[214:217], v[86:89]
	v_mfma_f32_16x16x32_bf16 v[82:85], v[190:193], v[214:217], v[82:85]
	v_mfma_f32_16x16x32_bf16 v[70:73], v[182:185], v[222:225], v[70:73]
	v_mfma_f32_16x16x32_bf16 v[66:69], v[190:193], v[222:225], v[66:69]
	s_barrier
	s_add_i32 s66, s58, s21
	v_lshl_add_u64 v[158:159], s[46:47], 0, v[132:133]
	s_mov_b32 m0, s66
	ds_read_b128 v[194:197], v168 offset:16384
	ds_read_b128 v[198:201], v168 offset:17408
	ds_read_b128 v[202:205], v168 offset:18432
	ds_read_b128 v[206:209], v168 offset:19456
	ds_read_b128 v[210:213], v168 offset:20480
	ds_read_b128 v[214:217], v168 offset:21504
	ds_read_b128 v[218:221], v168 offset:22528
	ds_read_b128 v[222:225], v168 offset:23552
	global_load_lds_dwordx4 v[158:159], off
	s_add_i32 m0, s66, 0x2000
	s_add_u32 s66, s46, 0x40000
	v_lshl_add_u64 v[226:227], s[46:47], 0, v[136:137]
	s_addc_u32 s67, s47, 0
	s_add_i32 s72, s59, s21
	global_load_lds_dwordx4 v[226:227], off
	v_lshl_add_u64 v[228:229], s[66:67], 0, v[132:133]
	s_mov_b32 m0, s72
	v_lshl_add_u64 v[230:231], s[48:49], 0, v[134:135]
	global_load_lds_dwordx4 v[228:229], off
	v_lshl_add_u64 v[228:229], s[66:67], 0, v[136:137]
	s_add_i32 m0, s72, 0x2000
	s_nop 0
	global_load_lds_dwordx4 v[228:229], off
	v_lshl_add_u64 v[228:229], s[48:49], 0, v[130:131]
	s_mov_b32 m0, s33
	s_nop 0
	global_load_lds_dwordx4 v[228:229], off
	s_mov_b32 m0, s35
	s_nop 0
	global_load_lds_dwordx4 v[230:231], off
	s_waitcnt vmcnt(8)
	s_waitcnt lgkmcnt(0)
	s_barrier
	s_waitcnt lgkmcnt(0)
	v_mfma_f32_16x16x32_bf16 v[62:65], v[150:153], v[194:197], v[62:65]
	v_mfma_f32_16x16x32_bf16 v[58:61], v[170:173], v[194:197], v[58:61]
	v_mfma_f32_16x16x32_bf16 v[46:49], v[150:153], v[202:205], v[46:49]
	v_mfma_f32_16x16x32_bf16 v[42:45], v[170:173], v[202:205], v[42:45]
	v_mfma_f32_16x16x32_bf16 v[30:33], v[150:153], v[210:213], v[30:33]
	v_mfma_f32_16x16x32_bf16 v[26:29], v[170:173], v[210:213], v[26:29]
	v_mfma_f32_16x16x32_bf16 v[14:17], v[150:153], v[218:221], v[14:17]
	v_mfma_f32_16x16x32_bf16 v[10:13], v[170:173], v[218:221], v[10:13]
	v_mfma_f32_16x16x32_bf16 v[62:65], v[154:157], v[198:201], v[62:65]
	v_mfma_f32_16x16x32_bf16 v[58:61], v[174:177], v[198:201], v[58:61]
	v_mfma_f32_16x16x32_bf16 v[46:49], v[154:157], v[206:209], v[46:49]
	v_mfma_f32_16x16x32_bf16 v[42:45], v[174:177], v[206:209], v[42:45]
	v_mfma_f32_16x16x32_bf16 v[30:33], v[154:157], v[214:217], v[30:33]
	v_mfma_f32_16x16x32_bf16 v[26:29], v[174:177], v[214:217], v[26:29]
	v_mfma_f32_16x16x32_bf16 v[14:17], v[154:157], v[222:225], v[14:17]
	v_mfma_f32_16x16x32_bf16 v[10:13], v[174:177], v[222:225], v[10:13]
	v_mfma_f32_16x16x32_bf16 v[54:57], v[178:181], v[194:197], v[54:57]
	v_mfma_f32_16x16x32_bf16 v[50:53], v[186:189], v[194:197], v[50:53]
	v_mfma_f32_16x16x32_bf16 v[38:41], v[178:181], v[202:205], v[38:41]
	v_mfma_f32_16x16x32_bf16 v[34:37], v[186:189], v[202:205], v[34:37]
	v_mfma_f32_16x16x32_bf16 v[22:25], v[178:181], v[210:213], v[22:25]
	v_mfma_f32_16x16x32_bf16 v[18:21], v[186:189], v[210:213], v[18:21]
	v_mfma_f32_16x16x32_bf16 v[6:9], v[178:181], v[218:221], v[6:9]
	v_mfma_f32_16x16x32_bf16 v[2:5], v[186:189], v[218:221], v[2:5]
	v_mfma_f32_16x16x32_bf16 v[54:57], v[182:185], v[198:201], v[54:57]
	v_mfma_f32_16x16x32_bf16 v[50:53], v[190:193], v[198:201], v[50:53]
	v_mfma_f32_16x16x32_bf16 v[38:41], v[182:185], v[206:209], v[38:41]
	v_mfma_f32_16x16x32_bf16 v[34:37], v[190:193], v[206:209], v[34:37]
	v_mfma_f32_16x16x32_bf16 v[22:25], v[182:185], v[214:217], v[22:25]
	v_mfma_f32_16x16x32_bf16 v[18:21], v[190:193], v[214:217], v[18:21]
	v_mfma_f32_16x16x32_bf16 v[6:9], v[182:185], v[222:225], v[6:9]
	v_mfma_f32_16x16x32_bf16 v[2:5], v[190:193], v[222:225], v[2:5]
	s_barrier
	s_add_i32 s66, 0, 0x18000
	s_add_i32 s67, 0, 0x1c000
	v_add_u32_e32 v174, s66, v164
	v_add_u32_e32 v190, s67, v164
	ds_read_b128 v[150:153], v174
	ds_read_b128 v[154:157], v174 offset:1024
	ds_read_b128 v[170:173], v174 offset:2048
	ds_read_b128 v[174:177], v174 offset:3072
	ds_read_b128 v[178:181], v190
	ds_read_b128 v[182:185], v190 offset:1024
	ds_read_b128 v[186:189], v190 offset:2048
	ds_read_b128 v[190:193], v190 offset:3072
	s_add_u32 s48, s48, 0x40000
	s_addc_u32 s49, s49, 0
	s_mov_b32 m0, s50
	v_lshl_add_u64 v[232:233], s[48:49], 0, v[130:131]
	ds_read_b128 v[194:197], v168 offset:32768
	ds_read_b128 v[198:201], v168 offset:33792
	ds_read_b128 v[202:205], v168 offset:34816
	ds_read_b128 v[206:209], v168 offset:35840
	ds_read_b128 v[210:213], v168 offset:36864
	ds_read_b128 v[214:217], v168 offset:37888
	ds_read_b128 v[218:221], v168 offset:38912
	ds_read_b128 v[222:225], v168 offset:39936
	global_load_lds_dwordx4 v[232:233], off
	v_lshl_add_u64 v[232:233], s[48:49], 0, v[134:135]
	s_mov_b32 m0, s51
	s_nop 0
	global_load_lds_dwordx4 v[232:233], off
	s_waitcnt vmcnt(8)
	s_waitcnt lgkmcnt(0)
	s_barrier
	s_waitcnt lgkmcnt(0)
	v_mfma_f32_16x16x32_bf16 v[126:129], v[150:153], v[194:197], v[126:129]
	v_mfma_f32_16x16x32_bf16 v[122:125], v[170:173], v[194:197], v[122:125]
	v_mfma_f32_16x16x32_bf16 v[110:113], v[150:153], v[202:205], v[110:113]
	v_mfma_f32_16x16x32_bf16 v[106:109], v[170:173], v[202:205], v[106:109]
	v_mfma_f32_16x16x32_bf16 v[94:97], v[150:153], v[210:213], v[94:97]
	v_mfma_f32_16x16x32_bf16 v[90:93], v[170:173], v[210:213], v[90:93]
	v_mfma_f32_16x16x32_bf16 v[78:81], v[150:153], v[218:221], v[78:81]
	v_mfma_f32_16x16x32_bf16 v[74:77], v[170:173], v[218:221], v[74:77]
	v_mfma_f32_16x16x32_bf16 v[126:129], v[154:157], v[198:201], v[126:129]
	v_mfma_f32_16x16x32_bf16 v[122:125], v[174:177], v[198:201], v[122:125]
	v_mfma_f32_16x16x32_bf16 v[110:113], v[154:157], v[206:209], v[110:113]
	v_mfma_f32_16x16x32_bf16 v[106:109], v[174:177], v[206:209], v[106:109]
	v_mfma_f32_16x16x32_bf16 v[94:97], v[154:157], v[214:217], v[94:97]
	v_mfma_f32_16x16x32_bf16 v[90:93], v[174:177], v[214:217], v[90:93]
	v_mfma_f32_16x16x32_bf16 v[78:81], v[154:157], v[222:225], v[78:81]
	v_mfma_f32_16x16x32_bf16 v[74:77], v[174:177], v[222:225], v[74:77]
	v_mfma_f32_16x16x32_bf16 v[118:121], v[178:181], v[194:197], v[118:121]
	v_mfma_f32_16x16x32_bf16 v[114:117], v[186:189], v[194:197], v[114:117]
	v_mfma_f32_16x16x32_bf16 v[102:105], v[178:181], v[202:205], v[102:105]
	v_mfma_f32_16x16x32_bf16 v[98:101], v[186:189], v[202:205], v[98:101]
	v_mfma_f32_16x16x32_bf16 v[86:89], v[178:181], v[210:213], v[86:89]
	v_mfma_f32_16x16x32_bf16 v[82:85], v[186:189], v[210:213], v[82:85]
	v_mfma_f32_16x16x32_bf16 v[70:73], v[178:181], v[218:221], v[70:73]
	v_mfma_f32_16x16x32_bf16 v[66:69], v[186:189], v[218:221], v[66:69]
	v_mfma_f32_16x16x32_bf16 v[118:121], v[182:185], v[198:201], v[118:121]
	v_mfma_f32_16x16x32_bf16 v[114:117], v[190:193], v[198:201], v[114:117]
	v_mfma_f32_16x16x32_bf16 v[102:105], v[182:185], v[206:209], v[102:105]
	v_mfma_f32_16x16x32_bf16 v[98:101], v[190:193], v[206:209], v[98:101]
	v_mfma_f32_16x16x32_bf16 v[86:89], v[182:185], v[214:217], v[86:89]
	v_mfma_f32_16x16x32_bf16 v[82:85], v[190:193], v[214:217], v[82:85]
	v_mfma_f32_16x16x32_bf16 v[70:73], v[182:185], v[222:225], v[70:73]
	v_mfma_f32_16x16x32_bf16 v[66:69], v[190:193], v[222:225], v[66:69]
	s_barrier
	s_add_i32 s48, s66, s21
	v_lshl_add_u64 v[158:159], v[158:159], 0, s[10:11]
	s_mov_b32 m0, s48
	ds_read_b128 v[194:197], v168 offset:49152
	ds_read_b128 v[198:201], v168 offset:50176
	ds_read_b128 v[202:205], v168 offset:51200
	ds_read_b128 v[206:209], v168 offset:52224
	ds_read_b128 v[210:213], v168 offset:53248
	ds_read_b128 v[214:217], v168 offset:54272
	ds_read_b128 v[218:221], v168 offset:55296
	ds_read_b128 v[222:225], v168 offset:56320
	global_load_lds_dwordx4 v[158:159], off
	s_add_i32 m0, s48, 0x2000
	s_add_u32 s46, s46, 0x40080
	v_lshl_add_u64 v[158:159], v[226:227], 0, s[10:11]
	s_addc_u32 s47, s47, 0
	s_add_i32 s48, s67, s21
	global_load_lds_dwordx4 v[158:159], off
	v_lshl_add_u64 v[158:159], s[46:47], 0, v[132:133]
	s_mov_b32 m0, s48
	s_nop 0
	global_load_lds_dwordx4 v[158:159], off
	v_lshl_add_u64 v[158:159], s[46:47], 0, v[136:137]
	s_add_i32 m0, s48, 0x2000
	s_nop 0
	global_load_lds_dwordx4 v[158:159], off
	v_lshl_add_u64 v[158:159], v[228:229], 0, s[10:11]
	s_mov_b32 m0, s53
	s_nop 0
	global_load_lds_dwordx4 v[158:159], off
	v_lshl_add_u64 v[158:159], v[230:231], 0, s[10:11]
	s_mov_b32 m0, s54
	s_nop 0
	global_load_lds_dwordx4 v[158:159], off
	s_waitcnt vmcnt(8)
	s_waitcnt lgkmcnt(0)
	s_barrier
	s_waitcnt lgkmcnt(0)
	v_mfma_f32_16x16x32_bf16 v[62:65], v[150:153], v[194:197], v[62:65]
	v_mfma_f32_16x16x32_bf16 v[58:61], v[170:173], v[194:197], v[58:61]
	v_mfma_f32_16x16x32_bf16 v[46:49], v[150:153], v[202:205], v[46:49]
	v_mfma_f32_16x16x32_bf16 v[42:45], v[170:173], v[202:205], v[42:45]
	v_mfma_f32_16x16x32_bf16 v[30:33], v[150:153], v[210:213], v[30:33]
	v_mfma_f32_16x16x32_bf16 v[26:29], v[170:173], v[210:213], v[26:29]
	v_mfma_f32_16x16x32_bf16 v[14:17], v[150:153], v[218:221], v[14:17]
	v_mfma_f32_16x16x32_bf16 v[10:13], v[170:173], v[218:221], v[10:13]
	v_mfma_f32_16x16x32_bf16 v[62:65], v[154:157], v[198:201], v[62:65]
	v_mfma_f32_16x16x32_bf16 v[58:61], v[174:177], v[198:201], v[58:61]
	v_mfma_f32_16x16x32_bf16 v[46:49], v[154:157], v[206:209], v[46:49]
	v_mfma_f32_16x16x32_bf16 v[42:45], v[174:177], v[206:209], v[42:45]
	v_mfma_f32_16x16x32_bf16 v[30:33], v[154:157], v[214:217], v[30:33]
	v_mfma_f32_16x16x32_bf16 v[26:29], v[174:177], v[214:217], v[26:29]
	v_mfma_f32_16x16x32_bf16 v[14:17], v[154:157], v[222:225], v[14:17]
	v_mfma_f32_16x16x32_bf16 v[10:13], v[174:177], v[222:225], v[10:13]
	v_mfma_f32_16x16x32_bf16 v[54:57], v[178:181], v[194:197], v[54:57]
	v_mfma_f32_16x16x32_bf16 v[50:53], v[186:189], v[194:197], v[50:53]
	v_mfma_f32_16x16x32_bf16 v[38:41], v[178:181], v[202:205], v[38:41]
	v_mfma_f32_16x16x32_bf16 v[34:37], v[186:189], v[202:205], v[34:37]
	v_mfma_f32_16x16x32_bf16 v[22:25], v[178:181], v[210:213], v[22:25]
	v_mfma_f32_16x16x32_bf16 v[18:21], v[186:189], v[210:213], v[18:21]
	v_mfma_f32_16x16x32_bf16 v[6:9], v[178:181], v[218:221], v[6:9]
	v_mfma_f32_16x16x32_bf16 v[2:5], v[186:189], v[218:221], v[2:5]
	v_mfma_f32_16x16x32_bf16 v[54:57], v[182:185], v[198:201], v[54:57]
	v_mfma_f32_16x16x32_bf16 v[50:53], v[190:193], v[198:201], v[50:53]
	v_mfma_f32_16x16x32_bf16 v[38:41], v[182:185], v[206:209], v[38:41]
	v_mfma_f32_16x16x32_bf16 v[34:37], v[190:193], v[206:209], v[34:37]
	v_mfma_f32_16x16x32_bf16 v[22:25], v[182:185], v[214:217], v[22:25]
	v_mfma_f32_16x16x32_bf16 v[18:21], v[190:193], v[214:217], v[18:21]
	v_mfma_f32_16x16x32_bf16 v[6:9], v[182:185], v[222:225], v[6:9]
	v_mfma_f32_16x16x32_bf16 v[2:5], v[190:193], v[222:225], v[2:5]
	s_add_i32 s71, s71, 2
	s_add_u32 s44, s44, 0x100
	s_addc_u32 s45, s45, 0
	s_add_u32 s69, s69, 0x100
	s_addc_u32 s70, s70, 0
	s_cmp_gt_u32 s71, 13
	s_barrier
	s_cbranch_scc0 .LBB0_2916
	s_and_b64 vcc, exec, s[16:17]
	s_cbranch_vccz .LBB0_2919
	s_barrier

.LBB0_3029:
	ds_read_b128 v[130:133], v168
	ds_read_b128 v[134:137], v168 offset:1024
	ds_read_b128 v[154:157], v168 offset:2048
	ds_read_b128 v[158:161], v168 offset:3072
	ds_read_b128 v[172:175], v169
	ds_read_b128 v[176:179], v169 offset:1024
	ds_read_b128 v[180:183], v169 offset:2048
	ds_read_b128 v[184:187], v169 offset:3072
	s_add_u32 s42, s40, 0xfffc0080
	s_addc_u32 s43, s41, -1
	s_cmp_eq_u32 s59, 12
	s_cselect_b32 s45, s21, s43
	s_cselect_b32 s44, s55, s42
	s_cselect_b32 s43, s19, s58
	s_cselect_b32 s42, s56, s57
	v_lshl_add_u64 v[162:163], s[40:41], 0, v[146:147]
	s_add_i32 m0, s35, 0xc000
	ds_read_b128 v[188:191], v170
	ds_read_b128 v[192:195], v170 offset:1024
	ds_read_b128 v[196:199], v170 offset:2048
	ds_read_b128 v[200:203], v170 offset:3072
	ds_read_b128 v[204:207], v170 offset:4096
	ds_read_b128 v[208:211], v170 offset:5120
	ds_read_b128 v[212:215], v170 offset:6144
	ds_read_b128 v[216:219], v170 offset:7168
	global_load_lds_dwordx4 v[162:163], off
	v_lshl_add_u64 v[162:163], s[40:41], 0, v[148:149]
	s_add_i32 m0, s35, 0xe000
	s_nop 0
	global_load_lds_dwordx4 v[162:163], off
	s_waitcnt vmcnt(8)
	s_waitcnt lgkmcnt(0)
	s_barrier
	s_waitcnt lgkmcnt(0)
	v_mfma_f32_16x16x32_bf16 v[126:129], v[130:133], v[188:191], v[126:129]
	v_mfma_f32_16x16x32_bf16 v[122:125], v[154:157], v[188:191], v[122:125]
	v_mfma_f32_16x16x32_bf16 v[110:113], v[130:133], v[196:199], v[110:113]
	v_mfma_f32_16x16x32_bf16 v[106:109], v[154:157], v[196:199], v[106:109]
	v_mfma_f32_16x16x32_bf16 v[94:97], v[130:133], v[204:207], v[94:97]
	v_mfma_f32_16x16x32_bf16 v[90:93], v[154:157], v[204:207], v[90:93]
	v_mfma_f32_16x16x32_bf16 v[82:85], v[130:133], v[212:215], v[82:85]
	v_mfma_f32_16x16x32_bf16 v[74:77], v[154:157], v[212:215], v[74:77]
	v_mfma_f32_16x16x32_bf16 v[126:129], v[134:137], v[192:195], v[126:129]
	v_mfma_f32_16x16x32_bf16 v[122:125], v[158:161], v[192:195], v[122:125]
	v_mfma_f32_16x16x32_bf16 v[110:113], v[134:137], v[200:203], v[110:113]
	v_mfma_f32_16x16x32_bf16 v[106:109], v[158:161], v[200:203], v[106:109]
	v_mfma_f32_16x16x32_bf16 v[94:97], v[134:137], v[208:211], v[94:97]
	v_mfma_f32_16x16x32_bf16 v[90:93], v[158:161], v[208:211], v[90:93]
	v_mfma_f32_16x16x32_bf16 v[82:85], v[134:137], v[216:219], v[82:85]
	v_mfma_f32_16x16x32_bf16 v[74:77], v[158:161], v[216:219], v[74:77]
	v_mfma_f32_16x16x32_bf16 v[118:121], v[172:175], v[188:191], v[118:121]
	v_mfma_f32_16x16x32_bf16 v[114:117], v[180:183], v[188:191], v[114:117]
	v_mfma_f32_16x16x32_bf16 v[102:105], v[172:175], v[196:199], v[102:105]
	v_mfma_f32_16x16x32_bf16 v[98:101], v[180:183], v[196:199], v[98:101]
	v_mfma_f32_16x16x32_bf16 v[86:89], v[172:175], v[204:207], v[86:89]
	v_mfma_f32_16x16x32_bf16 v[78:81], v[180:183], v[204:207], v[78:81]
	v_mfma_f32_16x16x32_bf16 v[70:73], v[172:175], v[212:215], v[70:73]
	v_mfma_f32_16x16x32_bf16 v[66:69], v[180:183], v[212:215], v[66:69]
	v_mfma_f32_16x16x32_bf16 v[118:121], v[176:179], v[192:195], v[118:121]
	v_mfma_f32_16x16x32_bf16 v[114:117], v[184:187], v[192:195], v[114:117]
	v_mfma_f32_16x16x32_bf16 v[102:105], v[176:179], v[200:203], v[102:105]
	v_mfma_f32_16x16x32_bf16 v[98:101], v[184:187], v[200:203], v[98:101]
	v_mfma_f32_16x16x32_bf16 v[86:89], v[176:179], v[208:211], v[86:89]
	v_mfma_f32_16x16x32_bf16 v[78:81], v[184:187], v[208:211], v[78:81]
	v_mfma_f32_16x16x32_bf16 v[70:73], v[176:179], v[216:219], v[70:73]
	v_mfma_f32_16x16x32_bf16 v[66:69], v[184:187], v[216:219], v[66:69]
	s_barrier
	s_add_i32 s60, s52, s33
	v_lshl_add_u64 v[162:163], s[42:43], 0, v[140:141]
	s_mov_b32 m0, s60
	ds_read_b128 v[188:191], v170 offset:16384
	ds_read_b128 v[192:195], v170 offset:17408
	ds_read_b128 v[196:199], v170 offset:18432
	ds_read_b128 v[200:203], v170 offset:19456
	ds_read_b128 v[204:207], v170 offset:20480
	ds_read_b128 v[208:211], v170 offset:21504
	ds_read_b128 v[212:215], v170 offset:22528
	ds_read_b128 v[216:219], v170 offset:23552
	global_load_lds_dwordx4 v[162:163], off
	s_add_i32 m0, s60, 0x2000
	s_add_u32 s60, s42, 0x40000
	v_lshl_add_u64 v[220:221], s[42:43], 0, v[144:145]
	s_addc_u32 s61, s43, 0
	s_add_i32 s66, s53, s33
	global_load_lds_dwordx4 v[220:221], off
	v_lshl_add_u64 v[222:223], s[60:61], 0, v[140:141]
	s_mov_b32 m0, s66
	v_lshl_add_u64 v[224:225], s[44:45], 0, v[142:143]
	global_load_lds_dwordx4 v[222:223], off
	v_lshl_add_u64 v[222:223], s[60:61], 0, v[144:145]
	s_add_i32 m0, s66, 0x2000
	s_nop 0
	global_load_lds_dwordx4 v[222:223], off
	v_lshl_add_u64 v[222:223], s[44:45], 0, v[138:139]
	s_mov_b32 m0, s35
	s_nop 0
	global_load_lds_dwordx4 v[222:223], off
	s_mov_b32 m0, s39
	s_nop 0
	global_load_lds_dwordx4 v[224:225], off
	s_waitcnt vmcnt(8)
	s_waitcnt lgkmcnt(0)
	s_barrier
	s_waitcnt lgkmcnt(0)
	v_mfma_f32_16x16x32_bf16 v[62:65], v[130:133], v[188:191], v[62:65]
	v_mfma_f32_16x16x32_bf16 v[58:61], v[154:157], v[188:191], v[58:61]
	v_mfma_f32_16x16x32_bf16 v[46:49], v[130:133], v[196:199], v[46:49]
	v_mfma_f32_16x16x32_bf16 v[42:45], v[154:157], v[196:199], v[42:45]
	v_mfma_f32_16x16x32_bf16 v[30:33], v[130:133], v[204:207], v[30:33]
	v_mfma_f32_16x16x32_bf16 v[26:29], v[154:157], v[204:207], v[26:29]
	v_mfma_f32_16x16x32_bf16 v[14:17], v[130:133], v[212:215], v[14:17]
	v_mfma_f32_16x16x32_bf16 v[10:13], v[154:157], v[212:215], v[10:13]
	v_mfma_f32_16x16x32_bf16 v[62:65], v[134:137], v[192:195], v[62:65]
	v_mfma_f32_16x16x32_bf16 v[58:61], v[158:161], v[192:195], v[58:61]
	v_mfma_f32_16x16x32_bf16 v[46:49], v[134:137], v[200:203], v[46:49]
	v_mfma_f32_16x16x32_bf16 v[42:45], v[158:161], v[200:203], v[42:45]
	v_mfma_f32_16x16x32_bf16 v[30:33], v[134:137], v[208:211], v[30:33]
	v_mfma_f32_16x16x32_bf16 v[26:29], v[158:161], v[208:211], v[26:29]
	v_mfma_f32_16x16x32_bf16 v[14:17], v[134:137], v[216:219], v[14:17]
	v_mfma_f32_16x16x32_bf16 v[10:13], v[158:161], v[216:219], v[10:13]
	v_mfma_f32_16x16x32_bf16 v[54:57], v[172:175], v[188:191], v[54:57]
	v_mfma_f32_16x16x32_bf16 v[50:53], v[180:183], v[188:191], v[50:53]
	v_mfma_f32_16x16x32_bf16 v[38:41], v[172:175], v[196:199], v[38:41]
	v_mfma_f32_16x16x32_bf16 v[34:37], v[180:183], v[196:199], v[34:37]
	v_mfma_f32_16x16x32_bf16 v[22:25], v[172:175], v[204:207], v[22:25]
	v_mfma_f32_16x16x32_bf16 v[18:21], v[180:183], v[204:207], v[18:21]
	v_mfma_f32_16x16x32_bf16 v[6:9], v[172:175], v[212:215], v[6:9]
	v_mfma_f32_16x16x32_bf16 v[2:5], v[180:183], v[212:215], v[2:5]
	v_mfma_f32_16x16x32_bf16 v[54:57], v[176:179], v[192:195], v[54:57]
	v_mfma_f32_16x16x32_bf16 v[50:53], v[184:187], v[192:195], v[50:53]
	v_mfma_f32_16x16x32_bf16 v[38:41], v[176:179], v[200:203], v[38:41]
	v_mfma_f32_16x16x32_bf16 v[34:37], v[184:187], v[200:203], v[34:37]
	v_mfma_f32_16x16x32_bf16 v[22:25], v[176:179], v[208:211], v[22:25]
	v_mfma_f32_16x16x32_bf16 v[18:21], v[184:187], v[208:211], v[18:21]
	v_mfma_f32_16x16x32_bf16 v[6:9], v[176:179], v[216:219], v[6:9]
	v_mfma_f32_16x16x32_bf16 v[2:5], v[184:187], v[216:219], v[2:5]
	s_barrier
	s_add_i32 s60, 0, 0x18000
	s_add_i32 s61, 0, 0x1c000
	v_add_u32_e32 v158, s60, v166
	v_add_u32_e32 v171, s61, v166
	ds_read_b128 v[130:133], v158
	ds_read_b128 v[134:137], v158 offset:1024
	ds_read_b128 v[154:157], v158 offset:2048
	ds_read_b128 v[158:161], v158 offset:3072
	ds_read_b128 v[172:175], v171
	ds_read_b128 v[176:179], v171 offset:1024
	ds_read_b128 v[180:183], v171 offset:2048
	ds_read_b128 v[184:187], v171 offset:3072
	s_add_u32 s44, s44, 0x40000
	s_addc_u32 s45, s45, 0
	s_mov_b32 m0, s46
	v_lshl_add_u64 v[226:227], s[44:45], 0, v[138:139]
	ds_read_b128 v[188:191], v170 offset:32768
	ds_read_b128 v[192:195], v170 offset:33792
	ds_read_b128 v[196:199], v170 offset:34816
	ds_read_b128 v[200:203], v170 offset:35840
	ds_read_b128 v[204:207], v170 offset:36864
	ds_read_b128 v[208:211], v170 offset:37888
	ds_read_b128 v[212:215], v170 offset:38912
	ds_read_b128 v[216:219], v170 offset:39936
	global_load_lds_dwordx4 v[226:227], off
	v_lshl_add_u64 v[226:227], s[44:45], 0, v[142:143]
	s_mov_b32 m0, s47
	s_nop 0
	global_load_lds_dwordx4 v[226:227], off
	s_waitcnt vmcnt(8)
	s_waitcnt lgkmcnt(0)
	s_barrier
	s_waitcnt lgkmcnt(0)
	v_mfma_f32_16x16x32_bf16 v[126:129], v[130:133], v[188:191], v[126:129]
	v_mfma_f32_16x16x32_bf16 v[122:125], v[154:157], v[188:191], v[122:125]
	v_mfma_f32_16x16x32_bf16 v[110:113], v[130:133], v[196:199], v[110:113]
	v_mfma_f32_16x16x32_bf16 v[106:109], v[154:157], v[196:199], v[106:109]
	v_mfma_f32_16x16x32_bf16 v[94:97], v[130:133], v[204:207], v[94:97]
	v_mfma_f32_16x16x32_bf16 v[90:93], v[154:157], v[204:207], v[90:93]
	v_mfma_f32_16x16x32_bf16 v[82:85], v[130:133], v[212:215], v[82:85]
	v_mfma_f32_16x16x32_bf16 v[74:77], v[154:157], v[212:215], v[74:77]
	v_mfma_f32_16x16x32_bf16 v[126:129], v[134:137], v[192:195], v[126:129]
	v_mfma_f32_16x16x32_bf16 v[122:125], v[158:161], v[192:195], v[122:125]
	v_mfma_f32_16x16x32_bf16 v[110:113], v[134:137], v[200:203], v[110:113]
	v_mfma_f32_16x16x32_bf16 v[106:109], v[158:161], v[200:203], v[106:109]
	v_mfma_f32_16x16x32_bf16 v[94:97], v[134:137], v[208:211], v[94:97]
	v_mfma_f32_16x16x32_bf16 v[90:93], v[158:161], v[208:211], v[90:93]
	v_mfma_f32_16x16x32_bf16 v[82:85], v[134:137], v[216:219], v[82:85]
	v_mfma_f32_16x16x32_bf16 v[74:77], v[158:161], v[216:219], v[74:77]
	v_mfma_f32_16x16x32_bf16 v[118:121], v[172:175], v[188:191], v[118:121]
	v_mfma_f32_16x16x32_bf16 v[114:117], v[180:183], v[188:191], v[114:117]
	v_mfma_f32_16x16x32_bf16 v[102:105], v[172:175], v[196:199], v[102:105]
	v_mfma_f32_16x16x32_bf16 v[98:101], v[180:183], v[196:199], v[98:101]
	v_mfma_f32_16x16x32_bf16 v[86:89], v[172:175], v[204:207], v[86:89]
	v_mfma_f32_16x16x32_bf16 v[78:81], v[180:183], v[204:207], v[78:81]
	v_mfma_f32_16x16x32_bf16 v[70:73], v[172:175], v[212:215], v[70:73]
	v_mfma_f32_16x16x32_bf16 v[66:69], v[180:183], v[212:215], v[66:69]
	v_mfma_f32_16x16x32_bf16 v[118:121], v[176:179], v[192:195], v[118:121]
	v_mfma_f32_16x16x32_bf16 v[114:117], v[184:187], v[192:195], v[114:117]
	v_mfma_f32_16x16x32_bf16 v[102:105], v[176:179], v[200:203], v[102:105]
	v_mfma_f32_16x16x32_bf16 v[98:101], v[184:187], v[200:203], v[98:101]
	v_mfma_f32_16x16x32_bf16 v[86:89], v[176:179], v[208:211], v[86:89]
	v_mfma_f32_16x16x32_bf16 v[78:81], v[184:187], v[208:211], v[78:81]
	v_mfma_f32_16x16x32_bf16 v[70:73], v[176:179], v[216:219], v[70:73]
	v_mfma_f32_16x16x32_bf16 v[66:69], v[184:187], v[216:219], v[66:69]
	s_barrier
	s_add_i32 s44, s60, s33
	v_lshl_add_u64 v[162:163], v[162:163], 0, s[12:13]
	s_mov_b32 m0, s44
	ds_read_b128 v[188:191], v170 offset:49152
	ds_read_b128 v[192:195], v170 offset:50176
	ds_read_b128 v[196:199], v170 offset:51200
	ds_read_b128 v[200:203], v170 offset:52224
	ds_read_b128 v[204:207], v170 offset:53248
	ds_read_b128 v[208:211], v170 offset:54272
	ds_read_b128 v[212:215], v170 offset:55296
	ds_read_b128 v[216:219], v170 offset:56320
	global_load_lds_dwordx4 v[162:163], off
	s_add_i32 m0, s44, 0x2000
	s_add_u32 s42, s42, 0x40080
	v_lshl_add_u64 v[162:163], v[220:221], 0, s[12:13]
	s_addc_u32 s43, s43, 0
	s_add_i32 s44, s61, s33
	global_load_lds_dwordx4 v[162:163], off
	v_lshl_add_u64 v[162:163], s[42:43], 0, v[140:141]
	s_mov_b32 m0, s44
	s_nop 0
	global_load_lds_dwordx4 v[162:163], off
	v_lshl_add_u64 v[162:163], s[42:43], 0, v[144:145]
	s_add_i32 m0, s44, 0x2000
	s_nop 0
	global_load_lds_dwordx4 v[162:163], off
	v_lshl_add_u64 v[162:163], v[222:223], 0, s[12:13]
	s_mov_b32 m0, s49
	s_nop 0
	global_load_lds_dwordx4 v[162:163], off
	v_lshl_add_u64 v[162:163], v[224:225], 0, s[12:13]
	s_mov_b32 m0, s50
	s_nop 0
	global_load_lds_dwordx4 v[162:163], off
	s_waitcnt vmcnt(8)
	s_waitcnt lgkmcnt(0)
	s_barrier
	s_waitcnt lgkmcnt(0)
	v_mfma_f32_16x16x32_bf16 v[62:65], v[130:133], v[188:191], v[62:65]
	v_mfma_f32_16x16x32_bf16 v[58:61], v[154:157], v[188:191], v[58:61]
	v_mfma_f32_16x16x32_bf16 v[46:49], v[130:133], v[196:199], v[46:49]
	v_mfma_f32_16x16x32_bf16 v[42:45], v[154:157], v[196:199], v[42:45]
	v_mfma_f32_16x16x32_bf16 v[30:33], v[130:133], v[204:207], v[30:33]
	v_mfma_f32_16x16x32_bf16 v[26:29], v[154:157], v[204:207], v[26:29]
	v_mfma_f32_16x16x32_bf16 v[14:17], v[130:133], v[212:215], v[14:17]
	v_mfma_f32_16x16x32_bf16 v[10:13], v[154:157], v[212:215], v[10:13]
	v_mfma_f32_16x16x32_bf16 v[62:65], v[134:137], v[192:195], v[62:65]
	v_mfma_f32_16x16x32_bf16 v[58:61], v[158:161], v[192:195], v[58:61]
	v_mfma_f32_16x16x32_bf16 v[46:49], v[134:137], v[200:203], v[46:49]
	v_mfma_f32_16x16x32_bf16 v[42:45], v[158:161], v[200:203], v[42:45]
	v_mfma_f32_16x16x32_bf16 v[30:33], v[134:137], v[208:211], v[30:33]
	v_mfma_f32_16x16x32_bf16 v[26:29], v[158:161], v[208:211], v[26:29]
	v_mfma_f32_16x16x32_bf16 v[14:17], v[134:137], v[216:219], v[14:17]
	v_mfma_f32_16x16x32_bf16 v[10:13], v[158:161], v[216:219], v[10:13]
	v_mfma_f32_16x16x32_bf16 v[54:57], v[172:175], v[188:191], v[54:57]
	v_mfma_f32_16x16x32_bf16 v[50:53], v[180:183], v[188:191], v[50:53]
	v_mfma_f32_16x16x32_bf16 v[38:41], v[172:175], v[196:199], v[38:41]
	v_mfma_f32_16x16x32_bf16 v[34:37], v[180:183], v[196:199], v[34:37]
	v_mfma_f32_16x16x32_bf16 v[22:25], v[172:175], v[204:207], v[22:25]
	v_mfma_f32_16x16x32_bf16 v[18:21], v[180:183], v[204:207], v[18:21]
	v_mfma_f32_16x16x32_bf16 v[6:9], v[172:175], v[212:215], v[6:9]
	v_mfma_f32_16x16x32_bf16 v[2:5], v[180:183], v[212:215], v[2:5]
	v_mfma_f32_16x16x32_bf16 v[54:57], v[176:179], v[192:195], v[54:57]
	v_mfma_f32_16x16x32_bf16 v[50:53], v[184:187], v[192:195], v[50:53]
	v_mfma_f32_16x16x32_bf16 v[38:41], v[176:179], v[200:203], v[38:41]
	v_mfma_f32_16x16x32_bf16 v[34:37], v[184:187], v[200:203], v[34:37]
	v_mfma_f32_16x16x32_bf16 v[22:25], v[176:179], v[208:211], v[22:25]
	v_mfma_f32_16x16x32_bf16 v[18:21], v[184:187], v[208:211], v[18:21]
	v_mfma_f32_16x16x32_bf16 v[6:9], v[176:179], v[216:219], v[6:9]
	v_mfma_f32_16x16x32_bf16 v[2:5], v[184:187], v[216:219], v[2:5]
	s_add_i32 s59, s59, 2
	s_add_u32 s40, s40, 0x100
	s_addc_u32 s41, s41, 0
	s_add_u32 s57, s57, 0x100
	s_addc_u32 s58, s58, 0
	s_cmp_gt_u32 s59, 13
	s_barrier
	s_cbranch_scc0 .LBB0_3029
	s_and_b64 vcc, exec, s[16:17]
	s_cbranch_vccz .LBB0_3032
	s_barrier

.LBB0_3131:
	ds_read_b128 v[130:133], v172
	ds_read_b128 v[134:137], v172 offset:1024
	ds_read_b128 v[156:159], v172 offset:2048
	ds_read_b128 v[176:179], v172 offset:3072
	ds_read_b128 v[180:183], v173
	ds_read_b128 v[184:187], v173 offset:1024
	ds_read_b128 v[188:191], v173 offset:2048
	ds_read_b128 v[192:195], v173 offset:3072
	s_add_u32 s46, s44, 0xfffc0080
	s_addc_u32 s47, s45, -1
	s_cmp_eq_u32 s71, 12
	s_cselect_b32 s49, s37, s47
	s_cselect_b32 s48, s43, s46
	s_cselect_b32 s47, s23, s70
	s_cselect_b32 s46, s68, s69
	v_lshl_add_u64 v[138:139], s[44:45], 0, v[148:149]
	s_add_i32 m0, s33, 0xc000
	ds_read_b128 v[196:199], v174
	ds_read_b128 v[200:203], v174 offset:1024
	ds_read_b128 v[204:207], v174 offset:2048
	ds_read_b128 v[208:211], v174 offset:3072
	ds_read_b128 v[212:215], v174 offset:4096
	ds_read_b128 v[216:219], v174 offset:5120
	ds_read_b128 v[220:223], v174 offset:6144
	ds_read_b128 v[224:227], v174 offset:7168
	global_load_lds_dwordx4 v[138:139], off
	v_lshl_add_u64 v[138:139], s[44:45], 0, v[150:151]
	s_add_i32 m0, s33, 0xe000
	s_nop 0
	global_load_lds_dwordx4 v[138:139], off
	s_waitcnt vmcnt(8)
	s_waitcnt lgkmcnt(0)
	s_barrier
	s_waitcnt lgkmcnt(0)
	v_mfma_f32_16x16x32_bf16 v[126:129], v[130:133], v[196:199], v[126:129]
	v_mfma_f32_16x16x32_bf16 v[122:125], v[156:159], v[196:199], v[122:125]
	v_mfma_f32_16x16x32_bf16 v[110:113], v[130:133], v[204:207], v[110:113]
	v_mfma_f32_16x16x32_bf16 v[106:109], v[156:159], v[204:207], v[106:109]
	v_mfma_f32_16x16x32_bf16 v[94:97], v[130:133], v[212:215], v[94:97]
	v_mfma_f32_16x16x32_bf16 v[90:93], v[156:159], v[212:215], v[90:93]
	v_mfma_f32_16x16x32_bf16 v[78:81], v[130:133], v[220:223], v[78:81]
	v_mfma_f32_16x16x32_bf16 v[74:77], v[156:159], v[220:223], v[74:77]
	v_mfma_f32_16x16x32_bf16 v[126:129], v[134:137], v[200:203], v[126:129]
	v_mfma_f32_16x16x32_bf16 v[122:125], v[176:179], v[200:203], v[122:125]
	v_mfma_f32_16x16x32_bf16 v[110:113], v[134:137], v[208:211], v[110:113]
	v_mfma_f32_16x16x32_bf16 v[106:109], v[176:179], v[208:211], v[106:109]
	v_mfma_f32_16x16x32_bf16 v[94:97], v[134:137], v[216:219], v[94:97]
	v_mfma_f32_16x16x32_bf16 v[90:93], v[176:179], v[216:219], v[90:93]
	v_mfma_f32_16x16x32_bf16 v[78:81], v[134:137], v[224:227], v[78:81]
	v_mfma_f32_16x16x32_bf16 v[74:77], v[176:179], v[224:227], v[74:77]
	v_mfma_f32_16x16x32_bf16 v[118:121], v[180:183], v[196:199], v[118:121]
	v_mfma_f32_16x16x32_bf16 v[114:117], v[188:191], v[196:199], v[114:117]
	v_mfma_f32_16x16x32_bf16 v[102:105], v[180:183], v[204:207], v[102:105]
	v_mfma_f32_16x16x32_bf16 v[98:101], v[188:191], v[204:207], v[98:101]
	v_mfma_f32_16x16x32_bf16 v[86:89], v[180:183], v[212:215], v[86:89]
	v_mfma_f32_16x16x32_bf16 v[82:85], v[188:191], v[212:215], v[82:85]
	v_mfma_f32_16x16x32_bf16 v[70:73], v[180:183], v[220:223], v[70:73]
	v_mfma_f32_16x16x32_bf16 v[66:69], v[188:191], v[220:223], v[66:69]
	v_mfma_f32_16x16x32_bf16 v[118:121], v[184:187], v[200:203], v[118:121]
	v_mfma_f32_16x16x32_bf16 v[114:117], v[192:195], v[200:203], v[114:117]
	v_mfma_f32_16x16x32_bf16 v[102:105], v[184:187], v[208:211], v[102:105]
	v_mfma_f32_16x16x32_bf16 v[98:101], v[192:195], v[208:211], v[98:101]
	v_mfma_f32_16x16x32_bf16 v[86:89], v[184:187], v[216:219], v[86:89]
	v_mfma_f32_16x16x32_bf16 v[82:85], v[192:195], v[216:219], v[82:85]
	v_mfma_f32_16x16x32_bf16 v[70:73], v[184:187], v[224:227], v[70:73]
	v_mfma_f32_16x16x32_bf16 v[66:69], v[192:195], v[224:227], v[66:69]
	s_barrier
	s_add_i32 s72, s60, s3
	v_lshl_add_u64 v[138:139], s[46:47], 0, v[142:143]
	s_mov_b32 m0, s72
	ds_read_b128 v[196:199], v174 offset:16384
	ds_read_b128 v[200:203], v174 offset:17408
	ds_read_b128 v[204:207], v174 offset:18432
	ds_read_b128 v[208:211], v174 offset:19456
	ds_read_b128 v[212:215], v174 offset:20480
	ds_read_b128 v[216:219], v174 offset:21504
	ds_read_b128 v[220:223], v174 offset:22528
	ds_read_b128 v[224:227], v174 offset:23552
	global_load_lds_dwordx4 v[138:139], off
	s_add_i32 m0, s72, 0x2000
	s_add_u32 s72, s46, 0x40000
	v_lshl_add_u64 v[160:161], s[46:47], 0, v[146:147]
	s_addc_u32 s73, s47, 0
	s_add_i32 s74, s61, s3
	global_load_lds_dwordx4 v[160:161], off
	v_lshl_add_u64 v[228:229], s[72:73], 0, v[142:143]
	s_mov_b32 m0, s74
	v_lshl_add_u64 v[230:231], s[48:49], 0, v[144:145]
	global_load_lds_dwordx4 v[228:229], off
	v_lshl_add_u64 v[228:229], s[72:73], 0, v[146:147]
	s_add_i32 m0, s74, 0x2000
	s_nop 0
	global_load_lds_dwordx4 v[228:229], off
	v_lshl_add_u64 v[228:229], s[48:49], 0, v[140:141]
	s_mov_b32 m0, s33
	s_nop 0
	global_load_lds_dwordx4 v[228:229], off
	s_mov_b32 m0, s35
	s_nop 0
	global_load_lds_dwordx4 v[230:231], off
	s_waitcnt vmcnt(8)
	s_waitcnt lgkmcnt(0)
	s_barrier
	s_waitcnt lgkmcnt(0)
	v_mfma_f32_16x16x32_bf16 v[62:65], v[130:133], v[196:199], v[62:65]
	v_mfma_f32_16x16x32_bf16 v[58:61], v[156:159], v[196:199], v[58:61]
	v_mfma_f32_16x16x32_bf16 v[46:49], v[130:133], v[204:207], v[46:49]
	v_mfma_f32_16x16x32_bf16 v[42:45], v[156:159], v[204:207], v[42:45]
	v_mfma_f32_16x16x32_bf16 v[30:33], v[130:133], v[212:215], v[30:33]
	v_mfma_f32_16x16x32_bf16 v[26:29], v[156:159], v[212:215], v[26:29]
	v_mfma_f32_16x16x32_bf16 v[14:17], v[130:133], v[220:223], v[14:17]
	v_mfma_f32_16x16x32_bf16 v[10:13], v[156:159], v[220:223], v[10:13]
	v_mfma_f32_16x16x32_bf16 v[62:65], v[134:137], v[200:203], v[62:65]
	v_mfma_f32_16x16x32_bf16 v[58:61], v[176:179], v[200:203], v[58:61]
	v_mfma_f32_16x16x32_bf16 v[46:49], v[134:137], v[208:211], v[46:49]
	v_mfma_f32_16x16x32_bf16 v[42:45], v[176:179], v[208:211], v[42:45]
	v_mfma_f32_16x16x32_bf16 v[30:33], v[134:137], v[216:219], v[30:33]
	v_mfma_f32_16x16x32_bf16 v[26:29], v[176:179], v[216:219], v[26:29]
	v_mfma_f32_16x16x32_bf16 v[14:17], v[134:137], v[224:227], v[14:17]
	v_mfma_f32_16x16x32_bf16 v[10:13], v[176:179], v[224:227], v[10:13]
	v_mfma_f32_16x16x32_bf16 v[54:57], v[180:183], v[196:199], v[54:57]
	v_mfma_f32_16x16x32_bf16 v[50:53], v[188:191], v[196:199], v[50:53]
	v_mfma_f32_16x16x32_bf16 v[38:41], v[180:183], v[204:207], v[38:41]
	v_mfma_f32_16x16x32_bf16 v[34:37], v[188:191], v[204:207], v[34:37]
	v_mfma_f32_16x16x32_bf16 v[22:25], v[180:183], v[212:215], v[22:25]
	v_mfma_f32_16x16x32_bf16 v[18:21], v[188:191], v[212:215], v[18:21]
	v_mfma_f32_16x16x32_bf16 v[6:9], v[180:183], v[220:223], v[6:9]
	v_mfma_f32_16x16x32_bf16 v[2:5], v[188:191], v[220:223], v[2:5]
	v_mfma_f32_16x16x32_bf16 v[54:57], v[184:187], v[200:203], v[54:57]
	v_mfma_f32_16x16x32_bf16 v[50:53], v[192:195], v[200:203], v[50:53]
	v_mfma_f32_16x16x32_bf16 v[38:41], v[184:187], v[208:211], v[38:41]
	v_mfma_f32_16x16x32_bf16 v[34:37], v[192:195], v[208:211], v[34:37]
	v_mfma_f32_16x16x32_bf16 v[22:25], v[184:187], v[216:219], v[22:25]
	v_mfma_f32_16x16x32_bf16 v[18:21], v[192:195], v[216:219], v[18:21]
	v_mfma_f32_16x16x32_bf16 v[6:9], v[184:187], v[224:227], v[6:9]
	v_mfma_f32_16x16x32_bf16 v[2:5], v[192:195], v[224:227], v[2:5]
	s_barrier
	s_add_i32 s72, 0, 0x18000
	s_add_i32 s73, 0, 0x1c000
	v_add_u32_e32 v176, s72, v166
	v_add_u32_e32 v192, s73, v166
	ds_read_b128 v[130:133], v176
	ds_read_b128 v[134:137], v176 offset:1024
	ds_read_b128 v[156:159], v176 offset:2048
	ds_read_b128 v[176:179], v176 offset:3072
	ds_read_b128 v[180:183], v192
	ds_read_b128 v[184:187], v192 offset:1024
	ds_read_b128 v[188:191], v192 offset:2048
	ds_read_b128 v[192:195], v192 offset:3072
	s_add_u32 s48, s48, 0x40000
	s_addc_u32 s49, s49, 0
	s_mov_b32 m0, s50
	v_lshl_add_u64 v[232:233], s[48:49], 0, v[140:141]
	ds_read_b128 v[196:199], v174 offset:32768
	ds_read_b128 v[200:203], v174 offset:33792
	ds_read_b128 v[204:207], v174 offset:34816
	ds_read_b128 v[208:211], v174 offset:35840
	ds_read_b128 v[212:215], v174 offset:36864
	ds_read_b128 v[216:219], v174 offset:37888
	ds_read_b128 v[220:223], v174 offset:38912
	ds_read_b128 v[224:227], v174 offset:39936
	global_load_lds_dwordx4 v[232:233], off
	v_lshl_add_u64 v[232:233], s[48:49], 0, v[144:145]
	s_mov_b32 m0, s51
	s_nop 0
	global_load_lds_dwordx4 v[232:233], off
	s_waitcnt vmcnt(8)
	s_waitcnt lgkmcnt(0)
	s_barrier
	s_waitcnt lgkmcnt(0)
	v_mfma_f32_16x16x32_bf16 v[126:129], v[130:133], v[196:199], v[126:129]
	v_mfma_f32_16x16x32_bf16 v[122:125], v[156:159], v[196:199], v[122:125]
	v_mfma_f32_16x16x32_bf16 v[110:113], v[130:133], v[204:207], v[110:113]
	v_mfma_f32_16x16x32_bf16 v[106:109], v[156:159], v[204:207], v[106:109]
	v_mfma_f32_16x16x32_bf16 v[94:97], v[130:133], v[212:215], v[94:97]
	v_mfma_f32_16x16x32_bf16 v[90:93], v[156:159], v[212:215], v[90:93]
	v_mfma_f32_16x16x32_bf16 v[78:81], v[130:133], v[220:223], v[78:81]
	v_mfma_f32_16x16x32_bf16 v[74:77], v[156:159], v[220:223], v[74:77]
	v_mfma_f32_16x16x32_bf16 v[126:129], v[134:137], v[200:203], v[126:129]
	v_mfma_f32_16x16x32_bf16 v[122:125], v[176:179], v[200:203], v[122:125]
	v_mfma_f32_16x16x32_bf16 v[110:113], v[134:137], v[208:211], v[110:113]
	v_mfma_f32_16x16x32_bf16 v[106:109], v[176:179], v[208:211], v[106:109]
	v_mfma_f32_16x16x32_bf16 v[94:97], v[134:137], v[216:219], v[94:97]
	v_mfma_f32_16x16x32_bf16 v[90:93], v[176:179], v[216:219], v[90:93]
	v_mfma_f32_16x16x32_bf16 v[78:81], v[134:137], v[224:227], v[78:81]
	v_mfma_f32_16x16x32_bf16 v[74:77], v[176:179], v[224:227], v[74:77]
	v_mfma_f32_16x16x32_bf16 v[118:121], v[180:183], v[196:199], v[118:121]
	v_mfma_f32_16x16x32_bf16 v[114:117], v[188:191], v[196:199], v[114:117]
	v_mfma_f32_16x16x32_bf16 v[102:105], v[180:183], v[204:207], v[102:105]
	v_mfma_f32_16x16x32_bf16 v[98:101], v[188:191], v[204:207], v[98:101]
	v_mfma_f32_16x16x32_bf16 v[86:89], v[180:183], v[212:215], v[86:89]
	v_mfma_f32_16x16x32_bf16 v[82:85], v[188:191], v[212:215], v[82:85]
	v_mfma_f32_16x16x32_bf16 v[70:73], v[180:183], v[220:223], v[70:73]
	v_mfma_f32_16x16x32_bf16 v[66:69], v[188:191], v[220:223], v[66:69]
	v_mfma_f32_16x16x32_bf16 v[118:121], v[184:187], v[200:203], v[118:121]
	v_mfma_f32_16x16x32_bf16 v[114:117], v[192:195], v[200:203], v[114:117]
	v_mfma_f32_16x16x32_bf16 v[102:105], v[184:187], v[208:211], v[102:105]
	v_mfma_f32_16x16x32_bf16 v[98:101], v[192:195], v[208:211], v[98:101]
	v_mfma_f32_16x16x32_bf16 v[86:89], v[184:187], v[216:219], v[86:89]
	v_mfma_f32_16x16x32_bf16 v[82:85], v[192:195], v[216:219], v[82:85]
	v_mfma_f32_16x16x32_bf16 v[70:73], v[184:187], v[224:227], v[70:73]
	v_mfma_f32_16x16x32_bf16 v[66:69], v[192:195], v[224:227], v[66:69]
	s_barrier
	s_add_i32 s48, s72, s3
	v_lshl_add_u64 v[138:139], v[138:139], 0, s[18:19]
	s_mov_b32 m0, s48
	ds_read_b128 v[196:199], v174 offset:49152
	ds_read_b128 v[200:203], v174 offset:50176
	ds_read_b128 v[204:207], v174 offset:51200
	ds_read_b128 v[208:211], v174 offset:52224
	ds_read_b128 v[212:215], v174 offset:53248
	ds_read_b128 v[216:219], v174 offset:54272
	ds_read_b128 v[220:223], v174 offset:55296
	ds_read_b128 v[224:227], v174 offset:56320
	global_load_lds_dwordx4 v[138:139], off
	s_add_i32 m0, s48, 0x2000
	s_add_u32 s46, s46, 0x40080
	v_lshl_add_u64 v[138:139], v[160:161], 0, s[18:19]
	s_addc_u32 s47, s47, 0
	s_add_i32 s48, s73, s3
	global_load_lds_dwordx4 v[138:139], off
	v_lshl_add_u64 v[138:139], s[46:47], 0, v[142:143]
	s_mov_b32 m0, s48
	s_nop 0
	global_load_lds_dwordx4 v[138:139], off
	v_lshl_add_u64 v[138:139], s[46:47], 0, v[146:147]
	s_add_i32 m0, s48, 0x2000
	s_nop 0
	global_load_lds_dwordx4 v[138:139], off
	v_lshl_add_u64 v[138:139], v[228:229], 0, s[18:19]
	s_mov_b32 m0, s54
	s_nop 0
	global_load_lds_dwordx4 v[138:139], off
	v_lshl_add_u64 v[138:139], v[230:231], 0, s[18:19]
	s_mov_b32 m0, s55
	s_nop 0
	global_load_lds_dwordx4 v[138:139], off
	s_waitcnt vmcnt(8)
	s_waitcnt lgkmcnt(0)
	s_barrier
	s_waitcnt lgkmcnt(0)
	v_mfma_f32_16x16x32_bf16 v[62:65], v[130:133], v[196:199], v[62:65]
	v_mfma_f32_16x16x32_bf16 v[58:61], v[156:159], v[196:199], v[58:61]
	v_mfma_f32_16x16x32_bf16 v[46:49], v[130:133], v[204:207], v[46:49]
	v_mfma_f32_16x16x32_bf16 v[42:45], v[156:159], v[204:207], v[42:45]
	v_mfma_f32_16x16x32_bf16 v[30:33], v[130:133], v[212:215], v[30:33]
	v_mfma_f32_16x16x32_bf16 v[26:29], v[156:159], v[212:215], v[26:29]
	v_mfma_f32_16x16x32_bf16 v[14:17], v[130:133], v[220:223], v[14:17]
	v_mfma_f32_16x16x32_bf16 v[10:13], v[156:159], v[220:223], v[10:13]
	v_mfma_f32_16x16x32_bf16 v[62:65], v[134:137], v[200:203], v[62:65]
	v_mfma_f32_16x16x32_bf16 v[58:61], v[176:179], v[200:203], v[58:61]
	v_mfma_f32_16x16x32_bf16 v[46:49], v[134:137], v[208:211], v[46:49]
	v_mfma_f32_16x16x32_bf16 v[42:45], v[176:179], v[208:211], v[42:45]
	v_mfma_f32_16x16x32_bf16 v[30:33], v[134:137], v[216:219], v[30:33]
	v_mfma_f32_16x16x32_bf16 v[26:29], v[176:179], v[216:219], v[26:29]
	v_mfma_f32_16x16x32_bf16 v[14:17], v[134:137], v[224:227], v[14:17]
	v_mfma_f32_16x16x32_bf16 v[10:13], v[176:179], v[224:227], v[10:13]
	v_mfma_f32_16x16x32_bf16 v[54:57], v[180:183], v[196:199], v[54:57]
	v_mfma_f32_16x16x32_bf16 v[50:53], v[188:191], v[196:199], v[50:53]
	v_mfma_f32_16x16x32_bf16 v[38:41], v[180:183], v[204:207], v[38:41]
	v_mfma_f32_16x16x32_bf16 v[34:37], v[188:191], v[204:207], v[34:37]
	v_mfma_f32_16x16x32_bf16 v[22:25], v[180:183], v[212:215], v[22:25]
	v_mfma_f32_16x16x32_bf16 v[18:21], v[188:191], v[212:215], v[18:21]
	v_mfma_f32_16x16x32_bf16 v[6:9], v[180:183], v[220:223], v[6:9]
	v_mfma_f32_16x16x32_bf16 v[2:5], v[188:191], v[220:223], v[2:5]
	v_mfma_f32_16x16x32_bf16 v[54:57], v[184:187], v[200:203], v[54:57]
	v_mfma_f32_16x16x32_bf16 v[50:53], v[192:195], v[200:203], v[50:53]
	v_mfma_f32_16x16x32_bf16 v[38:41], v[184:187], v[208:211], v[38:41]
	v_mfma_f32_16x16x32_bf16 v[34:37], v[192:195], v[208:211], v[34:37]
	v_mfma_f32_16x16x32_bf16 v[22:25], v[184:187], v[216:219], v[22:25]
	v_mfma_f32_16x16x32_bf16 v[18:21], v[192:195], v[216:219], v[18:21]
	v_mfma_f32_16x16x32_bf16 v[6:9], v[184:187], v[224:227], v[6:9]
	v_mfma_f32_16x16x32_bf16 v[2:5], v[192:195], v[224:227], v[2:5]
	s_add_i32 s71, s71, 2
	s_add_u32 s44, s44, 0x100
	s_addc_u32 s45, s45, 0
	s_add_u32 s69, s69, 0x100
	s_addc_u32 s70, s70, 0
	s_cmp_gt_u32 s71, 13
	s_barrier
	s_cbranch_scc0 .LBB0_3131
	s_and_b64 vcc, exec, s[20:21]
	s_cbranch_vccz .LBB0_3134
	s_barrier

.LBB0_3293:
	ds_read_b128 v[148:151], v156
	ds_read_b128 v[162:165], v156 offset:1024
	ds_read_b128 v[166:169], v156 offset:2048
	ds_read_b128 v[170:173], v156 offset:3072
	ds_read_b128 v[174:177], v157
	ds_read_b128 v[178:181], v157 offset:1024
	ds_read_b128 v[182:185], v157 offset:2048
	ds_read_b128 v[186:189], v157 offset:3072
	s_add_u32 s36, s22, 0xfffc0080
	s_addc_u32 s37, s23, -1
	s_cmp_eq_u32 s57, 12
	s_cselect_b32 s39, s17, s37
	s_cselect_b32 s38, s53, s36
	s_cselect_b32 s37, s13, s56
	s_cselect_b32 s36, s54, s55
	v_lshl_add_u64 v[152:153], s[22:23], 0, v[140:141]
	s_add_i32 m0, s41, 0xc000
	ds_read_b128 v[190:193], v158
	ds_read_b128 v[194:197], v158 offset:1024
	ds_read_b128 v[198:201], v158 offset:2048
	ds_read_b128 v[202:205], v158 offset:3072
	ds_read_b128 v[206:209], v158 offset:4096
	ds_read_b128 v[210:213], v158 offset:5120
	ds_read_b128 v[214:217], v158 offset:6144
	ds_read_b128 v[218:221], v158 offset:7168
	global_load_lds_dwordx4 v[152:153], off
	v_lshl_add_u64 v[152:153], s[22:23], 0, v[142:143]
	s_add_i32 m0, s41, 0xe000
	s_nop 0
	global_load_lds_dwordx4 v[152:153], off
	s_waitcnt vmcnt(8)
	s_waitcnt lgkmcnt(0)
	s_barrier
	s_waitcnt lgkmcnt(0)
	v_mfma_f32_16x16x32_bf16 v[126:129], v[148:151], v[190:193], v[126:129]
	v_mfma_f32_16x16x32_bf16 v[122:125], v[166:169], v[190:193], v[122:125]
	v_mfma_f32_16x16x32_bf16 v[110:113], v[148:151], v[198:201], v[110:113]
	v_mfma_f32_16x16x32_bf16 v[106:109], v[166:169], v[198:201], v[106:109]
	v_mfma_f32_16x16x32_bf16 v[94:97], v[148:151], v[206:209], v[94:97]
	v_mfma_f32_16x16x32_bf16 v[90:93], v[166:169], v[206:209], v[90:93]
	v_mfma_f32_16x16x32_bf16 v[78:81], v[148:151], v[214:217], v[78:81]
	v_mfma_f32_16x16x32_bf16 v[74:77], v[166:169], v[214:217], v[74:77]
	v_mfma_f32_16x16x32_bf16 v[126:129], v[162:165], v[194:197], v[126:129]
	v_mfma_f32_16x16x32_bf16 v[122:125], v[170:173], v[194:197], v[122:125]
	v_mfma_f32_16x16x32_bf16 v[110:113], v[162:165], v[202:205], v[110:113]
	v_mfma_f32_16x16x32_bf16 v[106:109], v[170:173], v[202:205], v[106:109]
	v_mfma_f32_16x16x32_bf16 v[94:97], v[162:165], v[210:213], v[94:97]
	v_mfma_f32_16x16x32_bf16 v[90:93], v[170:173], v[210:213], v[90:93]
	v_mfma_f32_16x16x32_bf16 v[78:81], v[162:165], v[218:221], v[78:81]
	v_mfma_f32_16x16x32_bf16 v[74:77], v[170:173], v[218:221], v[74:77]
	v_mfma_f32_16x16x32_bf16 v[118:121], v[174:177], v[190:193], v[118:121]
	v_mfma_f32_16x16x32_bf16 v[114:117], v[182:185], v[190:193], v[114:117]
	v_mfma_f32_16x16x32_bf16 v[102:105], v[174:177], v[198:201], v[102:105]
	v_mfma_f32_16x16x32_bf16 v[98:101], v[182:185], v[198:201], v[98:101]
	v_mfma_f32_16x16x32_bf16 v[86:89], v[174:177], v[206:209], v[86:89]
	v_mfma_f32_16x16x32_bf16 v[82:85], v[182:185], v[206:209], v[82:85]
	v_mfma_f32_16x16x32_bf16 v[70:73], v[174:177], v[214:217], v[70:73]
	v_mfma_f32_16x16x32_bf16 v[66:69], v[182:185], v[214:217], v[66:69]
	v_mfma_f32_16x16x32_bf16 v[118:121], v[178:181], v[194:197], v[118:121]
	v_mfma_f32_16x16x32_bf16 v[114:117], v[186:189], v[194:197], v[114:117]
	v_mfma_f32_16x16x32_bf16 v[102:105], v[178:181], v[202:205], v[102:105]
	v_mfma_f32_16x16x32_bf16 v[98:101], v[186:189], v[202:205], v[98:101]
	v_mfma_f32_16x16x32_bf16 v[86:89], v[178:181], v[210:213], v[86:89]
	v_mfma_f32_16x16x32_bf16 v[82:85], v[186:189], v[210:213], v[82:85]
	v_mfma_f32_16x16x32_bf16 v[70:73], v[178:181], v[218:221], v[70:73]
	v_mfma_f32_16x16x32_bf16 v[66:69], v[186:189], v[218:221], v[66:69]
	s_barrier
	s_add_i32 s58, s49, s40
	v_lshl_add_u64 v[152:153], s[36:37], 0, v[132:133]
	s_mov_b32 m0, s58
	ds_read_b128 v[190:193], v158 offset:16384
	ds_read_b128 v[194:197], v158 offset:17408
	ds_read_b128 v[198:201], v158 offset:18432
	ds_read_b128 v[202:205], v158 offset:19456
	ds_read_b128 v[206:209], v158 offset:20480
	ds_read_b128 v[210:213], v158 offset:21504
	ds_read_b128 v[214:217], v158 offset:22528
	ds_read_b128 v[218:221], v158 offset:23552
	global_load_lds_dwordx4 v[152:153], off
	s_add_i32 m0, s58, 0x2000
	s_add_u32 s58, s36, 0x40000
	v_lshl_add_u64 v[222:223], s[36:37], 0, v[136:137]
	s_addc_u32 s59, s37, 0
	s_add_i32 s60, s50, s40
	global_load_lds_dwordx4 v[222:223], off
	v_lshl_add_u64 v[224:225], s[58:59], 0, v[132:133]
	s_mov_b32 m0, s60
	v_lshl_add_u64 v[226:227], s[38:39], 0, v[134:135]
	global_load_lds_dwordx4 v[224:225], off
	v_lshl_add_u64 v[224:225], s[58:59], 0, v[136:137]
	s_add_i32 m0, s60, 0x2000
	s_nop 0
	global_load_lds_dwordx4 v[224:225], off
	v_lshl_add_u64 v[224:225], s[38:39], 0, v[130:131]
	s_mov_b32 m0, s41
	s_nop 0
	global_load_lds_dwordx4 v[224:225], off
	s_mov_b32 m0, s42
	s_nop 0
	global_load_lds_dwordx4 v[226:227], off
	s_waitcnt vmcnt(8)
	s_waitcnt lgkmcnt(0)
	s_barrier
	s_waitcnt lgkmcnt(0)
	v_mfma_f32_16x16x32_bf16 v[62:65], v[148:151], v[190:193], v[62:65]
	v_mfma_f32_16x16x32_bf16 v[58:61], v[166:169], v[190:193], v[58:61]
	v_mfma_f32_16x16x32_bf16 v[46:49], v[148:151], v[198:201], v[46:49]
	v_mfma_f32_16x16x32_bf16 v[42:45], v[166:169], v[198:201], v[42:45]
	v_mfma_f32_16x16x32_bf16 v[30:33], v[148:151], v[206:209], v[30:33]
	v_mfma_f32_16x16x32_bf16 v[26:29], v[166:169], v[206:209], v[26:29]
	v_mfma_f32_16x16x32_bf16 v[14:17], v[148:151], v[214:217], v[14:17]
	v_mfma_f32_16x16x32_bf16 v[10:13], v[166:169], v[214:217], v[10:13]
	v_mfma_f32_16x16x32_bf16 v[62:65], v[162:165], v[194:197], v[62:65]
	v_mfma_f32_16x16x32_bf16 v[58:61], v[170:173], v[194:197], v[58:61]
	v_mfma_f32_16x16x32_bf16 v[46:49], v[162:165], v[202:205], v[46:49]
	v_mfma_f32_16x16x32_bf16 v[42:45], v[170:173], v[202:205], v[42:45]
	v_mfma_f32_16x16x32_bf16 v[30:33], v[162:165], v[210:213], v[30:33]
	v_mfma_f32_16x16x32_bf16 v[26:29], v[170:173], v[210:213], v[26:29]
	v_mfma_f32_16x16x32_bf16 v[14:17], v[162:165], v[218:221], v[14:17]
	v_mfma_f32_16x16x32_bf16 v[10:13], v[170:173], v[218:221], v[10:13]
	v_mfma_f32_16x16x32_bf16 v[54:57], v[174:177], v[190:193], v[54:57]
	v_mfma_f32_16x16x32_bf16 v[50:53], v[182:185], v[190:193], v[50:53]
	v_mfma_f32_16x16x32_bf16 v[38:41], v[174:177], v[198:201], v[38:41]
	v_mfma_f32_16x16x32_bf16 v[34:37], v[182:185], v[198:201], v[34:37]
	v_mfma_f32_16x16x32_bf16 v[22:25], v[174:177], v[206:209], v[22:25]
	v_mfma_f32_16x16x32_bf16 v[18:21], v[182:185], v[206:209], v[18:21]
	v_mfma_f32_16x16x32_bf16 v[6:9], v[174:177], v[214:217], v[6:9]
	v_mfma_f32_16x16x32_bf16 v[2:5], v[182:185], v[214:217], v[2:5]
	v_mfma_f32_16x16x32_bf16 v[54:57], v[178:181], v[194:197], v[54:57]
	v_mfma_f32_16x16x32_bf16 v[50:53], v[186:189], v[194:197], v[50:53]
	v_mfma_f32_16x16x32_bf16 v[38:41], v[178:181], v[202:205], v[38:41]
	v_mfma_f32_16x16x32_bf16 v[34:37], v[186:189], v[202:205], v[34:37]
	v_mfma_f32_16x16x32_bf16 v[22:25], v[178:181], v[210:213], v[22:25]
	v_mfma_f32_16x16x32_bf16 v[18:21], v[186:189], v[210:213], v[18:21]
	v_mfma_f32_16x16x32_bf16 v[6:9], v[178:181], v[218:221], v[6:9]
	v_mfma_f32_16x16x32_bf16 v[2:5], v[186:189], v[218:221], v[2:5]
	s_barrier
	s_add_i32 s58, 0, 0x18000
	v_add_u32_e32 v161, s58, v154
	s_add_i32 s59, 0, 0x1c000
	ds_read_b128 v[148:151], v161
	ds_read_b128 v[162:165], v161 offset:1024
	ds_read_b128 v[166:169], v161 offset:2048
	ds_read_b128 v[170:173], v161 offset:3072
	v_add_u32_e32 v161, s59, v154
	ds_read_b128 v[174:177], v161
	ds_read_b128 v[178:181], v161 offset:1024
	ds_read_b128 v[182:185], v161 offset:2048
	ds_read_b128 v[186:189], v161 offset:3072
	s_add_u32 s38, s38, 0x40000
	s_addc_u32 s39, s39, 0
	s_mov_b32 m0, s43
	v_lshl_add_u64 v[228:229], s[38:39], 0, v[130:131]
	ds_read_b128 v[190:193], v158 offset:32768
	ds_read_b128 v[194:197], v158 offset:33792
	ds_read_b128 v[198:201], v158 offset:34816
	ds_read_b128 v[202:205], v158 offset:35840
	ds_read_b128 v[206:209], v158 offset:36864
	ds_read_b128 v[210:213], v158 offset:37888
	ds_read_b128 v[214:217], v158 offset:38912
	ds_read_b128 v[218:221], v158 offset:39936
	global_load_lds_dwordx4 v[228:229], off
	v_lshl_add_u64 v[228:229], s[38:39], 0, v[134:135]
	s_mov_b32 m0, s44
	s_nop 0
	global_load_lds_dwordx4 v[228:229], off
	s_waitcnt vmcnt(8)
	s_waitcnt lgkmcnt(0)
	s_barrier
	s_waitcnt lgkmcnt(0)
	v_mfma_f32_16x16x32_bf16 v[126:129], v[148:151], v[190:193], v[126:129]
	v_mfma_f32_16x16x32_bf16 v[122:125], v[166:169], v[190:193], v[122:125]
	v_mfma_f32_16x16x32_bf16 v[110:113], v[148:151], v[198:201], v[110:113]
	v_mfma_f32_16x16x32_bf16 v[106:109], v[166:169], v[198:201], v[106:109]
	v_mfma_f32_16x16x32_bf16 v[94:97], v[148:151], v[206:209], v[94:97]
	v_mfma_f32_16x16x32_bf16 v[90:93], v[166:169], v[206:209], v[90:93]
	v_mfma_f32_16x16x32_bf16 v[78:81], v[148:151], v[214:217], v[78:81]
	v_mfma_f32_16x16x32_bf16 v[74:77], v[166:169], v[214:217], v[74:77]
	v_mfma_f32_16x16x32_bf16 v[126:129], v[162:165], v[194:197], v[126:129]
	v_mfma_f32_16x16x32_bf16 v[122:125], v[170:173], v[194:197], v[122:125]
	v_mfma_f32_16x16x32_bf16 v[110:113], v[162:165], v[202:205], v[110:113]
	v_mfma_f32_16x16x32_bf16 v[106:109], v[170:173], v[202:205], v[106:109]
	v_mfma_f32_16x16x32_bf16 v[94:97], v[162:165], v[210:213], v[94:97]
	v_mfma_f32_16x16x32_bf16 v[90:93], v[170:173], v[210:213], v[90:93]
	v_mfma_f32_16x16x32_bf16 v[78:81], v[162:165], v[218:221], v[78:81]
	v_mfma_f32_16x16x32_bf16 v[74:77], v[170:173], v[218:221], v[74:77]
	v_mfma_f32_16x16x32_bf16 v[118:121], v[174:177], v[190:193], v[118:121]
	v_mfma_f32_16x16x32_bf16 v[114:117], v[182:185], v[190:193], v[114:117]
	v_mfma_f32_16x16x32_bf16 v[102:105], v[174:177], v[198:201], v[102:105]
	v_mfma_f32_16x16x32_bf16 v[98:101], v[182:185], v[198:201], v[98:101]
	v_mfma_f32_16x16x32_bf16 v[86:89], v[174:177], v[206:209], v[86:89]
	v_mfma_f32_16x16x32_bf16 v[82:85], v[182:185], v[206:209], v[82:85]
	v_mfma_f32_16x16x32_bf16 v[70:73], v[174:177], v[214:217], v[70:73]
	v_mfma_f32_16x16x32_bf16 v[66:69], v[182:185], v[214:217], v[66:69]
	v_mfma_f32_16x16x32_bf16 v[118:121], v[178:181], v[194:197], v[118:121]
	v_mfma_f32_16x16x32_bf16 v[114:117], v[186:189], v[194:197], v[114:117]
	v_mfma_f32_16x16x32_bf16 v[102:105], v[178:181], v[202:205], v[102:105]
	v_mfma_f32_16x16x32_bf16 v[98:101], v[186:189], v[202:205], v[98:101]
	v_mfma_f32_16x16x32_bf16 v[86:89], v[178:181], v[210:213], v[86:89]
	v_mfma_f32_16x16x32_bf16 v[82:85], v[186:189], v[210:213], v[82:85]
	v_mfma_f32_16x16x32_bf16 v[70:73], v[178:181], v[218:221], v[70:73]
	v_mfma_f32_16x16x32_bf16 v[66:69], v[186:189], v[218:221], v[66:69]
	s_barrier
	s_add_i32 s38, s58, s40
	v_lshl_add_u64 v[152:153], v[152:153], 0, s[10:11]
	s_mov_b32 m0, s38
	ds_read_b128 v[190:193], v158 offset:49152
	ds_read_b128 v[194:197], v158 offset:50176
	ds_read_b128 v[198:201], v158 offset:51200
	ds_read_b128 v[202:205], v158 offset:52224
	ds_read_b128 v[206:209], v158 offset:53248
	ds_read_b128 v[210:213], v158 offset:54272
	ds_read_b128 v[214:217], v158 offset:55296
	ds_read_b128 v[218:221], v158 offset:56320
	global_load_lds_dwordx4 v[152:153], off
	s_add_i32 m0, s38, 0x2000
	s_add_u32 s36, s36, 0x40080
	v_lshl_add_u64 v[152:153], v[222:223], 0, s[10:11]
	s_addc_u32 s37, s37, 0
	s_add_i32 s38, s59, s40
	global_load_lds_dwordx4 v[152:153], off
	v_lshl_add_u64 v[152:153], s[36:37], 0, v[132:133]
	s_mov_b32 m0, s38
	s_nop 0
	global_load_lds_dwordx4 v[152:153], off
	v_lshl_add_u64 v[152:153], s[36:37], 0, v[136:137]
	s_add_i32 m0, s38, 0x2000
	s_nop 0
	global_load_lds_dwordx4 v[152:153], off
	v_lshl_add_u64 v[152:153], v[224:225], 0, s[10:11]
	s_mov_b32 m0, s46
	s_nop 0
	global_load_lds_dwordx4 v[152:153], off
	v_lshl_add_u64 v[152:153], v[226:227], 0, s[10:11]
	s_mov_b32 m0, s47
	s_nop 0
	global_load_lds_dwordx4 v[152:153], off
	s_waitcnt vmcnt(8)
	s_waitcnt lgkmcnt(0)
	s_barrier
	s_waitcnt lgkmcnt(0)
	v_mfma_f32_16x16x32_bf16 v[62:65], v[148:151], v[190:193], v[62:65]
	v_mfma_f32_16x16x32_bf16 v[58:61], v[166:169], v[190:193], v[58:61]
	v_mfma_f32_16x16x32_bf16 v[46:49], v[148:151], v[198:201], v[46:49]
	v_mfma_f32_16x16x32_bf16 v[42:45], v[166:169], v[198:201], v[42:45]
	v_mfma_f32_16x16x32_bf16 v[30:33], v[148:151], v[206:209], v[30:33]
	v_mfma_f32_16x16x32_bf16 v[26:29], v[166:169], v[206:209], v[26:29]
	v_mfma_f32_16x16x32_bf16 v[14:17], v[148:151], v[214:217], v[14:17]
	v_mfma_f32_16x16x32_bf16 v[10:13], v[166:169], v[214:217], v[10:13]
	v_mfma_f32_16x16x32_bf16 v[62:65], v[162:165], v[194:197], v[62:65]
	v_mfma_f32_16x16x32_bf16 v[58:61], v[170:173], v[194:197], v[58:61]
	v_mfma_f32_16x16x32_bf16 v[46:49], v[162:165], v[202:205], v[46:49]
	v_mfma_f32_16x16x32_bf16 v[42:45], v[170:173], v[202:205], v[42:45]
	v_mfma_f32_16x16x32_bf16 v[30:33], v[162:165], v[210:213], v[30:33]
	v_mfma_f32_16x16x32_bf16 v[26:29], v[170:173], v[210:213], v[26:29]
	v_mfma_f32_16x16x32_bf16 v[14:17], v[162:165], v[218:221], v[14:17]
	v_mfma_f32_16x16x32_bf16 v[10:13], v[170:173], v[218:221], v[10:13]
	v_mfma_f32_16x16x32_bf16 v[54:57], v[174:177], v[190:193], v[54:57]
	v_mfma_f32_16x16x32_bf16 v[50:53], v[182:185], v[190:193], v[50:53]
	v_mfma_f32_16x16x32_bf16 v[38:41], v[174:177], v[198:201], v[38:41]
	v_mfma_f32_16x16x32_bf16 v[34:37], v[182:185], v[198:201], v[34:37]
	v_mfma_f32_16x16x32_bf16 v[22:25], v[174:177], v[206:209], v[22:25]
	v_mfma_f32_16x16x32_bf16 v[18:21], v[182:185], v[206:209], v[18:21]
	v_mfma_f32_16x16x32_bf16 v[6:9], v[174:177], v[214:217], v[6:9]
	v_mfma_f32_16x16x32_bf16 v[2:5], v[182:185], v[214:217], v[2:5]
	v_mfma_f32_16x16x32_bf16 v[54:57], v[178:181], v[194:197], v[54:57]
	v_mfma_f32_16x16x32_bf16 v[50:53], v[186:189], v[194:197], v[50:53]
	v_mfma_f32_16x16x32_bf16 v[38:41], v[178:181], v[202:205], v[38:41]
	v_mfma_f32_16x16x32_bf16 v[34:37], v[186:189], v[202:205], v[34:37]
	v_mfma_f32_16x16x32_bf16 v[22:25], v[178:181], v[210:213], v[22:25]
	v_mfma_f32_16x16x32_bf16 v[18:21], v[186:189], v[210:213], v[18:21]
	v_mfma_f32_16x16x32_bf16 v[6:9], v[178:181], v[218:221], v[6:9]
	v_mfma_f32_16x16x32_bf16 v[2:5], v[186:189], v[218:221], v[2:5]
	s_add_i32 s57, s57, 2
	s_add_u32 s22, s22, 0x100
	s_addc_u32 s23, s23, 0
	s_add_u32 s55, s55, 0x100
	s_addc_u32 s56, s56, 0
	s_cmp_gt_u32 s57, 13
	s_barrier
	s_cbranch_scc0 .LBB0_3293
	s_and_b64 vcc, exec, s[14:15]
	s_cbranch_vccz .LBB0_3296
	s_barrier

.LBB0_3379:
	ds_read_b128 v[130:133], v169
	ds_read_b128 v[134:137], v169 offset:1024
	ds_read_b128 v[158:161], v169 offset:2048
	ds_read_b128 v[174:177], v169 offset:3072
	ds_read_b128 v[178:181], v170
	ds_read_b128 v[182:185], v170 offset:1024
	ds_read_b128 v[186:189], v170 offset:2048
	ds_read_b128 v[190:193], v170 offset:3072
	s_add_u32 s40, s38, 0xfff50080
	s_addc_u32 s41, s39, -1
	s_cmp_eq_u32 s63, 40
	s_cselect_b32 s43, s7, s41
	s_cselect_b32 s42, s6, s40
	s_cselect_b32 s41, s37, s62
	s_cselect_b32 s40, s36, s61
	v_lshl_add_u64 v[138:139], s[38:39], 0, v[150:151]
	s_add_i32 m0, s33, 0xc000
	ds_read_b128 v[194:197], v171
	ds_read_b128 v[198:201], v171 offset:1024
	ds_read_b128 v[202:205], v171 offset:2048
	ds_read_b128 v[206:209], v171 offset:3072
	ds_read_b128 v[210:213], v171 offset:4096
	ds_read_b128 v[214:217], v171 offset:5120
	ds_read_b128 v[218:221], v171 offset:6144
	ds_read_b128 v[222:225], v171 offset:7168
	global_load_lds_dwordx4 v[138:139], off
	v_lshl_add_u64 v[138:139], s[38:39], 0, v[152:153]
	s_add_i32 m0, s33, 0xe000
	s_nop 0
	global_load_lds_dwordx4 v[138:139], off
	s_waitcnt vmcnt(8)
	s_waitcnt lgkmcnt(0)
	s_barrier
	s_waitcnt lgkmcnt(0)
	v_mfma_f32_16x16x32_bf16 v[126:129], v[130:133], v[194:197], v[126:129]
	v_mfma_f32_16x16x32_bf16 v[122:125], v[158:161], v[194:197], v[122:125]
	v_mfma_f32_16x16x32_bf16 v[110:113], v[130:133], v[202:205], v[110:113]
	v_mfma_f32_16x16x32_bf16 v[106:109], v[158:161], v[202:205], v[106:109]
	v_mfma_f32_16x16x32_bf16 v[94:97], v[130:133], v[210:213], v[94:97]
	v_mfma_f32_16x16x32_bf16 v[90:93], v[158:161], v[210:213], v[90:93]
	v_mfma_f32_16x16x32_bf16 v[78:81], v[130:133], v[218:221], v[78:81]
	v_mfma_f32_16x16x32_bf16 v[74:77], v[158:161], v[218:221], v[74:77]
	v_mfma_f32_16x16x32_bf16 v[126:129], v[134:137], v[198:201], v[126:129]
	v_mfma_f32_16x16x32_bf16 v[122:125], v[174:177], v[198:201], v[122:125]
	v_mfma_f32_16x16x32_bf16 v[110:113], v[134:137], v[206:209], v[110:113]
	v_mfma_f32_16x16x32_bf16 v[106:109], v[174:177], v[206:209], v[106:109]
	v_mfma_f32_16x16x32_bf16 v[94:97], v[134:137], v[214:217], v[94:97]
	v_mfma_f32_16x16x32_bf16 v[90:93], v[174:177], v[214:217], v[90:93]
	v_mfma_f32_16x16x32_bf16 v[78:81], v[134:137], v[222:225], v[78:81]
	v_mfma_f32_16x16x32_bf16 v[74:77], v[174:177], v[222:225], v[74:77]
	v_mfma_f32_16x16x32_bf16 v[118:121], v[178:181], v[194:197], v[118:121]
	v_mfma_f32_16x16x32_bf16 v[114:117], v[186:189], v[194:197], v[114:117]
	v_mfma_f32_16x16x32_bf16 v[102:105], v[178:181], v[202:205], v[102:105]
	v_mfma_f32_16x16x32_bf16 v[98:101], v[186:189], v[202:205], v[98:101]
	v_mfma_f32_16x16x32_bf16 v[86:89], v[178:181], v[210:213], v[86:89]
	v_mfma_f32_16x16x32_bf16 v[82:85], v[186:189], v[210:213], v[82:85]
	v_mfma_f32_16x16x32_bf16 v[70:73], v[178:181], v[218:221], v[70:73]
	v_mfma_f32_16x16x32_bf16 v[66:69], v[186:189], v[218:221], v[66:69]
	v_mfma_f32_16x16x32_bf16 v[118:121], v[182:185], v[198:201], v[118:121]
	v_mfma_f32_16x16x32_bf16 v[114:117], v[190:193], v[198:201], v[114:117]
	v_mfma_f32_16x16x32_bf16 v[102:105], v[182:185], v[206:209], v[102:105]
	v_mfma_f32_16x16x32_bf16 v[98:101], v[190:193], v[206:209], v[98:101]
	v_mfma_f32_16x16x32_bf16 v[86:89], v[182:185], v[214:217], v[86:89]
	v_mfma_f32_16x16x32_bf16 v[82:85], v[190:193], v[214:217], v[82:85]
	v_mfma_f32_16x16x32_bf16 v[70:73], v[182:185], v[222:225], v[70:73]
	v_mfma_f32_16x16x32_bf16 v[66:69], v[190:193], v[222:225], v[66:69]
	s_barrier
	s_add_i32 s66, s54, s3
	v_lshl_add_u64 v[138:139], s[40:41], 0, v[144:145]
	s_mov_b32 m0, s66
	ds_read_b128 v[194:197], v171 offset:16384
	ds_read_b128 v[198:201], v171 offset:17408
	ds_read_b128 v[202:205], v171 offset:18432
	ds_read_b128 v[206:209], v171 offset:19456
	ds_read_b128 v[210:213], v171 offset:20480
	ds_read_b128 v[214:217], v171 offset:21504
	ds_read_b128 v[218:221], v171 offset:22528
	ds_read_b128 v[222:225], v171 offset:23552
	global_load_lds_dwordx4 v[138:139], off
	s_add_i32 m0, s66, 0x2000
	s_add_u32 s66, s40, 0xb0000
	v_lshl_add_u64 v[162:163], s[40:41], 0, v[148:149]
	s_addc_u32 s67, s41, 0
	s_add_i32 s68, s55, s3
	global_load_lds_dwordx4 v[162:163], off
	v_lshl_add_u64 v[226:227], s[66:67], 0, v[144:145]
	s_mov_b32 m0, s68
	v_lshl_add_u64 v[228:229], s[42:43], 0, v[146:147]
	global_load_lds_dwordx4 v[226:227], off
	v_lshl_add_u64 v[226:227], s[66:67], 0, v[148:149]
	s_add_i32 m0, s68, 0x2000
	s_nop 0
	global_load_lds_dwordx4 v[226:227], off
	v_lshl_add_u64 v[226:227], s[42:43], 0, v[142:143]
	s_mov_b32 m0, s33
	s_nop 0
	global_load_lds_dwordx4 v[226:227], off
	s_mov_b32 m0, s35
	s_nop 0
	global_load_lds_dwordx4 v[228:229], off
	s_waitcnt vmcnt(8)
	s_waitcnt lgkmcnt(0)
	s_barrier
	s_waitcnt lgkmcnt(0)
	v_mfma_f32_16x16x32_bf16 v[62:65], v[130:133], v[194:197], v[62:65]
	v_mfma_f32_16x16x32_bf16 v[58:61], v[158:161], v[194:197], v[58:61]
	v_mfma_f32_16x16x32_bf16 v[46:49], v[130:133], v[202:205], v[46:49]
	v_mfma_f32_16x16x32_bf16 v[42:45], v[158:161], v[202:205], v[42:45]
	v_mfma_f32_16x16x32_bf16 v[30:33], v[130:133], v[210:213], v[30:33]
	v_mfma_f32_16x16x32_bf16 v[26:29], v[158:161], v[210:213], v[26:29]
	v_mfma_f32_16x16x32_bf16 v[14:17], v[130:133], v[218:221], v[14:17]
	v_mfma_f32_16x16x32_bf16 v[10:13], v[158:161], v[218:221], v[10:13]
	v_mfma_f32_16x16x32_bf16 v[62:65], v[134:137], v[198:201], v[62:65]
	v_mfma_f32_16x16x32_bf16 v[58:61], v[174:177], v[198:201], v[58:61]
	v_mfma_f32_16x16x32_bf16 v[46:49], v[134:137], v[206:209], v[46:49]
	v_mfma_f32_16x16x32_bf16 v[42:45], v[174:177], v[206:209], v[42:45]
	v_mfma_f32_16x16x32_bf16 v[30:33], v[134:137], v[214:217], v[30:33]
	v_mfma_f32_16x16x32_bf16 v[26:29], v[174:177], v[214:217], v[26:29]
	v_mfma_f32_16x16x32_bf16 v[14:17], v[134:137], v[222:225], v[14:17]
	v_mfma_f32_16x16x32_bf16 v[10:13], v[174:177], v[222:225], v[10:13]
	v_mfma_f32_16x16x32_bf16 v[54:57], v[178:181], v[194:197], v[54:57]
	v_mfma_f32_16x16x32_bf16 v[50:53], v[186:189], v[194:197], v[50:53]
	v_mfma_f32_16x16x32_bf16 v[38:41], v[178:181], v[202:205], v[38:41]
	v_mfma_f32_16x16x32_bf16 v[34:37], v[186:189], v[202:205], v[34:37]
	v_mfma_f32_16x16x32_bf16 v[22:25], v[178:181], v[210:213], v[22:25]
	v_mfma_f32_16x16x32_bf16 v[18:21], v[186:189], v[210:213], v[18:21]
	v_mfma_f32_16x16x32_bf16 v[6:9], v[178:181], v[218:221], v[6:9]
	v_mfma_f32_16x16x32_bf16 v[2:5], v[186:189], v[218:221], v[2:5]
	v_mfma_f32_16x16x32_bf16 v[54:57], v[182:185], v[198:201], v[54:57]
	v_mfma_f32_16x16x32_bf16 v[50:53], v[190:193], v[198:201], v[50:53]
	v_mfma_f32_16x16x32_bf16 v[38:41], v[182:185], v[206:209], v[38:41]
	v_mfma_f32_16x16x32_bf16 v[34:37], v[190:193], v[206:209], v[34:37]
	v_mfma_f32_16x16x32_bf16 v[22:25], v[182:185], v[214:217], v[22:25]
	v_mfma_f32_16x16x32_bf16 v[18:21], v[190:193], v[214:217], v[18:21]
	v_mfma_f32_16x16x32_bf16 v[6:9], v[182:185], v[222:225], v[6:9]
	v_mfma_f32_16x16x32_bf16 v[2:5], v[190:193], v[222:225], v[2:5]
	s_barrier
	s_add_i32 s66, 0, 0x18000
	v_add_u32_e32 v173, s66, v141
	s_add_i32 s67, 0, 0x1c000
	ds_read_b128 v[130:133], v173
	ds_read_b128 v[134:137], v173 offset:1024
	ds_read_b128 v[158:161], v173 offset:2048
	ds_read_b128 v[174:177], v173 offset:3072
	v_add_u32_e32 v173, s67, v141
	ds_read_b128 v[178:181], v173
	ds_read_b128 v[182:185], v173 offset:1024
	ds_read_b128 v[186:189], v173 offset:2048
	ds_read_b128 v[190:193], v173 offset:3072
	s_add_u32 s42, s42, 0xb0000
	s_addc_u32 s43, s43, 0
	s_mov_b32 m0, s44
	v_lshl_add_u64 v[230:231], s[42:43], 0, v[142:143]
	ds_read_b128 v[194:197], v171 offset:32768
	ds_read_b128 v[198:201], v171 offset:33792
	ds_read_b128 v[202:205], v171 offset:34816
	ds_read_b128 v[206:209], v171 offset:35840
	ds_read_b128 v[210:213], v171 offset:36864
	ds_read_b128 v[214:217], v171 offset:37888
	ds_read_b128 v[218:221], v171 offset:38912
	ds_read_b128 v[222:225], v171 offset:39936
	global_load_lds_dwordx4 v[230:231], off
	v_lshl_add_u64 v[230:231], s[42:43], 0, v[146:147]
	s_mov_b32 m0, s45
	s_nop 0
	global_load_lds_dwordx4 v[230:231], off
	s_waitcnt vmcnt(8)
	s_waitcnt lgkmcnt(0)
	s_barrier
	s_waitcnt lgkmcnt(0)
	v_mfma_f32_16x16x32_bf16 v[126:129], v[130:133], v[194:197], v[126:129]
	v_mfma_f32_16x16x32_bf16 v[122:125], v[158:161], v[194:197], v[122:125]
	v_mfma_f32_16x16x32_bf16 v[110:113], v[130:133], v[202:205], v[110:113]
	v_mfma_f32_16x16x32_bf16 v[106:109], v[158:161], v[202:205], v[106:109]
	v_mfma_f32_16x16x32_bf16 v[94:97], v[130:133], v[210:213], v[94:97]
	v_mfma_f32_16x16x32_bf16 v[90:93], v[158:161], v[210:213], v[90:93]
	v_mfma_f32_16x16x32_bf16 v[78:81], v[130:133], v[218:221], v[78:81]
	v_mfma_f32_16x16x32_bf16 v[74:77], v[158:161], v[218:221], v[74:77]
	v_mfma_f32_16x16x32_bf16 v[126:129], v[134:137], v[198:201], v[126:129]
	v_mfma_f32_16x16x32_bf16 v[122:125], v[174:177], v[198:201], v[122:125]
	v_mfma_f32_16x16x32_bf16 v[110:113], v[134:137], v[206:209], v[110:113]
	v_mfma_f32_16x16x32_bf16 v[106:109], v[174:177], v[206:209], v[106:109]
	v_mfma_f32_16x16x32_bf16 v[94:97], v[134:137], v[214:217], v[94:97]
	v_mfma_f32_16x16x32_bf16 v[90:93], v[174:177], v[214:217], v[90:93]
	v_mfma_f32_16x16x32_bf16 v[78:81], v[134:137], v[222:225], v[78:81]
	v_mfma_f32_16x16x32_bf16 v[74:77], v[174:177], v[222:225], v[74:77]
	v_mfma_f32_16x16x32_bf16 v[118:121], v[178:181], v[194:197], v[118:121]
	v_mfma_f32_16x16x32_bf16 v[114:117], v[186:189], v[194:197], v[114:117]
	v_mfma_f32_16x16x32_bf16 v[102:105], v[178:181], v[202:205], v[102:105]
	v_mfma_f32_16x16x32_bf16 v[98:101], v[186:189], v[202:205], v[98:101]
	v_mfma_f32_16x16x32_bf16 v[86:89], v[178:181], v[210:213], v[86:89]
	v_mfma_f32_16x16x32_bf16 v[82:85], v[186:189], v[210:213], v[82:85]
	v_mfma_f32_16x16x32_bf16 v[70:73], v[178:181], v[218:221], v[70:73]
	v_mfma_f32_16x16x32_bf16 v[66:69], v[186:189], v[218:221], v[66:69]
	v_mfma_f32_16x16x32_bf16 v[118:121], v[182:185], v[198:201], v[118:121]
	v_mfma_f32_16x16x32_bf16 v[114:117], v[190:193], v[198:201], v[114:117]
	v_mfma_f32_16x16x32_bf16 v[102:105], v[182:185], v[206:209], v[102:105]
	v_mfma_f32_16x16x32_bf16 v[98:101], v[190:193], v[206:209], v[98:101]
	v_mfma_f32_16x16x32_bf16 v[86:89], v[182:185], v[214:217], v[86:89]
	v_mfma_f32_16x16x32_bf16 v[82:85], v[190:193], v[214:217], v[82:85]
	v_mfma_f32_16x16x32_bf16 v[70:73], v[182:185], v[222:225], v[70:73]
	v_mfma_f32_16x16x32_bf16 v[66:69], v[190:193], v[222:225], v[66:69]
	s_barrier
	s_add_i32 s42, s66, s3
	v_lshl_add_u64 v[138:139], v[138:139], 0, s[20:21]
	s_mov_b32 m0, s42
	ds_read_b128 v[194:197], v171 offset:49152
	ds_read_b128 v[198:201], v171 offset:50176
	ds_read_b128 v[202:205], v171 offset:51200
	ds_read_b128 v[206:209], v171 offset:52224
	ds_read_b128 v[210:213], v171 offset:53248
	ds_read_b128 v[214:217], v171 offset:54272
	ds_read_b128 v[218:221], v171 offset:55296
	ds_read_b128 v[222:225], v171 offset:56320
	global_load_lds_dwordx4 v[138:139], off
	s_add_i32 m0, s42, 0x2000
	s_add_u32 s40, s40, 0xb0080
	v_lshl_add_u64 v[138:139], v[162:163], 0, s[20:21]
	s_addc_u32 s41, s41, 0
	s_add_i32 s42, s67, s3
	global_load_lds_dwordx4 v[138:139], off
	v_lshl_add_u64 v[138:139], s[40:41], 0, v[144:145]
	s_mov_b32 m0, s42
	s_nop 0
	global_load_lds_dwordx4 v[138:139], off
	v_lshl_add_u64 v[138:139], s[40:41], 0, v[148:149]
	s_add_i32 m0, s42, 0x2000
	s_nop 0
	global_load_lds_dwordx4 v[138:139], off
	v_lshl_add_u64 v[138:139], v[226:227], 0, s[20:21]
	s_mov_b32 m0, s48
	s_nop 0
	global_load_lds_dwordx4 v[138:139], off
	v_lshl_add_u64 v[138:139], v[228:229], 0, s[20:21]
	s_mov_b32 m0, s49
	s_nop 0
	global_load_lds_dwordx4 v[138:139], off
	s_waitcnt vmcnt(8)
	s_waitcnt lgkmcnt(0)
	s_barrier
	s_waitcnt lgkmcnt(0)
	v_mfma_f32_16x16x32_bf16 v[62:65], v[130:133], v[194:197], v[62:65]
	v_mfma_f32_16x16x32_bf16 v[58:61], v[158:161], v[194:197], v[58:61]
	v_mfma_f32_16x16x32_bf16 v[46:49], v[130:133], v[202:205], v[46:49]
	v_mfma_f32_16x16x32_bf16 v[42:45], v[158:161], v[202:205], v[42:45]
	v_mfma_f32_16x16x32_bf16 v[30:33], v[130:133], v[210:213], v[30:33]
	v_mfma_f32_16x16x32_bf16 v[26:29], v[158:161], v[210:213], v[26:29]
	v_mfma_f32_16x16x32_bf16 v[14:17], v[130:133], v[218:221], v[14:17]
	v_mfma_f32_16x16x32_bf16 v[10:13], v[158:161], v[218:221], v[10:13]
	v_mfma_f32_16x16x32_bf16 v[62:65], v[134:137], v[198:201], v[62:65]
	v_mfma_f32_16x16x32_bf16 v[58:61], v[174:177], v[198:201], v[58:61]
	v_mfma_f32_16x16x32_bf16 v[46:49], v[134:137], v[206:209], v[46:49]
	v_mfma_f32_16x16x32_bf16 v[42:45], v[174:177], v[206:209], v[42:45]
	v_mfma_f32_16x16x32_bf16 v[30:33], v[134:137], v[214:217], v[30:33]
	v_mfma_f32_16x16x32_bf16 v[26:29], v[174:177], v[214:217], v[26:29]
	v_mfma_f32_16x16x32_bf16 v[14:17], v[134:137], v[222:225], v[14:17]
	v_mfma_f32_16x16x32_bf16 v[10:13], v[174:177], v[222:225], v[10:13]
	v_mfma_f32_16x16x32_bf16 v[54:57], v[178:181], v[194:197], v[54:57]
	v_mfma_f32_16x16x32_bf16 v[50:53], v[186:189], v[194:197], v[50:53]
	v_mfma_f32_16x16x32_bf16 v[38:41], v[178:181], v[202:205], v[38:41]
	v_mfma_f32_16x16x32_bf16 v[34:37], v[186:189], v[202:205], v[34:37]
	v_mfma_f32_16x16x32_bf16 v[22:25], v[178:181], v[210:213], v[22:25]
	v_mfma_f32_16x16x32_bf16 v[18:21], v[186:189], v[210:213], v[18:21]
	v_mfma_f32_16x16x32_bf16 v[6:9], v[178:181], v[218:221], v[6:9]
	v_mfma_f32_16x16x32_bf16 v[2:5], v[186:189], v[218:221], v[2:5]
	v_mfma_f32_16x16x32_bf16 v[54:57], v[182:185], v[198:201], v[54:57]
	v_mfma_f32_16x16x32_bf16 v[50:53], v[190:193], v[198:201], v[50:53]
	v_mfma_f32_16x16x32_bf16 v[38:41], v[182:185], v[206:209], v[38:41]
	v_mfma_f32_16x16x32_bf16 v[34:37], v[190:193], v[206:209], v[34:37]
	v_mfma_f32_16x16x32_bf16 v[22:25], v[182:185], v[214:217], v[22:25]
	v_mfma_f32_16x16x32_bf16 v[18:21], v[190:193], v[214:217], v[18:21]
	v_mfma_f32_16x16x32_bf16 v[6:9], v[182:185], v[222:225], v[6:9]
	v_mfma_f32_16x16x32_bf16 v[2:5], v[190:193], v[222:225], v[2:5]
	s_add_i32 s63, s63, 2
	s_add_u32 s38, s38, 0x100
	s_addc_u32 s39, s39, 0
	s_add_u32 s61, s61, 0x100
	s_addc_u32 s62, s62, 0
	s_cmp_gt_u32 s63, 41
	s_barrier
	s_cbranch_scc0 .LBB0_3379
	s_and_b64 vcc, exec, s[22:23]
	s_cbranch_vccz .LBB0_3382
	s_barrier

.LBB0_3455:
	v_add_u32_e32 v168, s54, v154
	v_add_u32_e32 v184, s55, v154
	s_add_u32 s44, s40, s42
	ds_read_b128 v[156:159], v168
	ds_read_b128 v[160:163], v168 offset:1024
	ds_read_b128 v[164:167], v168 offset:2048
	ds_read_b128 v[168:171], v168 offset:3072
	ds_read_b128 v[172:175], v184
	ds_read_b128 v[176:179], v184 offset:1024
	ds_read_b128 v[180:183], v184 offset:2048
	ds_read_b128 v[184:187], v184 offset:3072
	s_addc_u32 s45, s41, s43
	s_add_u32 s44, s44, 0x100
	s_addc_u32 s45, s45, 0
	s_add_u32 s61, s37, s42
	s_addc_u32 s62, s59, s43
	s_cmpk_eq_i32 s42, 0x1500
	s_cselect_b32 s47, s7, s45
	s_cselect_b32 s46, s6, s44
	s_cselect_b32 s45, s39, s62
	s_cselect_b32 s44, s38, s61
	v_lshl_add_u64 v[220:221], v[148:149], 0, s[42:43]
	s_add_i32 m0, s35, 0xc000
	ds_read_b128 v[188:191], v155
	ds_read_b128 v[192:195], v155 offset:1024
	ds_read_b128 v[196:199], v155 offset:2048
	ds_read_b128 v[200:203], v155 offset:3072
	ds_read_b128 v[204:207], v155 offset:4096
	ds_read_b128 v[208:211], v155 offset:5120
	ds_read_b128 v[212:215], v155 offset:6144
	ds_read_b128 v[216:219], v155 offset:7168
	global_load_lds_dwordx4 v[220:221], off
	v_lshl_add_u64 v[220:221], v[150:151], 0, s[42:43]
	s_add_i32 m0, s35, 0xe000
	s_nop 0
	global_load_lds_dwordx4 v[220:221], off
	s_waitcnt vmcnt(8)
	s_waitcnt lgkmcnt(0)
	s_barrier
	s_waitcnt lgkmcnt(0)
	v_mfma_f32_16x16x32_bf16 v[126:129], v[156:159], v[188:191], v[126:129]
	v_mfma_f32_16x16x32_bf16 v[122:125], v[164:167], v[188:191], v[122:125]
	v_mfma_f32_16x16x32_bf16 v[110:113], v[156:159], v[196:199], v[110:113]
	v_mfma_f32_16x16x32_bf16 v[106:109], v[164:167], v[196:199], v[106:109]
	v_mfma_f32_16x16x32_bf16 v[94:97], v[156:159], v[204:207], v[94:97]
	v_mfma_f32_16x16x32_bf16 v[90:93], v[164:167], v[204:207], v[90:93]
	v_mfma_f32_16x16x32_bf16 v[78:81], v[156:159], v[212:215], v[78:81]
	v_mfma_f32_16x16x32_bf16 v[74:77], v[164:167], v[212:215], v[74:77]
	v_mfma_f32_16x16x32_bf16 v[126:129], v[160:163], v[192:195], v[126:129]
	v_mfma_f32_16x16x32_bf16 v[122:125], v[168:171], v[192:195], v[122:125]
	v_mfma_f32_16x16x32_bf16 v[110:113], v[160:163], v[200:203], v[110:113]
	v_mfma_f32_16x16x32_bf16 v[106:109], v[168:171], v[200:203], v[106:109]
	v_mfma_f32_16x16x32_bf16 v[94:97], v[160:163], v[208:211], v[94:97]
	v_mfma_f32_16x16x32_bf16 v[90:93], v[168:171], v[208:211], v[90:93]
	v_mfma_f32_16x16x32_bf16 v[78:81], v[160:163], v[216:219], v[78:81]
	v_mfma_f32_16x16x32_bf16 v[74:77], v[168:171], v[216:219], v[74:77]
	v_mfma_f32_16x16x32_bf16 v[118:121], v[172:175], v[188:191], v[118:121]
	v_mfma_f32_16x16x32_bf16 v[114:117], v[180:183], v[188:191], v[114:117]
	v_mfma_f32_16x16x32_bf16 v[102:105], v[172:175], v[196:199], v[102:105]
	v_mfma_f32_16x16x32_bf16 v[98:101], v[180:183], v[196:199], v[98:101]
	v_mfma_f32_16x16x32_bf16 v[86:89], v[172:175], v[204:207], v[86:89]
	v_mfma_f32_16x16x32_bf16 v[82:85], v[180:183], v[204:207], v[82:85]
	v_mfma_f32_16x16x32_bf16 v[70:73], v[172:175], v[212:215], v[70:73]
	v_mfma_f32_16x16x32_bf16 v[66:69], v[180:183], v[212:215], v[66:69]
	v_mfma_f32_16x16x32_bf16 v[118:121], v[176:179], v[192:195], v[118:121]
	v_mfma_f32_16x16x32_bf16 v[114:117], v[184:187], v[192:195], v[114:117]
	v_mfma_f32_16x16x32_bf16 v[102:105], v[176:179], v[200:203], v[102:105]
	v_mfma_f32_16x16x32_bf16 v[98:101], v[184:187], v[200:203], v[98:101]
	v_mfma_f32_16x16x32_bf16 v[86:89], v[176:179], v[208:211], v[86:89]
	v_mfma_f32_16x16x32_bf16 v[82:85], v[184:187], v[208:211], v[82:85]
	v_mfma_f32_16x16x32_bf16 v[70:73], v[176:179], v[216:219], v[70:73]
	v_mfma_f32_16x16x32_bf16 v[66:69], v[184:187], v[216:219], v[66:69]
	s_barrier
	s_add_i32 s61, s54, s33
	v_lshl_add_u64 v[220:221], s[44:45], 0, v[132:133]
	s_mov_b32 m0, s61
	ds_read_b128 v[188:191], v155 offset:16384
	ds_read_b128 v[192:195], v155 offset:17408
	ds_read_b128 v[196:199], v155 offset:18432
	ds_read_b128 v[200:203], v155 offset:19456
	ds_read_b128 v[204:207], v155 offset:20480
	ds_read_b128 v[208:211], v155 offset:21504
	ds_read_b128 v[212:215], v155 offset:22528
	ds_read_b128 v[216:219], v155 offset:23552
	global_load_lds_dwordx4 v[220:221], off
	s_add_i32 m0, s61, 0x2000
	s_add_u32 s62, s44, 0xb0000
	v_lshl_add_u64 v[222:223], s[44:45], 0, v[136:137]
	s_addc_u32 s63, s45, 0
	s_add_i32 s61, s55, s33
	global_load_lds_dwordx4 v[222:223], off
	v_lshl_add_u64 v[224:225], s[62:63], 0, v[132:133]
	s_mov_b32 m0, s61
	v_lshl_add_u64 v[226:227], s[46:47], 0, v[134:135]
	global_load_lds_dwordx4 v[224:225], off
	v_lshl_add_u64 v[224:225], s[62:63], 0, v[136:137]
	s_add_i32 m0, s61, 0x2000
	s_nop 0
	global_load_lds_dwordx4 v[224:225], off
	v_lshl_add_u64 v[224:225], s[46:47], 0, v[130:131]
	s_mov_b32 m0, s35
	s_nop 0
	global_load_lds_dwordx4 v[224:225], off
	s_mov_b32 m0, s48
	s_nop 0
	global_load_lds_dwordx4 v[226:227], off
	s_waitcnt vmcnt(8)
	s_waitcnt lgkmcnt(0)
	s_barrier
	s_waitcnt lgkmcnt(0)
	v_mfma_f32_16x16x32_bf16 v[62:65], v[156:159], v[188:191], v[62:65]
	v_mfma_f32_16x16x32_bf16 v[58:61], v[164:167], v[188:191], v[58:61]
	v_mfma_f32_16x16x32_bf16 v[46:49], v[156:159], v[196:199], v[46:49]
	v_mfma_f32_16x16x32_bf16 v[42:45], v[164:167], v[196:199], v[42:45]
	v_mfma_f32_16x16x32_bf16 v[30:33], v[156:159], v[204:207], v[30:33]
	v_mfma_f32_16x16x32_bf16 v[26:29], v[164:167], v[204:207], v[26:29]
	v_mfma_f32_16x16x32_bf16 v[14:17], v[156:159], v[212:215], v[14:17]
	v_mfma_f32_16x16x32_bf16 v[10:13], v[164:167], v[212:215], v[10:13]
	v_mfma_f32_16x16x32_bf16 v[62:65], v[160:163], v[192:195], v[62:65]
	v_mfma_f32_16x16x32_bf16 v[58:61], v[168:171], v[192:195], v[58:61]
	v_mfma_f32_16x16x32_bf16 v[46:49], v[160:163], v[200:203], v[46:49]
	v_mfma_f32_16x16x32_bf16 v[42:45], v[168:171], v[200:203], v[42:45]
	v_mfma_f32_16x16x32_bf16 v[30:33], v[160:163], v[208:211], v[30:33]
	v_mfma_f32_16x16x32_bf16 v[26:29], v[168:171], v[208:211], v[26:29]
	v_mfma_f32_16x16x32_bf16 v[14:17], v[160:163], v[216:219], v[14:17]
	v_mfma_f32_16x16x32_bf16 v[10:13], v[168:171], v[216:219], v[10:13]
	v_mfma_f32_16x16x32_bf16 v[54:57], v[172:175], v[188:191], v[54:57]
	v_mfma_f32_16x16x32_bf16 v[50:53], v[180:183], v[188:191], v[50:53]
	v_mfma_f32_16x16x32_bf16 v[38:41], v[172:175], v[196:199], v[38:41]
	v_mfma_f32_16x16x32_bf16 v[34:37], v[180:183], v[196:199], v[34:37]
	v_mfma_f32_16x16x32_bf16 v[22:25], v[172:175], v[204:207], v[22:25]
	v_mfma_f32_16x16x32_bf16 v[18:21], v[180:183], v[204:207], v[18:21]
	v_mfma_f32_16x16x32_bf16 v[6:9], v[172:175], v[212:215], v[6:9]
	v_mfma_f32_16x16x32_bf16 v[2:5], v[180:183], v[212:215], v[2:5]
	v_mfma_f32_16x16x32_bf16 v[54:57], v[176:179], v[192:195], v[54:57]
	v_mfma_f32_16x16x32_bf16 v[50:53], v[184:187], v[192:195], v[50:53]
	v_mfma_f32_16x16x32_bf16 v[38:41], v[176:179], v[200:203], v[38:41]
	v_mfma_f32_16x16x32_bf16 v[34:37], v[184:187], v[200:203], v[34:37]
	v_mfma_f32_16x16x32_bf16 v[22:25], v[176:179], v[208:211], v[22:25]
	v_mfma_f32_16x16x32_bf16 v[18:21], v[184:187], v[208:211], v[18:21]
	v_mfma_f32_16x16x32_bf16 v[6:9], v[176:179], v[216:219], v[6:9]
	v_mfma_f32_16x16x32_bf16 v[2:5], v[184:187], v[216:219], v[2:5]
	s_barrier
	s_add_i32 s61, 0, 0x18000
	s_add_i32 s62, 0, 0x1c000
	v_add_u32_e32 v168, s61, v154
	v_add_u32_e32 v184, s62, v154
	ds_read_b128 v[156:159], v168
	ds_read_b128 v[160:163], v168 offset:1024
	ds_read_b128 v[164:167], v168 offset:2048
	ds_read_b128 v[168:171], v168 offset:3072
	ds_read_b128 v[172:175], v184
	ds_read_b128 v[176:179], v184 offset:1024
	ds_read_b128 v[180:183], v184 offset:2048
	ds_read_b128 v[184:187], v184 offset:3072
	s_add_u32 s46, s46, 0xb0000
	s_addc_u32 s47, s47, 0
	s_mov_b32 m0, s49
	v_lshl_add_u64 v[228:229], s[46:47], 0, v[130:131]
	ds_read_b128 v[188:191], v155 offset:32768
	ds_read_b128 v[192:195], v155 offset:33792
	ds_read_b128 v[196:199], v155 offset:34816
	ds_read_b128 v[200:203], v155 offset:35840
	ds_read_b128 v[204:207], v155 offset:36864
	ds_read_b128 v[208:211], v155 offset:37888
	ds_read_b128 v[212:215], v155 offset:38912
	ds_read_b128 v[216:219], v155 offset:39936
	global_load_lds_dwordx4 v[228:229], off
	v_lshl_add_u64 v[228:229], s[46:47], 0, v[134:135]
	s_mov_b32 m0, s50
	s_nop 0
	global_load_lds_dwordx4 v[228:229], off
	s_waitcnt vmcnt(8)
	s_waitcnt lgkmcnt(0)
	s_barrier
	s_waitcnt lgkmcnt(0)
	v_mfma_f32_16x16x32_bf16 v[126:129], v[156:159], v[188:191], v[126:129]
	v_mfma_f32_16x16x32_bf16 v[122:125], v[164:167], v[188:191], v[122:125]
	v_mfma_f32_16x16x32_bf16 v[110:113], v[156:159], v[196:199], v[110:113]
	v_mfma_f32_16x16x32_bf16 v[106:109], v[164:167], v[196:199], v[106:109]
	v_mfma_f32_16x16x32_bf16 v[94:97], v[156:159], v[204:207], v[94:97]
	v_mfma_f32_16x16x32_bf16 v[90:93], v[164:167], v[204:207], v[90:93]
	v_mfma_f32_16x16x32_bf16 v[78:81], v[156:159], v[212:215], v[78:81]
	v_mfma_f32_16x16x32_bf16 v[74:77], v[164:167], v[212:215], v[74:77]
	v_mfma_f32_16x16x32_bf16 v[126:129], v[160:163], v[192:195], v[126:129]
	v_mfma_f32_16x16x32_bf16 v[122:125], v[168:171], v[192:195], v[122:125]
	v_mfma_f32_16x16x32_bf16 v[110:113], v[160:163], v[200:203], v[110:113]
	v_mfma_f32_16x16x32_bf16 v[106:109], v[168:171], v[200:203], v[106:109]
	v_mfma_f32_16x16x32_bf16 v[94:97], v[160:163], v[208:211], v[94:97]
	v_mfma_f32_16x16x32_bf16 v[90:93], v[168:171], v[208:211], v[90:93]
	v_mfma_f32_16x16x32_bf16 v[78:81], v[160:163], v[216:219], v[78:81]
	v_mfma_f32_16x16x32_bf16 v[74:77], v[168:171], v[216:219], v[74:77]
	v_mfma_f32_16x16x32_bf16 v[118:121], v[172:175], v[188:191], v[118:121]
	v_mfma_f32_16x16x32_bf16 v[114:117], v[180:183], v[188:191], v[114:117]
	v_mfma_f32_16x16x32_bf16 v[102:105], v[172:175], v[196:199], v[102:105]
	v_mfma_f32_16x16x32_bf16 v[98:101], v[180:183], v[196:199], v[98:101]
	v_mfma_f32_16x16x32_bf16 v[86:89], v[172:175], v[204:207], v[86:89]
	v_mfma_f32_16x16x32_bf16 v[82:85], v[180:183], v[204:207], v[82:85]
	v_mfma_f32_16x16x32_bf16 v[70:73], v[172:175], v[212:215], v[70:73]
	v_mfma_f32_16x16x32_bf16 v[66:69], v[180:183], v[212:215], v[66:69]
	v_mfma_f32_16x16x32_bf16 v[118:121], v[176:179], v[192:195], v[118:121]
	v_mfma_f32_16x16x32_bf16 v[114:117], v[184:187], v[192:195], v[114:117]
	v_mfma_f32_16x16x32_bf16 v[102:105], v[176:179], v[200:203], v[102:105]
	v_mfma_f32_16x16x32_bf16 v[98:101], v[184:187], v[200:203], v[98:101]
	v_mfma_f32_16x16x32_bf16 v[86:89], v[176:179], v[208:211], v[86:89]
	v_mfma_f32_16x16x32_bf16 v[82:85], v[184:187], v[208:211], v[82:85]
	v_mfma_f32_16x16x32_bf16 v[70:73], v[176:179], v[216:219], v[70:73]
	v_mfma_f32_16x16x32_bf16 v[66:69], v[184:187], v[216:219], v[66:69]
	s_barrier
	s_add_i32 s46, s61, s33
	v_lshl_add_u64 v[220:221], v[220:221], 0, s[20:21]
	s_mov_b32 m0, s46
	ds_read_b128 v[188:191], v155 offset:49152
	ds_read_b128 v[192:195], v155 offset:50176
	ds_read_b128 v[196:199], v155 offset:51200
	ds_read_b128 v[200:203], v155 offset:52224
	ds_read_b128 v[204:207], v155 offset:53248
	ds_read_b128 v[208:211], v155 offset:54272
	ds_read_b128 v[212:215], v155 offset:55296
	ds_read_b128 v[216:219], v155 offset:56320
	global_load_lds_dwordx4 v[220:221], off
	s_add_i32 m0, s46, 0x2000
	s_add_u32 s44, s44, 0xb0080
	v_lshl_add_u64 v[220:221], v[222:223], 0, s[20:21]
	s_addc_u32 s45, s45, 0
	s_add_i32 s46, s62, s33
	global_load_lds_dwordx4 v[220:221], off
	v_lshl_add_u64 v[220:221], s[44:45], 0, v[132:133]
	s_mov_b32 m0, s46
	s_nop 0
	global_load_lds_dwordx4 v[220:221], off
	v_lshl_add_u64 v[220:221], s[44:45], 0, v[136:137]
	s_add_i32 m0, s46, 0x2000
	s_nop 0
	global_load_lds_dwordx4 v[220:221], off
	v_lshl_add_u64 v[220:221], v[224:225], 0, s[20:21]
	s_mov_b32 m0, s51
	s_nop 0
	global_load_lds_dwordx4 v[220:221], off
	v_lshl_add_u64 v[220:221], v[226:227], 0, s[20:21]
	s_mov_b32 m0, s52
	s_nop 0
	global_load_lds_dwordx4 v[220:221], off
	s_waitcnt vmcnt(8)
	s_waitcnt lgkmcnt(0)
	s_barrier
	s_waitcnt lgkmcnt(0)
	v_mfma_f32_16x16x32_bf16 v[62:65], v[156:159], v[188:191], v[62:65]
	v_mfma_f32_16x16x32_bf16 v[58:61], v[164:167], v[188:191], v[58:61]
	v_mfma_f32_16x16x32_bf16 v[46:49], v[156:159], v[196:199], v[46:49]
	v_mfma_f32_16x16x32_bf16 v[42:45], v[164:167], v[196:199], v[42:45]
	v_mfma_f32_16x16x32_bf16 v[30:33], v[156:159], v[204:207], v[30:33]
	v_mfma_f32_16x16x32_bf16 v[26:29], v[164:167], v[204:207], v[26:29]
	v_mfma_f32_16x16x32_bf16 v[14:17], v[156:159], v[212:215], v[14:17]
	v_mfma_f32_16x16x32_bf16 v[10:13], v[164:167], v[212:215], v[10:13]
	v_mfma_f32_16x16x32_bf16 v[62:65], v[160:163], v[192:195], v[62:65]
	v_mfma_f32_16x16x32_bf16 v[58:61], v[168:171], v[192:195], v[58:61]
	v_mfma_f32_16x16x32_bf16 v[46:49], v[160:163], v[200:203], v[46:49]
	v_mfma_f32_16x16x32_bf16 v[42:45], v[168:171], v[200:203], v[42:45]
	v_mfma_f32_16x16x32_bf16 v[30:33], v[160:163], v[208:211], v[30:33]
	v_mfma_f32_16x16x32_bf16 v[26:29], v[168:171], v[208:211], v[26:29]
	v_mfma_f32_16x16x32_bf16 v[14:17], v[160:163], v[216:219], v[14:17]
	v_mfma_f32_16x16x32_bf16 v[10:13], v[168:171], v[216:219], v[10:13]
	v_mfma_f32_16x16x32_bf16 v[54:57], v[172:175], v[188:191], v[54:57]
	v_mfma_f32_16x16x32_bf16 v[50:53], v[180:183], v[188:191], v[50:53]
	v_mfma_f32_16x16x32_bf16 v[38:41], v[172:175], v[196:199], v[38:41]
	v_mfma_f32_16x16x32_bf16 v[34:37], v[180:183], v[196:199], v[34:37]
	v_mfma_f32_16x16x32_bf16 v[22:25], v[172:175], v[204:207], v[22:25]
	v_mfma_f32_16x16x32_bf16 v[18:21], v[180:183], v[204:207], v[18:21]
	v_mfma_f32_16x16x32_bf16 v[6:9], v[172:175], v[212:215], v[6:9]
	v_mfma_f32_16x16x32_bf16 v[2:5], v[180:183], v[212:215], v[2:5]
	v_mfma_f32_16x16x32_bf16 v[54:57], v[176:179], v[192:195], v[54:57]
	v_mfma_f32_16x16x32_bf16 v[50:53], v[184:187], v[192:195], v[50:53]
	v_mfma_f32_16x16x32_bf16 v[38:41], v[176:179], v[200:203], v[38:41]
	v_mfma_f32_16x16x32_bf16 v[34:37], v[184:187], v[200:203], v[34:37]
	v_mfma_f32_16x16x32_bf16 v[22:25], v[176:179], v[208:211], v[22:25]
	v_mfma_f32_16x16x32_bf16 v[18:21], v[184:187], v[208:211], v[18:21]
	v_mfma_f32_16x16x32_bf16 v[6:9], v[176:179], v[216:219], v[6:9]
	v_mfma_f32_16x16x32_bf16 v[2:5], v[184:187], v[216:219], v[2:5]
	s_add_i32 s60, s60, 2
	s_add_u32 s42, s42, 0x100
	s_addc_u32 s43, s43, 0
	s_cmp_gt_u32 s60, 41
	s_barrier
	s_cbranch_scc0 .LBB0_3455
	s_and_b64 vcc, exec, s[22:23]
	s_cbranch_vccz .LBB0_3458
	s_barrier
